# MFMA issue order inside compute segments changed to snake path (accumulator + SrcB reuse between consecutive MFMAs), all 12 GEMM loops; on top of balanced staging
# speedup vs baseline: 1.0265x; 1.0120x over previous
.LBB0_272:
	s_add_u32 s58, s22, 0xfff00000
	s_addc_u32 s59, s23, -1
	s_mov_b32 m0, s36
	ds_read_b128 v[154:157], v148
	global_load_lds_dwordx4 v130, s[58:59]
	s_mov_b32 m0, s37
	ds_read_b128 v[158:161], v148 offset:1024
	global_load_lds_dwordx4 v134, s[58:59]
	s_mov_b32 m0, s40
	ds_read_b128 v[164:167], v148 offset:2048
	global_load_lds_dwordx4 v142, s[22:23]
	s_mov_b32 m0, s41
	ds_read_b128 v[168:171], v148 offset:3072
	global_load_lds_dwordx4 v144, s[22:23]
	ds_read_b128 v[172:175], v149
	ds_read_b128 v[176:179], v149 offset:1024
	ds_read_b128 v[180:183], v149 offset:2048
	ds_read_b128 v[184:187], v149 offset:3072
	s_add_u32 s24, s22, 0xfff00080
	s_addc_u32 s25, s23, -1
	s_cmp_eq_u32 s56, 60
	s_cselect_b32 s27, s51, s25
	s_cselect_b32 s26, s52, s24
	s_cselect_b32 s25, s7, s55
	s_cselect_b32 s24, s53, s54
	ds_read_b128 v[188:191], v150
	ds_read_b128 v[192:195], v150 offset:1024
	ds_read_b128 v[196:199], v150 offset:2048
	ds_read_b128 v[200:203], v150 offset:3072
	ds_read_b128 v[204:207], v150 offset:4096
	ds_read_b128 v[208:211], v150 offset:5120
	ds_read_b128 v[212:215], v150 offset:6144
	ds_read_b128 v[216:219], v150 offset:7168
	s_waitcnt vmcnt(8)
	s_waitcnt lgkmcnt(0)
	s_barrier
	s_setprio 1
	s_waitcnt lgkmcnt(0)
	v_mfma_f32_16x16x32_bf16 v[126:129], v[154:157], v[188:191], v[126:129]
	v_mfma_f32_16x16x32_bf16 v[126:129], v[158:161], v[192:195], v[126:129]
	v_mfma_f32_16x16x32_bf16 v[122:125], v[168:171], v[192:195], v[122:125]
	v_mfma_f32_16x16x32_bf16 v[122:125], v[164:167], v[188:191], v[122:125]
	v_mfma_f32_16x16x32_bf16 v[110:113], v[172:175], v[188:191], v[110:113]
	v_mfma_f32_16x16x32_bf16 v[110:113], v[176:179], v[192:195], v[110:113]
	v_mfma_f32_16x16x32_bf16 v[106:109], v[184:187], v[192:195], v[106:109]
	v_mfma_f32_16x16x32_bf16 v[106:109], v[180:183], v[188:191], v[106:109]
	v_mfma_f32_16x16x32_bf16 v[90:93], v[180:183], v[196:199], v[90:93]
	v_mfma_f32_16x16x32_bf16 v[90:93], v[184:187], v[200:203], v[90:93]
	v_mfma_f32_16x16x32_bf16 v[94:97], v[176:179], v[200:203], v[94:97]
	v_mfma_f32_16x16x32_bf16 v[94:97], v[172:175], v[196:199], v[94:97]
	v_mfma_f32_16x16x32_bf16 v[114:117], v[164:167], v[196:199], v[114:117]
	v_mfma_f32_16x16x32_bf16 v[114:117], v[168:171], v[200:203], v[114:117]
	v_mfma_f32_16x16x32_bf16 v[118:121], v[158:161], v[200:203], v[118:121]
	v_mfma_f32_16x16x32_bf16 v[118:121], v[154:157], v[196:199], v[118:121]
	v_mfma_f32_16x16x32_bf16 v[102:105], v[154:157], v[204:207], v[102:105]
	v_mfma_f32_16x16x32_bf16 v[102:105], v[158:161], v[208:211], v[102:105]
	v_mfma_f32_16x16x32_bf16 v[98:101], v[168:171], v[208:211], v[98:101]
	v_mfma_f32_16x16x32_bf16 v[98:101], v[164:167], v[204:207], v[98:101]
	v_mfma_f32_16x16x32_bf16 v[78:81], v[172:175], v[204:207], v[78:81]
	v_mfma_f32_16x16x32_bf16 v[78:81], v[176:179], v[208:211], v[78:81]
	v_mfma_f32_16x16x32_bf16 v[74:77], v[184:187], v[208:211], v[74:77]
	v_mfma_f32_16x16x32_bf16 v[74:77], v[180:183], v[204:207], v[74:77]
	v_mfma_f32_16x16x32_bf16 v[66:69], v[180:183], v[212:215], v[66:69]
	v_mfma_f32_16x16x32_bf16 v[66:69], v[184:187], v[216:219], v[66:69]
	v_mfma_f32_16x16x32_bf16 v[70:73], v[176:179], v[216:219], v[70:73]
	v_mfma_f32_16x16x32_bf16 v[70:73], v[172:175], v[212:215], v[70:73]
	v_mfma_f32_16x16x32_bf16 v[82:85], v[164:167], v[212:215], v[82:85]
	v_mfma_f32_16x16x32_bf16 v[82:85], v[168:171], v[216:219], v[82:85]
	v_mfma_f32_16x16x32_bf16 v[86:89], v[158:161], v[216:219], v[86:89]
	v_mfma_f32_16x16x32_bf16 v[86:89], v[154:157], v[212:215], v[86:89]
	s_setprio 0
	s_barrier
	s_mov_b32 m0, s42
	s_add_u32 s58, s24, 0x100000
	global_load_lds_dwordx4 v132, s[24:25]
	s_mov_b32 m0, s43
	s_addc_u32 s59, s25, 0
	global_load_lds_dwordx4 v136, s[24:25]
	s_mov_b32 m0, s44
	ds_read_b128 v[188:191], v150 offset:16384
	global_load_lds_dwordx4 v132, s[58:59]
	s_mov_b32 m0, s45
	ds_read_b128 v[192:195], v150 offset:17408
	global_load_lds_dwordx4 v136, s[58:59]
	ds_read_b128 v[196:199], v150 offset:18432
	ds_read_b128 v[200:203], v150 offset:19456
	ds_read_b128 v[204:207], v150 offset:20480
	ds_read_b128 v[208:211], v150 offset:21504
	ds_read_b128 v[212:215], v150 offset:22528
	ds_read_b128 v[216:219], v150 offset:23552
	s_waitcnt vmcnt(6)
	s_waitcnt lgkmcnt(0)
	s_barrier
	s_setprio 1
	s_waitcnt lgkmcnt(0)
	v_mfma_f32_16x16x32_bf16 v[62:65], v[154:157], v[188:191], v[62:65]
	v_mfma_f32_16x16x32_bf16 v[62:65], v[158:161], v[192:195], v[62:65]
	v_mfma_f32_16x16x32_bf16 v[58:61], v[168:171], v[192:195], v[58:61]
	v_mfma_f32_16x16x32_bf16 v[58:61], v[164:167], v[188:191], v[58:61]
	v_mfma_f32_16x16x32_bf16 v[46:49], v[172:175], v[188:191], v[46:49]
	v_mfma_f32_16x16x32_bf16 v[46:49], v[176:179], v[192:195], v[46:49]
	v_mfma_f32_16x16x32_bf16 v[42:45], v[184:187], v[192:195], v[42:45]
	v_mfma_f32_16x16x32_bf16 v[42:45], v[180:183], v[188:191], v[42:45]
	v_mfma_f32_16x16x32_bf16 v[26:29], v[180:183], v[196:199], v[26:29]
	v_mfma_f32_16x16x32_bf16 v[26:29], v[184:187], v[200:203], v[26:29]
	v_mfma_f32_16x16x32_bf16 v[30:33], v[176:179], v[200:203], v[30:33]
	v_mfma_f32_16x16x32_bf16 v[30:33], v[172:175], v[196:199], v[30:33]
	v_mfma_f32_16x16x32_bf16 v[50:53], v[164:167], v[196:199], v[50:53]
	v_mfma_f32_16x16x32_bf16 v[50:53], v[168:171], v[200:203], v[50:53]
	v_mfma_f32_16x16x32_bf16 v[54:57], v[158:161], v[200:203], v[54:57]
	v_mfma_f32_16x16x32_bf16 v[54:57], v[154:157], v[196:199], v[54:57]
	v_mfma_f32_16x16x32_bf16 v[38:41], v[154:157], v[204:207], v[38:41]
	v_mfma_f32_16x16x32_bf16 v[38:41], v[158:161], v[208:211], v[38:41]
	v_mfma_f32_16x16x32_bf16 v[34:37], v[168:171], v[208:211], v[34:37]
	v_mfma_f32_16x16x32_bf16 v[34:37], v[164:167], v[204:207], v[34:37]
	v_mfma_f32_16x16x32_bf16 v[14:17], v[172:175], v[204:207], v[14:17]
	v_mfma_f32_16x16x32_bf16 v[14:17], v[176:179], v[208:211], v[14:17]
	v_mfma_f32_16x16x32_bf16 v[10:13], v[184:187], v[208:211], v[10:13]
	v_mfma_f32_16x16x32_bf16 v[10:13], v[180:183], v[204:207], v[10:13]
	v_mfma_f32_16x16x32_bf16 v[2:5], v[180:183], v[212:215], v[2:5]
	v_mfma_f32_16x16x32_bf16 v[2:5], v[184:187], v[216:219], v[2:5]
	v_mfma_f32_16x16x32_bf16 v[6:9], v[176:179], v[216:219], v[6:9]
	v_mfma_f32_16x16x32_bf16 v[6:9], v[172:175], v[212:215], v[6:9]
	v_mfma_f32_16x16x32_bf16 v[18:21], v[164:167], v[212:215], v[18:21]
	v_mfma_f32_16x16x32_bf16 v[18:21], v[168:171], v[216:219], v[18:21]
	v_mfma_f32_16x16x32_bf16 v[22:25], v[158:161], v[216:219], v[22:25]
	v_mfma_f32_16x16x32_bf16 v[22:25], v[154:157], v[212:215], v[22:25]
	s_setprio 0
	s_barrier
	s_mov_b32 m0, s30
	ds_read_b128 v[154:157], v151
	global_load_lds_dwordx4 v130, s[26:27]
	s_mov_b32 m0, s31
	ds_read_b128 v[158:161], v151 offset:1024
	global_load_lds_dwordx4 v134, s[26:27]
	s_add_u32 s26, s26, 0x100000
	s_addc_u32 s27, s27, 0
	s_mov_b32 m0, s33
	ds_read_b128 v[164:167], v151 offset:2048
	global_load_lds_dwordx4 v130, s[26:27]
	s_mov_b32 m0, s34
	ds_read_b128 v[168:171], v151 offset:3072
	global_load_lds_dwordx4 v134, s[26:27]
	ds_read_b128 v[172:175], v152
	ds_read_b128 v[176:179], v152 offset:1024
	ds_read_b128 v[180:183], v152 offset:2048
	ds_read_b128 v[184:187], v152 offset:3072
	ds_read_b128 v[188:191], v150 offset:32768
	ds_read_b128 v[192:195], v150 offset:33792
	ds_read_b128 v[196:199], v150 offset:34816
	ds_read_b128 v[200:203], v150 offset:35840
	ds_read_b128 v[204:207], v150 offset:36864
	ds_read_b128 v[208:211], v150 offset:37888
	ds_read_b128 v[212:215], v150 offset:38912
	ds_read_b128 v[216:219], v150 offset:39936
	s_waitcnt vmcnt(8)
	s_waitcnt lgkmcnt(0)
	s_barrier
	s_setprio 1
	s_waitcnt lgkmcnt(0)
	v_mfma_f32_16x16x32_bf16 v[126:129], v[154:157], v[188:191], v[126:129]
	v_mfma_f32_16x16x32_bf16 v[126:129], v[158:161], v[192:195], v[126:129]
	v_mfma_f32_16x16x32_bf16 v[122:125], v[168:171], v[192:195], v[122:125]
	v_mfma_f32_16x16x32_bf16 v[122:125], v[164:167], v[188:191], v[122:125]
	v_mfma_f32_16x16x32_bf16 v[110:113], v[172:175], v[188:191], v[110:113]
	v_mfma_f32_16x16x32_bf16 v[110:113], v[176:179], v[192:195], v[110:113]
	v_mfma_f32_16x16x32_bf16 v[106:109], v[184:187], v[192:195], v[106:109]
	v_mfma_f32_16x16x32_bf16 v[106:109], v[180:183], v[188:191], v[106:109]
	v_mfma_f32_16x16x32_bf16 v[90:93], v[180:183], v[196:199], v[90:93]
	v_mfma_f32_16x16x32_bf16 v[90:93], v[184:187], v[200:203], v[90:93]
	v_mfma_f32_16x16x32_bf16 v[94:97], v[176:179], v[200:203], v[94:97]
	v_mfma_f32_16x16x32_bf16 v[94:97], v[172:175], v[196:199], v[94:97]
	v_mfma_f32_16x16x32_bf16 v[114:117], v[164:167], v[196:199], v[114:117]
	v_mfma_f32_16x16x32_bf16 v[114:117], v[168:171], v[200:203], v[114:117]
	v_mfma_f32_16x16x32_bf16 v[118:121], v[158:161], v[200:203], v[118:121]
	v_mfma_f32_16x16x32_bf16 v[118:121], v[154:157], v[196:199], v[118:121]
	v_mfma_f32_16x16x32_bf16 v[102:105], v[154:157], v[204:207], v[102:105]
	v_mfma_f32_16x16x32_bf16 v[102:105], v[158:161], v[208:211], v[102:105]
	v_mfma_f32_16x16x32_bf16 v[98:101], v[168:171], v[208:211], v[98:101]
	v_mfma_f32_16x16x32_bf16 v[98:101], v[164:167], v[204:207], v[98:101]
	v_mfma_f32_16x16x32_bf16 v[78:81], v[172:175], v[204:207], v[78:81]
	v_mfma_f32_16x16x32_bf16 v[78:81], v[176:179], v[208:211], v[78:81]
	v_mfma_f32_16x16x32_bf16 v[74:77], v[184:187], v[208:211], v[74:77]
	v_mfma_f32_16x16x32_bf16 v[74:77], v[180:183], v[204:207], v[74:77]
	v_mfma_f32_16x16x32_bf16 v[66:69], v[180:183], v[212:215], v[66:69]
	v_mfma_f32_16x16x32_bf16 v[66:69], v[184:187], v[216:219], v[66:69]
	v_mfma_f32_16x16x32_bf16 v[70:73], v[176:179], v[216:219], v[70:73]
	v_mfma_f32_16x16x32_bf16 v[70:73], v[172:175], v[212:215], v[70:73]
	v_mfma_f32_16x16x32_bf16 v[82:85], v[164:167], v[212:215], v[82:85]
	v_mfma_f32_16x16x32_bf16 v[82:85], v[168:171], v[216:219], v[82:85]
	v_mfma_f32_16x16x32_bf16 v[86:89], v[158:161], v[216:219], v[86:89]
	v_mfma_f32_16x16x32_bf16 v[86:89], v[154:157], v[212:215], v[86:89]
	s_setprio 0
	s_barrier
	s_mov_b32 m0, s47
	s_add_u32 s24, s24, 0x80
	s_addc_u32 s25, s25, 0
	global_load_lds_dwordx4 v132, s[24:25]
	s_mov_b32 m0, s48
	ds_read_b128 v[188:191], v150 offset:49152
	global_load_lds_dwordx4 v136, s[24:25]
	s_add_i32 s26, s46, s29
	s_mov_b32 m0, s26
	s_add_u32 s24, s24, 0x100000
	s_addc_u32 s25, s25, 0
	global_load_lds_dwordx4 v132, s[24:25]
	s_add_i32 m0, s26, 0x2000
	ds_read_b128 v[192:195], v150 offset:50176
	global_load_lds_dwordx4 v136, s[24:25]
	ds_read_b128 v[196:199], v150 offset:51200
	ds_read_b128 v[200:203], v150 offset:52224
	ds_read_b128 v[204:207], v150 offset:53248
	ds_read_b128 v[208:211], v150 offset:54272
	ds_read_b128 v[212:215], v150 offset:55296
	ds_read_b128 v[216:219], v150 offset:56320
	s_waitcnt vmcnt(6)
	s_waitcnt lgkmcnt(0)
	s_barrier
	s_setprio 1
	s_waitcnt lgkmcnt(0)
	v_mfma_f32_16x16x32_bf16 v[62:65], v[154:157], v[188:191], v[62:65]
	v_mfma_f32_16x16x32_bf16 v[62:65], v[158:161], v[192:195], v[62:65]
	v_mfma_f32_16x16x32_bf16 v[58:61], v[168:171], v[192:195], v[58:61]
	v_mfma_f32_16x16x32_bf16 v[58:61], v[164:167], v[188:191], v[58:61]
	v_mfma_f32_16x16x32_bf16 v[46:49], v[172:175], v[188:191], v[46:49]
	v_mfma_f32_16x16x32_bf16 v[46:49], v[176:179], v[192:195], v[46:49]
	v_mfma_f32_16x16x32_bf16 v[42:45], v[184:187], v[192:195], v[42:45]
	v_mfma_f32_16x16x32_bf16 v[42:45], v[180:183], v[188:191], v[42:45]
	v_mfma_f32_16x16x32_bf16 v[26:29], v[180:183], v[196:199], v[26:29]
	v_mfma_f32_16x16x32_bf16 v[26:29], v[184:187], v[200:203], v[26:29]
	v_mfma_f32_16x16x32_bf16 v[30:33], v[176:179], v[200:203], v[30:33]
	v_mfma_f32_16x16x32_bf16 v[30:33], v[172:175], v[196:199], v[30:33]
	v_mfma_f32_16x16x32_bf16 v[50:53], v[164:167], v[196:199], v[50:53]
	v_mfma_f32_16x16x32_bf16 v[50:53], v[168:171], v[200:203], v[50:53]
	v_mfma_f32_16x16x32_bf16 v[54:57], v[158:161], v[200:203], v[54:57]
	v_mfma_f32_16x16x32_bf16 v[54:57], v[154:157], v[196:199], v[54:57]
	v_mfma_f32_16x16x32_bf16 v[38:41], v[154:157], v[204:207], v[38:41]
	v_mfma_f32_16x16x32_bf16 v[38:41], v[158:161], v[208:211], v[38:41]
	v_mfma_f32_16x16x32_bf16 v[34:37], v[168:171], v[208:211], v[34:37]
	v_mfma_f32_16x16x32_bf16 v[34:37], v[164:167], v[204:207], v[34:37]
	v_mfma_f32_16x16x32_bf16 v[14:17], v[172:175], v[204:207], v[14:17]
	v_mfma_f32_16x16x32_bf16 v[14:17], v[176:179], v[208:211], v[14:17]
	v_mfma_f32_16x16x32_bf16 v[10:13], v[184:187], v[208:211], v[10:13]
	v_mfma_f32_16x16x32_bf16 v[10:13], v[180:183], v[204:207], v[10:13]
	v_mfma_f32_16x16x32_bf16 v[2:5], v[180:183], v[212:215], v[2:5]
	v_mfma_f32_16x16x32_bf16 v[2:5], v[184:187], v[216:219], v[2:5]
	v_mfma_f32_16x16x32_bf16 v[6:9], v[176:179], v[216:219], v[6:9]
	v_mfma_f32_16x16x32_bf16 v[6:9], v[172:175], v[212:215], v[6:9]
	v_mfma_f32_16x16x32_bf16 v[18:21], v[164:167], v[212:215], v[18:21]
	v_mfma_f32_16x16x32_bf16 v[18:21], v[168:171], v[216:219], v[18:21]
	v_mfma_f32_16x16x32_bf16 v[22:25], v[158:161], v[216:219], v[22:25]
	v_mfma_f32_16x16x32_bf16 v[22:25], v[154:157], v[212:215], v[22:25]
	s_setprio 0
	s_barrier
	s_add_i32 s56, s56, 2
	s_add_u32 s22, s22, 0x100
	s_addc_u32 s23, s23, 0
	s_add_u32 s54, s54, 0x100
	s_addc_u32 s55, s55, 0
	s_cmp_gt_u32 s56, 61
	s_cbranch_scc0 .LBB0_272
	s_and_b64 vcc, exec, s[16:17]
	s_cbranch_vccz .LBB0_277
	s_barrier
	v_lshl_add_u32 v138, s50, 8, v1
	s_cmp_gt_i32 s49, 63
	s_mov_b64 s[22:23], -1
	s_cbranch_scc1 .LBB0_278

.LBB0_1009:
	ds_read_b128 v[142:145], v155
	ds_read_b128 v[158:161], v155 offset:1024
	ds_read_b128 v[168:171], v155 offset:2048
	ds_read_b128 v[176:179], v155 offset:3072
	ds_read_b128 v[180:183], v156
	ds_read_b128 v[184:187], v156 offset:1024
	ds_read_b128 v[188:191], v156 offset:2048
	ds_read_b128 v[192:195], v156 offset:3072
	s_add_u32 s24, s22, 0xfff00080
	s_addc_u32 s25, s23, -1
	s_cmp_eq_u32 s51, 60
	s_cselect_b32 s27, s19, s25
	s_cselect_b32 s26, s47, s24
	s_cselect_b32 s25, s7, s50
	s_cselect_b32 s24, s48, s49
	s_mov_b32 m0, s40
	v_lshl_add_u64 v[146:147], s[22:23], 0, v[138:139]
	ds_read_b128 v[202:205], v157
	ds_read_b128 v[206:209], v157 offset:1024
	ds_read_b128 v[210:213], v157 offset:2048
	ds_read_b128 v[214:217], v157 offset:3072
	ds_read_b128 v[218:221], v157 offset:4096
	ds_read_b128 v[222:225], v157 offset:5120
	ds_read_b128 v[226:229], v157 offset:6144
	ds_read_b128 v[230:233], v157 offset:7168
	global_load_lds_dwordx4 v[146:147], off
	v_lshl_add_u64 v[146:147], s[22:23], 0, v[140:141]
	s_mov_b32 m0, s41
	s_nop 0
	global_load_lds_dwordx4 v[146:147], off
	s_waitcnt vmcnt(8)
	s_waitcnt lgkmcnt(0)
	s_barrier
	s_setprio 1
	s_waitcnt lgkmcnt(0)
	v_mfma_f32_16x16x32_bf16 v[126:129], v[142:145], v[202:205], v[126:129]
	v_mfma_f32_16x16x32_bf16 v[126:129], v[158:161], v[206:209], v[126:129]
	v_mfma_f32_16x16x32_bf16 v[122:125], v[176:179], v[206:209], v[122:125]
	v_mfma_f32_16x16x32_bf16 v[122:125], v[168:171], v[202:205], v[122:125]
	v_mfma_f32_16x16x32_bf16 v[118:121], v[180:183], v[202:205], v[118:121]
	v_mfma_f32_16x16x32_bf16 v[118:121], v[184:187], v[206:209], v[118:121]
	v_mfma_f32_16x16x32_bf16 v[114:117], v[192:195], v[206:209], v[114:117]
	v_mfma_f32_16x16x32_bf16 v[114:117], v[188:191], v[202:205], v[114:117]
	v_mfma_f32_16x16x32_bf16 v[98:101], v[188:191], v[210:213], v[98:101]
	v_mfma_f32_16x16x32_bf16 v[98:101], v[192:195], v[214:217], v[98:101]
	v_mfma_f32_16x16x32_bf16 v[102:105], v[184:187], v[214:217], v[102:105]
	v_mfma_f32_16x16x32_bf16 v[102:105], v[180:183], v[210:213], v[102:105]
	v_mfma_f32_16x16x32_bf16 v[106:109], v[168:171], v[210:213], v[106:109]
	v_mfma_f32_16x16x32_bf16 v[106:109], v[176:179], v[214:217], v[106:109]
	v_mfma_f32_16x16x32_bf16 v[110:113], v[158:161], v[214:217], v[110:113]
	v_mfma_f32_16x16x32_bf16 v[110:113], v[142:145], v[210:213], v[110:113]
	v_mfma_f32_16x16x32_bf16 v[94:97], v[142:145], v[218:221], v[94:97]
	v_mfma_f32_16x16x32_bf16 v[94:97], v[158:161], v[222:225], v[94:97]
	v_mfma_f32_16x16x32_bf16 v[90:93], v[176:179], v[222:225], v[90:93]
	v_mfma_f32_16x16x32_bf16 v[90:93], v[168:171], v[218:221], v[90:93]
	v_mfma_f32_16x16x32_bf16 v[86:89], v[180:183], v[218:221], v[86:89]
	v_mfma_f32_16x16x32_bf16 v[86:89], v[184:187], v[222:225], v[86:89]
	v_mfma_f32_16x16x32_bf16 v[82:85], v[192:195], v[222:225], v[82:85]
	v_mfma_f32_16x16x32_bf16 v[82:85], v[188:191], v[218:221], v[82:85]
	v_mfma_f32_16x16x32_bf16 v[66:69], v[188:191], v[226:229], v[66:69]
	v_mfma_f32_16x16x32_bf16 v[66:69], v[192:195], v[230:233], v[66:69]
	v_mfma_f32_16x16x32_bf16 v[70:73], v[184:187], v[230:233], v[70:73]
	v_mfma_f32_16x16x32_bf16 v[70:73], v[180:183], v[226:229], v[70:73]
	v_mfma_f32_16x16x32_bf16 v[74:77], v[168:171], v[226:229], v[74:77]
	v_mfma_f32_16x16x32_bf16 v[74:77], v[176:179], v[230:233], v[74:77]
	v_mfma_f32_16x16x32_bf16 v[78:81], v[158:161], v[230:233], v[78:81]
	v_mfma_f32_16x16x32_bf16 v[78:81], v[142:145], v[226:229], v[78:81]
	s_setprio 0
	s_barrier
	s_mov_b32 m0, s42
	v_lshl_add_u64 v[146:147], s[24:25], 0, v[132:133]
	s_add_u32 s52, s24, 0x100000
	ds_read_b128 v[202:205], v157 offset:16384
	ds_read_b128 v[206:209], v157 offset:17408
	ds_read_b128 v[210:213], v157 offset:18432
	ds_read_b128 v[214:217], v157 offset:19456
	ds_read_b128 v[218:221], v157 offset:20480
	ds_read_b128 v[222:225], v157 offset:21504
	ds_read_b128 v[226:229], v157 offset:22528
	ds_read_b128 v[230:233], v157 offset:23552
	global_load_lds_dwordx4 v[146:147], off
	v_lshl_add_u64 v[172:173], s[24:25], 0, v[136:137]
	s_mov_b32 m0, s43
	s_addc_u32 s53, s25, 0
	global_load_lds_dwordx4 v[172:173], off
	v_lshl_add_u64 v[196:197], s[52:53], 0, v[132:133]
	s_mov_b32 m0, s44
	v_lshl_add_u64 v[234:235], s[26:27], 0, v[134:135]
	global_load_lds_dwordx4 v[196:197], off
	v_lshl_add_u64 v[196:197], s[52:53], 0, v[136:137]
	s_add_i32 m0, s44, 0x2000
	s_nop 0
	global_load_lds_dwordx4 v[196:197], off
	v_lshl_add_u64 v[196:197], s[26:27], 0, v[130:131]
	s_mov_b32 m0, s33
	s_nop 0
	global_load_lds_dwordx4 v[196:197], off
	s_mov_b32 m0, s34
	s_nop 0
	global_load_lds_dwordx4 v[234:235], off
	s_waitcnt vmcnt(8)
	s_waitcnt lgkmcnt(0)
	s_barrier
	s_setprio 1
	s_waitcnt lgkmcnt(0)
	v_mfma_f32_16x16x32_bf16 v[62:65], v[142:145], v[202:205], v[62:65]
	v_mfma_f32_16x16x32_bf16 v[62:65], v[158:161], v[206:209], v[62:65]
	v_mfma_f32_16x16x32_bf16 v[58:61], v[176:179], v[206:209], v[58:61]
	v_mfma_f32_16x16x32_bf16 v[58:61], v[168:171], v[202:205], v[58:61]
	v_mfma_f32_16x16x32_bf16 v[54:57], v[180:183], v[202:205], v[54:57]
	v_mfma_f32_16x16x32_bf16 v[54:57], v[184:187], v[206:209], v[54:57]
	v_mfma_f32_16x16x32_bf16 v[50:53], v[192:195], v[206:209], v[50:53]
	v_mfma_f32_16x16x32_bf16 v[50:53], v[188:191], v[202:205], v[50:53]
	v_mfma_f32_16x16x32_bf16 v[34:37], v[188:191], v[210:213], v[34:37]
	v_mfma_f32_16x16x32_bf16 v[34:37], v[192:195], v[214:217], v[34:37]
	v_mfma_f32_16x16x32_bf16 v[38:41], v[184:187], v[214:217], v[38:41]
	v_mfma_f32_16x16x32_bf16 v[38:41], v[180:183], v[210:213], v[38:41]
	v_mfma_f32_16x16x32_bf16 v[42:45], v[168:171], v[210:213], v[42:45]
	v_mfma_f32_16x16x32_bf16 v[42:45], v[176:179], v[214:217], v[42:45]
	v_mfma_f32_16x16x32_bf16 v[46:49], v[158:161], v[214:217], v[46:49]
	v_mfma_f32_16x16x32_bf16 v[46:49], v[142:145], v[210:213], v[46:49]
	v_mfma_f32_16x16x32_bf16 v[30:33], v[142:145], v[218:221], v[30:33]
	v_mfma_f32_16x16x32_bf16 v[30:33], v[158:161], v[222:225], v[30:33]
	v_mfma_f32_16x16x32_bf16 v[26:29], v[176:179], v[222:225], v[26:29]
	v_mfma_f32_16x16x32_bf16 v[26:29], v[168:171], v[218:221], v[26:29]
	v_mfma_f32_16x16x32_bf16 v[22:25], v[180:183], v[218:221], v[22:25]
	v_mfma_f32_16x16x32_bf16 v[22:25], v[184:187], v[222:225], v[22:25]
	v_mfma_f32_16x16x32_bf16 v[18:21], v[192:195], v[222:225], v[18:21]
	v_mfma_f32_16x16x32_bf16 v[18:21], v[188:191], v[218:221], v[18:21]
	v_mfma_f32_16x16x32_bf16 v[2:5], v[188:191], v[226:229], v[2:5]
	v_mfma_f32_16x16x32_bf16 v[2:5], v[192:195], v[230:233], v[2:5]
	v_mfma_f32_16x16x32_bf16 v[6:9], v[184:187], v[230:233], v[6:9]
	v_mfma_f32_16x16x32_bf16 v[6:9], v[180:183], v[226:229], v[6:9]
	v_mfma_f32_16x16x32_bf16 v[10:13], v[168:171], v[226:229], v[10:13]
	v_mfma_f32_16x16x32_bf16 v[10:13], v[176:179], v[230:233], v[10:13]
	v_mfma_f32_16x16x32_bf16 v[14:17], v[158:161], v[230:233], v[14:17]
	v_mfma_f32_16x16x32_bf16 v[14:17], v[142:145], v[226:229], v[14:17]
	s_setprio 0
	s_barrier
	s_add_i32 s52, 0, 0x18000
	v_add_u32_e32 v166, s52, v153
	s_add_i32 s53, 0, 0x1c000
	ds_read_b128 v[142:145], v166
	ds_read_b128 v[158:161], v166 offset:1024
	ds_read_b128 v[168:171], v166 offset:2048
	ds_read_b128 v[176:179], v166 offset:3072
	v_add_u32_e32 v166, s53, v153
	ds_read_b128 v[180:183], v166
	ds_read_b128 v[184:187], v166 offset:1024
	ds_read_b128 v[188:191], v166 offset:2048
	ds_read_b128 v[192:195], v166 offset:3072
	s_add_u32 s26, s26, 0x100000
	s_addc_u32 s27, s27, 0
	s_mov_b32 m0, s35
	v_lshl_add_u64 v[236:237], s[26:27], 0, v[130:131]
	ds_read_b128 v[202:205], v157 offset:32768
	ds_read_b128 v[206:209], v157 offset:33792
	ds_read_b128 v[210:213], v157 offset:34816
	ds_read_b128 v[214:217], v157 offset:35840
	ds_read_b128 v[218:221], v157 offset:36864
	ds_read_b128 v[222:225], v157 offset:37888
	ds_read_b128 v[226:229], v157 offset:38912
	ds_read_b128 v[230:233], v157 offset:39936
	global_load_lds_dwordx4 v[236:237], off
	v_lshl_add_u64 v[236:237], s[26:27], 0, v[134:135]
	s_mov_b32 m0, s36
	s_nop 0
	global_load_lds_dwordx4 v[236:237], off
	s_waitcnt vmcnt(8)
	s_waitcnt lgkmcnt(0)
	s_barrier
	s_setprio 1
	s_waitcnt lgkmcnt(0)
	v_mfma_f32_16x16x32_bf16 v[126:129], v[142:145], v[202:205], v[126:129]
	v_mfma_f32_16x16x32_bf16 v[126:129], v[158:161], v[206:209], v[126:129]
	v_mfma_f32_16x16x32_bf16 v[122:125], v[176:179], v[206:209], v[122:125]
	v_mfma_f32_16x16x32_bf16 v[122:125], v[168:171], v[202:205], v[122:125]
	v_mfma_f32_16x16x32_bf16 v[118:121], v[180:183], v[202:205], v[118:121]
	v_mfma_f32_16x16x32_bf16 v[118:121], v[184:187], v[206:209], v[118:121]
	v_mfma_f32_16x16x32_bf16 v[114:117], v[192:195], v[206:209], v[114:117]
	v_mfma_f32_16x16x32_bf16 v[114:117], v[188:191], v[202:205], v[114:117]
	v_mfma_f32_16x16x32_bf16 v[98:101], v[188:191], v[210:213], v[98:101]
	v_mfma_f32_16x16x32_bf16 v[98:101], v[192:195], v[214:217], v[98:101]
	v_mfma_f32_16x16x32_bf16 v[102:105], v[184:187], v[214:217], v[102:105]
	v_mfma_f32_16x16x32_bf16 v[102:105], v[180:183], v[210:213], v[102:105]
	v_mfma_f32_16x16x32_bf16 v[106:109], v[168:171], v[210:213], v[106:109]
	v_mfma_f32_16x16x32_bf16 v[106:109], v[176:179], v[214:217], v[106:109]
	v_mfma_f32_16x16x32_bf16 v[110:113], v[158:161], v[214:217], v[110:113]
	v_mfma_f32_16x16x32_bf16 v[110:113], v[142:145], v[210:213], v[110:113]
	v_mfma_f32_16x16x32_bf16 v[94:97], v[142:145], v[218:221], v[94:97]
	v_mfma_f32_16x16x32_bf16 v[94:97], v[158:161], v[222:225], v[94:97]
	v_mfma_f32_16x16x32_bf16 v[90:93], v[176:179], v[222:225], v[90:93]
	v_mfma_f32_16x16x32_bf16 v[90:93], v[168:171], v[218:221], v[90:93]
	v_mfma_f32_16x16x32_bf16 v[86:89], v[180:183], v[218:221], v[86:89]
	v_mfma_f32_16x16x32_bf16 v[86:89], v[184:187], v[222:225], v[86:89]
	v_mfma_f32_16x16x32_bf16 v[82:85], v[192:195], v[222:225], v[82:85]
	v_mfma_f32_16x16x32_bf16 v[82:85], v[188:191], v[218:221], v[82:85]
	v_mfma_f32_16x16x32_bf16 v[66:69], v[188:191], v[226:229], v[66:69]
	v_mfma_f32_16x16x32_bf16 v[66:69], v[192:195], v[230:233], v[66:69]
	v_mfma_f32_16x16x32_bf16 v[70:73], v[184:187], v[230:233], v[70:73]
	v_mfma_f32_16x16x32_bf16 v[70:73], v[180:183], v[226:229], v[70:73]
	v_mfma_f32_16x16x32_bf16 v[74:77], v[168:171], v[226:229], v[74:77]
	v_mfma_f32_16x16x32_bf16 v[74:77], v[176:179], v[230:233], v[74:77]
	v_mfma_f32_16x16x32_bf16 v[78:81], v[158:161], v[230:233], v[78:81]
	v_mfma_f32_16x16x32_bf16 v[78:81], v[142:145], v[226:229], v[78:81]
	s_setprio 0
	s_barrier
	s_add_i32 s26, s52, s30
	v_lshl_add_u64 v[146:147], v[146:147], 0, s[14:15]
	s_mov_b32 m0, s26
	ds_read_b128 v[202:205], v157 offset:49152
	ds_read_b128 v[206:209], v157 offset:50176
	ds_read_b128 v[210:213], v157 offset:51200
	ds_read_b128 v[214:217], v157 offset:52224
	ds_read_b128 v[218:221], v157 offset:53248
	ds_read_b128 v[222:225], v157 offset:54272
	ds_read_b128 v[226:229], v157 offset:55296
	ds_read_b128 v[230:233], v157 offset:56320
	global_load_lds_dwordx4 v[146:147], off
	s_add_i32 m0, s26, 0x2000
	s_add_u32 s24, s24, 0x100080
	v_lshl_add_u64 v[146:147], v[172:173], 0, s[14:15]
	s_addc_u32 s25, s25, 0
	s_add_i32 s26, s53, s30
	global_load_lds_dwordx4 v[146:147], off
	v_lshl_add_u64 v[146:147], s[24:25], 0, v[132:133]
	s_mov_b32 m0, s26
	s_nop 0
	global_load_lds_dwordx4 v[146:147], off
	v_lshl_add_u64 v[146:147], s[24:25], 0, v[136:137]
	s_add_i32 m0, s26, 0x2000
	s_nop 0
	global_load_lds_dwordx4 v[146:147], off
	v_lshl_add_u64 v[146:147], v[196:197], 0, s[14:15]
	s_mov_b32 m0, s38
	s_nop 0
	global_load_lds_dwordx4 v[146:147], off
	v_lshl_add_u64 v[146:147], v[234:235], 0, s[14:15]
	s_mov_b32 m0, s39
	s_nop 0
	global_load_lds_dwordx4 v[146:147], off
	s_waitcnt vmcnt(8)
	s_waitcnt lgkmcnt(0)
	s_barrier
	s_setprio 1
	s_waitcnt lgkmcnt(0)
	v_mfma_f32_16x16x32_bf16 v[62:65], v[142:145], v[202:205], v[62:65]
	v_mfma_f32_16x16x32_bf16 v[62:65], v[158:161], v[206:209], v[62:65]
	v_mfma_f32_16x16x32_bf16 v[58:61], v[176:179], v[206:209], v[58:61]
	v_mfma_f32_16x16x32_bf16 v[58:61], v[168:171], v[202:205], v[58:61]
	v_mfma_f32_16x16x32_bf16 v[54:57], v[180:183], v[202:205], v[54:57]
	v_mfma_f32_16x16x32_bf16 v[54:57], v[184:187], v[206:209], v[54:57]
	v_mfma_f32_16x16x32_bf16 v[50:53], v[192:195], v[206:209], v[50:53]
	v_mfma_f32_16x16x32_bf16 v[50:53], v[188:191], v[202:205], v[50:53]
	v_mfma_f32_16x16x32_bf16 v[34:37], v[188:191], v[210:213], v[34:37]
	v_mfma_f32_16x16x32_bf16 v[34:37], v[192:195], v[214:217], v[34:37]
	v_mfma_f32_16x16x32_bf16 v[38:41], v[184:187], v[214:217], v[38:41]
	v_mfma_f32_16x16x32_bf16 v[38:41], v[180:183], v[210:213], v[38:41]
	v_mfma_f32_16x16x32_bf16 v[42:45], v[168:171], v[210:213], v[42:45]
	v_mfma_f32_16x16x32_bf16 v[42:45], v[176:179], v[214:217], v[42:45]
	v_mfma_f32_16x16x32_bf16 v[46:49], v[158:161], v[214:217], v[46:49]
	v_mfma_f32_16x16x32_bf16 v[46:49], v[142:145], v[210:213], v[46:49]
	v_mfma_f32_16x16x32_bf16 v[30:33], v[142:145], v[218:221], v[30:33]
	v_mfma_f32_16x16x32_bf16 v[30:33], v[158:161], v[222:225], v[30:33]
	v_mfma_f32_16x16x32_bf16 v[26:29], v[176:179], v[222:225], v[26:29]
	v_mfma_f32_16x16x32_bf16 v[26:29], v[168:171], v[218:221], v[26:29]
	v_mfma_f32_16x16x32_bf16 v[22:25], v[180:183], v[218:221], v[22:25]
	v_mfma_f32_16x16x32_bf16 v[22:25], v[184:187], v[222:225], v[22:25]
	v_mfma_f32_16x16x32_bf16 v[18:21], v[192:195], v[222:225], v[18:21]
	v_mfma_f32_16x16x32_bf16 v[18:21], v[188:191], v[218:221], v[18:21]
	v_mfma_f32_16x16x32_bf16 v[2:5], v[188:191], v[226:229], v[2:5]
	v_mfma_f32_16x16x32_bf16 v[2:5], v[192:195], v[230:233], v[2:5]
	v_mfma_f32_16x16x32_bf16 v[6:9], v[184:187], v[230:233], v[6:9]
	v_mfma_f32_16x16x32_bf16 v[6:9], v[180:183], v[226:229], v[6:9]
	v_mfma_f32_16x16x32_bf16 v[10:13], v[168:171], v[226:229], v[10:13]
	v_mfma_f32_16x16x32_bf16 v[10:13], v[176:179], v[230:233], v[10:13]
	v_mfma_f32_16x16x32_bf16 v[14:17], v[158:161], v[230:233], v[14:17]
	v_mfma_f32_16x16x32_bf16 v[14:17], v[142:145], v[226:229], v[14:17]
	s_setprio 0
	s_barrier
	s_add_i32 s51, s51, 2
	s_add_u32 s22, s22, 0x100
	s_addc_u32 s23, s23, 0
	s_add_u32 s49, s49, 0x100
	s_addc_u32 s50, s50, 0
	s_cmp_gt_u32 s51, 61
	s_cbranch_scc0 .LBB0_1009
	s_and_b64 vcc, exec, s[16:17]
	s_cbranch_vccz .LBB0_1012
	s_barrier

.LBB0_1019:
	s_add_i32 s21, s20, 0x100
	s_and_b64 s[18:19], s[18:19], exec
	s_cselect_b32 s19, 0, s21
	s_cselect_b32 s18, 0, 0
	s_add_u32 s22, s8, s19
	s_addc_u32 s23, s9, s18
	ds_read_b128 v[144:147], v139
	ds_read_b128 v[150:153], v139 offset:1024
	ds_read_b128 v[154:157], v139 offset:2048
	ds_read_b128 v[158:161], v139 offset:3072
	ds_read_b128 v[168:171], v140
	ds_read_b128 v[176:179], v140 offset:1024
	ds_read_b128 v[180:183], v140 offset:2048
	ds_read_b128 v[184:187], v140 offset:3072
	s_add_u32 s24, s10, s19
	s_addc_u32 s25, s11, s18
	s_add_u32 s30, s12, s20
	s_addc_u32 s31, s13, 0
	s_add_u32 s26, s24, 0x100000
	s_addc_u32 s27, s25, 0
	s_add_u32 s20, s22, 0x100000
	s_addc_u32 s21, s23, 0
	s_add_u32 s18, s24, 0x100080
	s_addc_u32 s19, s25, 0
	v_lshl_add_u64 v[172:173], s[30:31], 0, v[130:131]
	s_mov_b32 m0, s40
	v_lshl_add_u64 v[172:173], v[172:173], 0, s[14:15]
	ds_read_b128 v[188:191], v141
	ds_read_b128 v[192:195], v141 offset:1024
	ds_read_b128 v[202:205], v141 offset:2048
	ds_read_b128 v[206:209], v141 offset:3072
	ds_read_b128 v[210:213], v141 offset:4096
	ds_read_b128 v[214:217], v141 offset:5120
	ds_read_b128 v[218:221], v141 offset:6144
	ds_read_b128 v[222:225], v141 offset:7168
	global_load_lds_dwordx4 v[172:173], off
	v_lshl_add_u64 v[172:173], s[30:31], 0, v[134:135]
	v_lshl_add_u64 v[172:173], v[172:173], 0, s[14:15]
	s_mov_b32 m0, s41
	s_nop 0
	global_load_lds_dwordx4 v[172:173], off
	s_waitcnt vmcnt(8)
	s_waitcnt lgkmcnt(0)
	s_barrier
	s_setprio 1
	s_waitcnt lgkmcnt(0)
	v_mfma_f32_16x16x32_bf16 v[126:129], v[144:147], v[188:191], v[126:129]
	v_mfma_f32_16x16x32_bf16 v[126:129], v[150:153], v[192:195], v[126:129]
	v_mfma_f32_16x16x32_bf16 v[122:125], v[158:161], v[192:195], v[122:125]
	v_mfma_f32_16x16x32_bf16 v[122:125], v[154:157], v[188:191], v[122:125]
	v_mfma_f32_16x16x32_bf16 v[110:113], v[168:171], v[188:191], v[110:113]
	v_mfma_f32_16x16x32_bf16 v[110:113], v[176:179], v[192:195], v[110:113]
	v_mfma_f32_16x16x32_bf16 v[106:109], v[184:187], v[192:195], v[106:109]
	v_mfma_f32_16x16x32_bf16 v[106:109], v[180:183], v[188:191], v[106:109]
	v_mfma_f32_16x16x32_bf16 v[90:93], v[180:183], v[202:205], v[90:93]
	v_mfma_f32_16x16x32_bf16 v[90:93], v[184:187], v[206:209], v[90:93]
	v_mfma_f32_16x16x32_bf16 v[94:97], v[176:179], v[206:209], v[94:97]
	v_mfma_f32_16x16x32_bf16 v[94:97], v[168:171], v[202:205], v[94:97]
	v_mfma_f32_16x16x32_bf16 v[114:117], v[154:157], v[202:205], v[114:117]
	v_mfma_f32_16x16x32_bf16 v[114:117], v[158:161], v[206:209], v[114:117]
	v_mfma_f32_16x16x32_bf16 v[118:121], v[150:153], v[206:209], v[118:121]
	v_mfma_f32_16x16x32_bf16 v[118:121], v[144:147], v[202:205], v[118:121]
	v_mfma_f32_16x16x32_bf16 v[102:105], v[144:147], v[210:213], v[102:105]
	v_mfma_f32_16x16x32_bf16 v[102:105], v[150:153], v[214:217], v[102:105]
	v_mfma_f32_16x16x32_bf16 v[98:101], v[158:161], v[214:217], v[98:101]
	v_mfma_f32_16x16x32_bf16 v[98:101], v[154:157], v[210:213], v[98:101]
	v_mfma_f32_16x16x32_bf16 v[78:81], v[168:171], v[210:213], v[78:81]
	v_mfma_f32_16x16x32_bf16 v[78:81], v[176:179], v[214:217], v[78:81]
	v_mfma_f32_16x16x32_bf16 v[74:77], v[184:187], v[214:217], v[74:77]
	v_mfma_f32_16x16x32_bf16 v[74:77], v[180:183], v[210:213], v[74:77]
	v_mfma_f32_16x16x32_bf16 v[66:69], v[180:183], v[218:221], v[66:69]
	v_mfma_f32_16x16x32_bf16 v[66:69], v[184:187], v[222:225], v[66:69]
	v_mfma_f32_16x16x32_bf16 v[70:73], v[176:179], v[222:225], v[70:73]
	v_mfma_f32_16x16x32_bf16 v[70:73], v[168:171], v[218:221], v[70:73]
	v_mfma_f32_16x16x32_bf16 v[82:85], v[154:157], v[218:221], v[82:85]
	v_mfma_f32_16x16x32_bf16 v[82:85], v[158:161], v[222:225], v[82:85]
	v_mfma_f32_16x16x32_bf16 v[86:89], v[150:153], v[222:225], v[86:89]
	v_mfma_f32_16x16x32_bf16 v[86:89], v[144:147], v[218:221], v[86:89]
	s_setprio 0
	s_barrier
	s_mov_b32 m0, s42
	v_lshl_add_u64 v[172:173], s[24:25], 0, v[132:133]
	ds_read_b128 v[188:191], v141 offset:16384
	ds_read_b128 v[192:195], v141 offset:17408
	ds_read_b128 v[202:205], v141 offset:18432
	ds_read_b128 v[206:209], v141 offset:19456
	ds_read_b128 v[210:213], v141 offset:20480
	ds_read_b128 v[214:217], v141 offset:21504
	ds_read_b128 v[218:221], v141 offset:22528
	ds_read_b128 v[222:225], v141 offset:23552
	global_load_lds_dwordx4 v[172:173], off
	v_lshl_add_u64 v[196:197], s[24:25], 0, v[136:137]
	s_mov_b32 m0, s43
	v_lshl_add_u64 v[226:227], s[26:27], 0, v[132:133]
	global_load_lds_dwordx4 v[196:197], off
	s_mov_b32 m0, s44
	v_lshl_add_u64 v[228:229], s[22:23], 0, v[134:135]
	global_load_lds_dwordx4 v[226:227], off
	v_lshl_add_u64 v[226:227], s[26:27], 0, v[136:137]
	s_mov_b32 m0, s45
	s_nop 0
	global_load_lds_dwordx4 v[226:227], off
	v_lshl_add_u64 v[226:227], s[22:23], 0, v[130:131]
	s_mov_b32 m0, s7
	s_nop 0
	global_load_lds_dwordx4 v[226:227], off
	s_mov_b32 m0, s34
	s_nop 0
	global_load_lds_dwordx4 v[228:229], off
	s_waitcnt vmcnt(8)
	s_waitcnt lgkmcnt(0)
	s_barrier
	s_setprio 1
	s_waitcnt lgkmcnt(0)
	v_mfma_f32_16x16x32_bf16 v[62:65], v[144:147], v[188:191], v[62:65]
	v_mfma_f32_16x16x32_bf16 v[62:65], v[150:153], v[192:195], v[62:65]
	v_mfma_f32_16x16x32_bf16 v[58:61], v[158:161], v[192:195], v[58:61]
	v_mfma_f32_16x16x32_bf16 v[58:61], v[154:157], v[188:191], v[58:61]
	v_mfma_f32_16x16x32_bf16 v[46:49], v[168:171], v[188:191], v[46:49]
	v_mfma_f32_16x16x32_bf16 v[46:49], v[176:179], v[192:195], v[46:49]
	v_mfma_f32_16x16x32_bf16 v[42:45], v[184:187], v[192:195], v[42:45]
	v_mfma_f32_16x16x32_bf16 v[42:45], v[180:183], v[188:191], v[42:45]
	v_mfma_f32_16x16x32_bf16 v[26:29], v[180:183], v[202:205], v[26:29]
	v_mfma_f32_16x16x32_bf16 v[26:29], v[184:187], v[206:209], v[26:29]
	v_mfma_f32_16x16x32_bf16 v[30:33], v[176:179], v[206:209], v[30:33]
	v_mfma_f32_16x16x32_bf16 v[30:33], v[168:171], v[202:205], v[30:33]
	v_mfma_f32_16x16x32_bf16 v[50:53], v[154:157], v[202:205], v[50:53]
	v_mfma_f32_16x16x32_bf16 v[50:53], v[158:161], v[206:209], v[50:53]
	v_mfma_f32_16x16x32_bf16 v[54:57], v[150:153], v[206:209], v[54:57]
	v_mfma_f32_16x16x32_bf16 v[54:57], v[144:147], v[202:205], v[54:57]
	v_mfma_f32_16x16x32_bf16 v[38:41], v[144:147], v[210:213], v[38:41]
	v_mfma_f32_16x16x32_bf16 v[38:41], v[150:153], v[214:217], v[38:41]
	v_mfma_f32_16x16x32_bf16 v[34:37], v[158:161], v[214:217], v[34:37]
	v_mfma_f32_16x16x32_bf16 v[34:37], v[154:157], v[210:213], v[34:37]
	v_mfma_f32_16x16x32_bf16 v[14:17], v[168:171], v[210:213], v[14:17]
	v_mfma_f32_16x16x32_bf16 v[14:17], v[176:179], v[214:217], v[14:17]
	v_mfma_f32_16x16x32_bf16 v[10:13], v[184:187], v[214:217], v[10:13]
	v_mfma_f32_16x16x32_bf16 v[10:13], v[180:183], v[210:213], v[10:13]
	v_mfma_f32_16x16x32_bf16 v[2:5], v[180:183], v[218:221], v[2:5]
	v_mfma_f32_16x16x32_bf16 v[2:5], v[184:187], v[222:225], v[2:5]
	v_mfma_f32_16x16x32_bf16 v[6:9], v[176:179], v[222:225], v[6:9]
	v_mfma_f32_16x16x32_bf16 v[6:9], v[168:171], v[218:221], v[6:9]
	v_mfma_f32_16x16x32_bf16 v[18:21], v[154:157], v[218:221], v[18:21]
	v_mfma_f32_16x16x32_bf16 v[18:21], v[158:161], v[222:225], v[18:21]
	v_mfma_f32_16x16x32_bf16 v[22:25], v[150:153], v[222:225], v[22:25]
	v_mfma_f32_16x16x32_bf16 v[22:25], v[144:147], v[218:221], v[22:25]
	s_setprio 0
	s_barrier
	ds_read_b128 v[144:147], v142
	ds_read_b128 v[150:153], v142 offset:1024
	ds_read_b128 v[154:157], v142 offset:2048
	ds_read_b128 v[158:161], v142 offset:3072
	ds_read_b128 v[168:171], v143
	ds_read_b128 v[176:179], v143 offset:1024
	ds_read_b128 v[180:183], v143 offset:2048
	ds_read_b128 v[184:187], v143 offset:3072
	s_mov_b32 m0, s35
	v_lshl_add_u64 v[230:231], s[20:21], 0, v[130:131]
	ds_read_b128 v[188:191], v141 offset:32768
	ds_read_b128 v[192:195], v141 offset:33792
	ds_read_b128 v[202:205], v141 offset:34816
	ds_read_b128 v[206:209], v141 offset:35840
	ds_read_b128 v[210:213], v141 offset:36864
	ds_read_b128 v[214:217], v141 offset:37888
	ds_read_b128 v[218:221], v141 offset:38912
	ds_read_b128 v[222:225], v141 offset:39936
	global_load_lds_dwordx4 v[230:231], off
	v_lshl_add_u64 v[230:231], s[20:21], 0, v[134:135]
	s_mov_b32 m0, s36
	s_nop 0
	global_load_lds_dwordx4 v[230:231], off
	s_waitcnt vmcnt(8)
	s_waitcnt lgkmcnt(0)
	s_barrier
	s_setprio 1
	s_waitcnt lgkmcnt(0)
	v_mfma_f32_16x16x32_bf16 v[126:129], v[144:147], v[188:191], v[126:129]
	v_mfma_f32_16x16x32_bf16 v[126:129], v[150:153], v[192:195], v[126:129]
	v_mfma_f32_16x16x32_bf16 v[122:125], v[158:161], v[192:195], v[122:125]
	v_mfma_f32_16x16x32_bf16 v[122:125], v[154:157], v[188:191], v[122:125]
	v_mfma_f32_16x16x32_bf16 v[110:113], v[168:171], v[188:191], v[110:113]
	v_mfma_f32_16x16x32_bf16 v[110:113], v[176:179], v[192:195], v[110:113]
	v_mfma_f32_16x16x32_bf16 v[106:109], v[184:187], v[192:195], v[106:109]
	v_mfma_f32_16x16x32_bf16 v[106:109], v[180:183], v[188:191], v[106:109]
	v_mfma_f32_16x16x32_bf16 v[90:93], v[180:183], v[202:205], v[90:93]
	v_mfma_f32_16x16x32_bf16 v[90:93], v[184:187], v[206:209], v[90:93]
	v_mfma_f32_16x16x32_bf16 v[94:97], v[176:179], v[206:209], v[94:97]
	v_mfma_f32_16x16x32_bf16 v[94:97], v[168:171], v[202:205], v[94:97]
	v_mfma_f32_16x16x32_bf16 v[114:117], v[154:157], v[202:205], v[114:117]
	v_mfma_f32_16x16x32_bf16 v[114:117], v[158:161], v[206:209], v[114:117]
	v_mfma_f32_16x16x32_bf16 v[118:121], v[150:153], v[206:209], v[118:121]
	v_mfma_f32_16x16x32_bf16 v[118:121], v[144:147], v[202:205], v[118:121]
	v_mfma_f32_16x16x32_bf16 v[102:105], v[144:147], v[210:213], v[102:105]
	v_mfma_f32_16x16x32_bf16 v[102:105], v[150:153], v[214:217], v[102:105]
	v_mfma_f32_16x16x32_bf16 v[98:101], v[158:161], v[214:217], v[98:101]
	v_mfma_f32_16x16x32_bf16 v[98:101], v[154:157], v[210:213], v[98:101]
	v_mfma_f32_16x16x32_bf16 v[78:81], v[168:171], v[210:213], v[78:81]
	v_mfma_f32_16x16x32_bf16 v[78:81], v[176:179], v[214:217], v[78:81]
	v_mfma_f32_16x16x32_bf16 v[74:77], v[184:187], v[214:217], v[74:77]
	v_mfma_f32_16x16x32_bf16 v[74:77], v[180:183], v[210:213], v[74:77]
	v_mfma_f32_16x16x32_bf16 v[66:69], v[180:183], v[218:221], v[66:69]
	v_mfma_f32_16x16x32_bf16 v[66:69], v[184:187], v[222:225], v[66:69]
	v_mfma_f32_16x16x32_bf16 v[70:73], v[176:179], v[222:225], v[70:73]
	v_mfma_f32_16x16x32_bf16 v[70:73], v[168:171], v[218:221], v[70:73]
	v_mfma_f32_16x16x32_bf16 v[82:85], v[154:157], v[218:221], v[82:85]
	v_mfma_f32_16x16x32_bf16 v[82:85], v[158:161], v[222:225], v[82:85]
	v_mfma_f32_16x16x32_bf16 v[86:89], v[150:153], v[222:225], v[86:89]
	v_mfma_f32_16x16x32_bf16 v[86:89], v[144:147], v[218:221], v[86:89]
	s_setprio 0
	s_barrier
	s_mov_b32 m0, s46
	v_lshl_add_u64 v[172:173], v[172:173], 0, s[14:15]
	ds_read_b128 v[188:191], v141 offset:49152
	ds_read_b128 v[192:195], v141 offset:50176
	ds_read_b128 v[202:205], v141 offset:51200
	ds_read_b128 v[206:209], v141 offset:52224
	ds_read_b128 v[210:213], v141 offset:53248
	ds_read_b128 v[214:217], v141 offset:54272
	ds_read_b128 v[218:221], v141 offset:55296
	ds_read_b128 v[222:225], v141 offset:56320
	global_load_lds_dwordx4 v[172:173], off
	v_lshl_add_u64 v[172:173], v[196:197], 0, s[14:15]
	s_mov_b32 m0, s47
	s_nop 0
	global_load_lds_dwordx4 v[172:173], off
	v_lshl_add_u64 v[172:173], s[18:19], 0, v[132:133]
	s_mov_b32 m0, s48
	s_nop 0
	global_load_lds_dwordx4 v[172:173], off
	v_lshl_add_u64 v[172:173], s[18:19], 0, v[136:137]
	s_mov_b32 m0, s49
	s_nop 0
	global_load_lds_dwordx4 v[172:173], off
	v_lshl_add_u64 v[172:173], v[226:227], 0, s[14:15]
	s_mov_b32 m0, s38
	s_nop 0
	global_load_lds_dwordx4 v[172:173], off
	v_lshl_add_u64 v[172:173], v[228:229], 0, s[14:15]
	s_mov_b32 m0, s39
	s_nop 0
	global_load_lds_dwordx4 v[172:173], off
	s_waitcnt vmcnt(8)
	s_waitcnt lgkmcnt(0)
	s_barrier
	s_setprio 1
	s_waitcnt lgkmcnt(0)
	v_mfma_f32_16x16x32_bf16 v[62:65], v[144:147], v[188:191], v[62:65]
	v_mfma_f32_16x16x32_bf16 v[62:65], v[150:153], v[192:195], v[62:65]
	v_mfma_f32_16x16x32_bf16 v[58:61], v[158:161], v[192:195], v[58:61]
	v_mfma_f32_16x16x32_bf16 v[58:61], v[154:157], v[188:191], v[58:61]
	v_mfma_f32_16x16x32_bf16 v[46:49], v[168:171], v[188:191], v[46:49]
	v_mfma_f32_16x16x32_bf16 v[46:49], v[176:179], v[192:195], v[46:49]
	v_mfma_f32_16x16x32_bf16 v[42:45], v[184:187], v[192:195], v[42:45]
	v_mfma_f32_16x16x32_bf16 v[42:45], v[180:183], v[188:191], v[42:45]
	v_mfma_f32_16x16x32_bf16 v[26:29], v[180:183], v[202:205], v[26:29]
	v_mfma_f32_16x16x32_bf16 v[26:29], v[184:187], v[206:209], v[26:29]
	v_mfma_f32_16x16x32_bf16 v[30:33], v[176:179], v[206:209], v[30:33]
	v_mfma_f32_16x16x32_bf16 v[30:33], v[168:171], v[202:205], v[30:33]
	v_mfma_f32_16x16x32_bf16 v[50:53], v[154:157], v[202:205], v[50:53]
	v_mfma_f32_16x16x32_bf16 v[50:53], v[158:161], v[206:209], v[50:53]
	v_mfma_f32_16x16x32_bf16 v[54:57], v[150:153], v[206:209], v[54:57]
	v_mfma_f32_16x16x32_bf16 v[54:57], v[144:147], v[202:205], v[54:57]
	v_mfma_f32_16x16x32_bf16 v[38:41], v[144:147], v[210:213], v[38:41]
	v_mfma_f32_16x16x32_bf16 v[38:41], v[150:153], v[214:217], v[38:41]
	v_mfma_f32_16x16x32_bf16 v[34:37], v[158:161], v[214:217], v[34:37]
	v_mfma_f32_16x16x32_bf16 v[34:37], v[154:157], v[210:213], v[34:37]
	v_mfma_f32_16x16x32_bf16 v[14:17], v[168:171], v[210:213], v[14:17]
	v_mfma_f32_16x16x32_bf16 v[14:17], v[176:179], v[214:217], v[14:17]
	v_mfma_f32_16x16x32_bf16 v[10:13], v[184:187], v[214:217], v[10:13]
	v_mfma_f32_16x16x32_bf16 v[10:13], v[180:183], v[210:213], v[10:13]
	v_mfma_f32_16x16x32_bf16 v[2:5], v[180:183], v[218:221], v[2:5]
	v_mfma_f32_16x16x32_bf16 v[2:5], v[184:187], v[222:225], v[2:5]
	v_mfma_f32_16x16x32_bf16 v[6:9], v[176:179], v[222:225], v[6:9]
	v_mfma_f32_16x16x32_bf16 v[6:9], v[168:171], v[218:221], v[6:9]
	v_mfma_f32_16x16x32_bf16 v[18:21], v[154:157], v[218:221], v[18:21]
	v_mfma_f32_16x16x32_bf16 v[18:21], v[158:161], v[222:225], v[18:21]
	v_mfma_f32_16x16x32_bf16 v[22:25], v[150:153], v[222:225], v[22:25]
	v_mfma_f32_16x16x32_bf16 v[22:25], v[144:147], v[218:221], v[22:25]
	s_setprio 0
	s_barrier
	s_andn2_b64 vcc, exec, s[16:17]
	s_mov_b64 s[18:19], -1
	s_mov_b64 s[16:17], 0
	s_movk_i32 s20, 0x100
	s_cbranch_vccz .LBB0_1019
	s_lshl_b32 s7, s33, 21
	v_readlane_b32 s0, v249, 29
	v_lshl_or_b32 v130, s6, 8, v148
	v_mov_b32_e32 v139, 0
	s_add_u32 s8, s0, s7
	v_readlane_b32 s0, v249, 31
	v_or_b32_e32 v130, s37, v130
	v_cvt_pk_bf16_f32 v70, v70, v71
	v_cvt_pk_bf16_f32 v71, v72, v73
	v_cvt_pk_bf16_f32 v72, v66, v67
	v_add_u32_e32 v66, 0x80, v138
	v_mov_b32_e32 v67, v139
	s_addc_u32 s9, s0, 0
	v_ashrrev_i32_e32 v131, 31, v130
	v_lshlrev_b64 v[132:133], 13, v[138:139]
	v_cvt_pk_bf16_f32 v110, v110, v111
	v_cvt_pk_bf16_f32 v111, v112, v113
	v_cvt_pk_bf16_f32 v112, v106, v107
	v_or_b32_e32 v106, 16, v138
	v_mov_b32_e32 v107, v139
	v_lshlrev_b64 v[66:67], 13, v[66:67]
	v_cvt_pk_bf16_f32 v46, v46, v47
	v_cvt_pk_bf16_f32 v47, v48, v49
	v_cvt_pk_bf16_f32 v48, v42, v43
	v_add_u32_e32 v42, 0x90, v138
	v_mov_b32_e32 v43, v139
	v_lshl_add_u64 v[132:133], s[8:9], 0, v[132:133]
	v_lshlrev_b64 v[130:131], 1, v[130:131]
	v_lshlrev_b64 v[106:107], 13, v[106:107]
	v_cvt_pk_bf16_f32 v94, v94, v95
	v_cvt_pk_bf16_f32 v95, v96, v97
	v_cvt_pk_bf16_f32 v96, v90, v91
	v_or_b32_e32 v90, 32, v138
	v_mov_b32_e32 v91, v139
	v_lshl_add_u64 v[66:67], s[8:9], 0, v[66:67]
	v_lshlrev_b64 v[42:43], 13, v[42:43]
	v_cvt_pk_bf16_f32 v30, v30, v31
	v_cvt_pk_bf16_f32 v31, v32, v33
	v_cvt_pk_bf16_f32 v32, v26, v27
	v_add_u32_e32 v26, 0xa0, v138
	v_mov_b32_e32 v27, v139
	v_lshl_add_u64 v[132:133], v[132:133], 0, v[130:131]
	v_cvt_pk_bf16_f32 v113, v108, v109
	v_lshl_add_u64 v[106:107], s[8:9], 0, v[106:107]
	v_lshlrev_b64 v[90:91], 13, v[90:91]
	v_cvt_pk_bf16_f32 v78, v78, v79
	v_cvt_pk_bf16_f32 v79, v80, v81
	v_cvt_pk_bf16_f32 v80, v74, v75
	v_or_b32_e32 v74, 48, v138
	v_mov_b32_e32 v75, v139
	v_lshl_add_u64 v[66:67], v[66:67], 0, v[130:131]
	v_cvt_pk_bf16_f32 v49, v44, v45
	v_lshl_add_u64 v[42:43], s[8:9], 0, v[42:43]
	v_lshlrev_b64 v[26:27], 13, v[26:27]
	v_add_u32_e32 v138, 0xb0, v138
	global_store_dwordx4 v[132:133], v[110:113], off offset:256
	v_cvt_pk_bf16_f32 v97, v92, v93
	v_lshl_add_u64 v[90:91], s[8:9], 0, v[90:91]
	v_lshl_add_u64 v[110:111], v[106:107], 0, v[130:131]
	v_lshlrev_b64 v[74:75], 13, v[74:75]
	global_store_dwordx4 v[66:67], v[46:49], off offset:256
	v_cvt_pk_bf16_f32 v33, v28, v29
	v_lshl_add_u64 v[26:27], s[8:9], 0, v[26:27]
	v_lshl_add_u64 v[46:47], v[42:43], 0, v[130:131]
	v_cvt_pk_bf16_f32 v14, v14, v15
	v_cvt_pk_bf16_f32 v15, v16, v17
	v_cvt_pk_bf16_f32 v16, v10, v11
	v_lshlrev_b64 v[10:11], 13, v[138:139]
	global_store_dwordx4 v[110:111], v[94:97], off offset:256
	v_cvt_pk_bf16_f32 v81, v76, v77
	v_lshl_add_u64 v[74:75], s[8:9], 0, v[74:75]
	v_lshl_add_u64 v[94:95], v[90:91], 0, v[130:131]
	global_store_dwordx4 v[46:47], v[30:33], off offset:256
	v_cvt_pk_bf16_f32 v17, v12, v13
	v_lshl_add_u64 v[10:11], s[8:9], 0, v[10:11]
	v_lshl_add_u64 v[30:31], v[26:27], 0, v[130:131]
	v_cvt_pk_bf16_f32 v126, v126, v127
	v_cvt_pk_bf16_f32 v127, v128, v129
	v_cvt_pk_bf16_f32 v128, v122, v123
	v_cvt_pk_bf16_f32 v129, v124, v125
	v_cvt_pk_bf16_f32 v106, v118, v119
	v_cvt_pk_bf16_f32 v107, v120, v121
	v_cvt_pk_bf16_f32 v108, v114, v115
	v_cvt_pk_bf16_f32 v109, v116, v117
	v_cvt_pk_bf16_f32 v90, v102, v103
	v_cvt_pk_bf16_f32 v91, v104, v105
	v_cvt_pk_bf16_f32 v92, v98, v99
	v_cvt_pk_bf16_f32 v93, v100, v101
	global_store_dwordx4 v[94:95], v[78:81], off offset:256
	v_cvt_pk_bf16_f32 v76, v82, v83
	v_cvt_pk_bf16_f32 v77, v84, v85
	v_lshl_add_u64 v[78:79], v[74:75], 0, v[130:131]
	v_cvt_pk_bf16_f32 v74, v86, v87
	v_cvt_pk_bf16_f32 v75, v88, v89
	v_cvt_pk_bf16_f32 v73, v68, v69
	v_cvt_pk_bf16_f32 v62, v62, v63
	v_cvt_pk_bf16_f32 v63, v64, v65
	v_cvt_pk_bf16_f32 v64, v58, v59
	v_cvt_pk_bf16_f32 v65, v60, v61
	v_cvt_pk_bf16_f32 v42, v54, v55
	v_cvt_pk_bf16_f32 v43, v56, v57
	v_cvt_pk_bf16_f32 v44, v50, v51
	v_cvt_pk_bf16_f32 v45, v52, v53
	v_cvt_pk_bf16_f32 v26, v38, v39
	v_cvt_pk_bf16_f32 v27, v40, v41
	v_cvt_pk_bf16_f32 v28, v34, v35
	v_cvt_pk_bf16_f32 v29, v36, v37
	global_store_dwordx4 v[30:31], v[14:17], off offset:256
	v_cvt_pk_bf16_f32 v12, v18, v19
	v_cvt_pk_bf16_f32 v13, v20, v21
	v_lshl_add_u64 v[14:15], v[10:11], 0, v[130:131]
	v_cvt_pk_bf16_f32 v10, v22, v23
	v_cvt_pk_bf16_f32 v11, v24, v25
	v_cvt_pk_bf16_f32 v6, v6, v7
	v_cvt_pk_bf16_f32 v7, v8, v9
	v_cvt_pk_bf16_f32 v8, v2, v3
	v_cvt_pk_bf16_f32 v9, v4, v5
	global_store_dwordx4 v[132:133], v[126:129], off
	global_store_dwordx4 v[110:111], v[106:109], off
	global_store_dwordx4 v[94:95], v[90:93], off
	global_store_dwordx4 v[78:79], v[74:77], off
	global_store_dwordx4 v[78:79], v[70:73], off offset:256
	global_store_dwordx4 v[66:67], v[62:65], off
	global_store_dwordx4 v[46:47], v[42:45], off
	global_store_dwordx4 v[30:31], v[26:29], off
	global_store_dwordx4 v[14:15], v[10:13], off
	global_store_dwordx4 v[14:15], v[6:9], off offset:256
	s_waitcnt vmcnt(0)
	s_cmpk_lt_u32 s3, 0x100
	s_cbranch_scc0 .LBB0_1022
	s_barrier

.LBB0_1172:
	s_add_u32 s62, s20, 0xfff00000
	s_addc_u32 s63, s21, -1
	s_mov_b32 m0, s37
	ds_read_b128 v[142:145], v148
	global_load_lds_dwordx4 v130, s[62:63]
	s_mov_b32 m0, s38
	ds_read_b128 v[154:157], v148 offset:1024
	global_load_lds_dwordx4 v134, s[62:63]
	s_mov_b32 m0, s42
	ds_read_b128 v[158:161], v148 offset:2048
	global_load_lds_dwordx4 v138, s[20:21]
	s_mov_b32 m0, s43
	ds_read_b128 v[168:171], v148 offset:3072
	global_load_lds_dwordx4 v140, s[20:21]
	ds_read_b128 v[176:179], v149
	ds_read_b128 v[180:183], v149 offset:1024
	ds_read_b128 v[184:187], v149 offset:2048
	ds_read_b128 v[188:191], v149 offset:3072
	s_add_u32 s22, s20, 0xfff00080
	s_addc_u32 s23, s21, -1
	s_cmp_eq_u32 s61, 60
	s_cselect_b32 s25, s54, s23
	s_cselect_b32 s24, s55, s22
	s_cselect_b32 s23, s7, s60
	s_cselect_b32 s22, s56, s57
	ds_read_b128 v[192:195], v150
	ds_read_b128 v[202:205], v150 offset:1024
	ds_read_b128 v[206:209], v150 offset:2048
	ds_read_b128 v[210:213], v150 offset:3072
	ds_read_b128 v[214:217], v150 offset:4096
	ds_read_b128 v[218:221], v150 offset:5120
	ds_read_b128 v[222:225], v150 offset:6144
	ds_read_b128 v[226:229], v150 offset:7168
	s_waitcnt vmcnt(8)
	s_waitcnt lgkmcnt(0)
	s_barrier
	s_setprio 1
	s_waitcnt lgkmcnt(0)
	v_mfma_f32_16x16x32_bf16 v[126:129], v[142:145], v[192:195], v[126:129]
	v_mfma_f32_16x16x32_bf16 v[126:129], v[154:157], v[202:205], v[126:129]
	v_mfma_f32_16x16x32_bf16 v[118:121], v[168:171], v[202:205], v[118:121]
	v_mfma_f32_16x16x32_bf16 v[118:121], v[158:161], v[192:195], v[118:121]
	v_mfma_f32_16x16x32_bf16 v[122:125], v[176:179], v[192:195], v[122:125]
	v_mfma_f32_16x16x32_bf16 v[122:125], v[180:183], v[202:205], v[122:125]
	v_mfma_f32_16x16x32_bf16 v[114:117], v[188:191], v[202:205], v[114:117]
	v_mfma_f32_16x16x32_bf16 v[114:117], v[184:187], v[192:195], v[114:117]
	v_mfma_f32_16x16x32_bf16 v[98:101], v[184:187], v[206:209], v[98:101]
	v_mfma_f32_16x16x32_bf16 v[98:101], v[188:191], v[210:213], v[98:101]
	v_mfma_f32_16x16x32_bf16 v[106:109], v[180:183], v[210:213], v[106:109]
	v_mfma_f32_16x16x32_bf16 v[106:109], v[176:179], v[206:209], v[106:109]
	v_mfma_f32_16x16x32_bf16 v[102:105], v[158:161], v[206:209], v[102:105]
	v_mfma_f32_16x16x32_bf16 v[102:105], v[168:171], v[210:213], v[102:105]
	v_mfma_f32_16x16x32_bf16 v[110:113], v[154:157], v[210:213], v[110:113]
	v_mfma_f32_16x16x32_bf16 v[110:113], v[142:145], v[206:209], v[110:113]
	v_mfma_f32_16x16x32_bf16 v[94:97], v[142:145], v[214:217], v[94:97]
	v_mfma_f32_16x16x32_bf16 v[94:97], v[154:157], v[218:221], v[94:97]
	v_mfma_f32_16x16x32_bf16 v[86:89], v[168:171], v[218:221], v[86:89]
	v_mfma_f32_16x16x32_bf16 v[86:89], v[158:161], v[214:217], v[86:89]
	v_mfma_f32_16x16x32_bf16 v[90:93], v[176:179], v[214:217], v[90:93]
	v_mfma_f32_16x16x32_bf16 v[90:93], v[180:183], v[218:221], v[90:93]
	v_mfma_f32_16x16x32_bf16 v[82:85], v[188:191], v[218:221], v[82:85]
	v_mfma_f32_16x16x32_bf16 v[82:85], v[184:187], v[214:217], v[82:85]
	v_mfma_f32_16x16x32_bf16 v[66:69], v[184:187], v[222:225], v[66:69]
	v_mfma_f32_16x16x32_bf16 v[66:69], v[188:191], v[226:229], v[66:69]
	v_mfma_f32_16x16x32_bf16 v[74:77], v[180:183], v[226:229], v[74:77]
	v_mfma_f32_16x16x32_bf16 v[74:77], v[176:179], v[222:225], v[74:77]
	v_mfma_f32_16x16x32_bf16 v[70:73], v[158:161], v[222:225], v[70:73]
	v_mfma_f32_16x16x32_bf16 v[70:73], v[168:171], v[226:229], v[70:73]
	v_mfma_f32_16x16x32_bf16 v[78:81], v[154:157], v[226:229], v[78:81]
	v_mfma_f32_16x16x32_bf16 v[78:81], v[142:145], v[222:225], v[78:81]
	s_setprio 0
	s_barrier
	s_mov_b32 m0, s44
	s_add_u32 s62, s22, 0x100000
	global_load_lds_dwordx4 v132, s[22:23]
	s_mov_b32 m0, s45
	s_addc_u32 s63, s23, 0
	global_load_lds_dwordx4 v136, s[22:23]
	s_mov_b32 m0, s46
	ds_read_b128 v[192:195], v150 offset:16384
	global_load_lds_dwordx4 v132, s[62:63]
	s_mov_b32 m0, s47
	ds_read_b128 v[202:205], v150 offset:17408
	global_load_lds_dwordx4 v136, s[62:63]
	ds_read_b128 v[206:209], v150 offset:18432
	ds_read_b128 v[210:213], v150 offset:19456
	ds_read_b128 v[214:217], v150 offset:20480
	ds_read_b128 v[218:221], v150 offset:21504
	ds_read_b128 v[222:225], v150 offset:22528
	ds_read_b128 v[226:229], v150 offset:23552
	s_waitcnt vmcnt(6)
	s_waitcnt lgkmcnt(0)
	s_barrier
	s_setprio 1
	s_waitcnt lgkmcnt(0)
	v_mfma_f32_16x16x32_bf16 v[62:65], v[142:145], v[192:195], v[62:65]
	v_mfma_f32_16x16x32_bf16 v[62:65], v[154:157], v[202:205], v[62:65]
	v_mfma_f32_16x16x32_bf16 v[54:57], v[168:171], v[202:205], v[54:57]
	v_mfma_f32_16x16x32_bf16 v[54:57], v[158:161], v[192:195], v[54:57]
	v_mfma_f32_16x16x32_bf16 v[58:61], v[176:179], v[192:195], v[58:61]
	v_mfma_f32_16x16x32_bf16 v[58:61], v[180:183], v[202:205], v[58:61]
	v_mfma_f32_16x16x32_bf16 v[50:53], v[188:191], v[202:205], v[50:53]
	v_mfma_f32_16x16x32_bf16 v[50:53], v[184:187], v[192:195], v[50:53]
	v_mfma_f32_16x16x32_bf16 v[34:37], v[184:187], v[206:209], v[34:37]
	v_mfma_f32_16x16x32_bf16 v[34:37], v[188:191], v[210:213], v[34:37]
	v_mfma_f32_16x16x32_bf16 v[42:45], v[180:183], v[210:213], v[42:45]
	v_mfma_f32_16x16x32_bf16 v[42:45], v[176:179], v[206:209], v[42:45]
	v_mfma_f32_16x16x32_bf16 v[38:41], v[158:161], v[206:209], v[38:41]
	v_mfma_f32_16x16x32_bf16 v[38:41], v[168:171], v[210:213], v[38:41]
	v_mfma_f32_16x16x32_bf16 v[46:49], v[154:157], v[210:213], v[46:49]
	v_mfma_f32_16x16x32_bf16 v[46:49], v[142:145], v[206:209], v[46:49]
	v_mfma_f32_16x16x32_bf16 v[30:33], v[142:145], v[214:217], v[30:33]
	v_mfma_f32_16x16x32_bf16 v[30:33], v[154:157], v[218:221], v[30:33]
	v_mfma_f32_16x16x32_bf16 v[22:25], v[168:171], v[218:221], v[22:25]
	v_mfma_f32_16x16x32_bf16 v[22:25], v[158:161], v[214:217], v[22:25]
	v_mfma_f32_16x16x32_bf16 v[26:29], v[176:179], v[214:217], v[26:29]
	v_mfma_f32_16x16x32_bf16 v[26:29], v[180:183], v[218:221], v[26:29]
	v_mfma_f32_16x16x32_bf16 v[18:21], v[188:191], v[218:221], v[18:21]
	v_mfma_f32_16x16x32_bf16 v[18:21], v[184:187], v[214:217], v[18:21]
	v_mfma_f32_16x16x32_bf16 v[2:5], v[184:187], v[222:225], v[2:5]
	v_mfma_f32_16x16x32_bf16 v[2:5], v[188:191], v[226:229], v[2:5]
	v_mfma_f32_16x16x32_bf16 v[10:13], v[180:183], v[226:229], v[10:13]
	v_mfma_f32_16x16x32_bf16 v[10:13], v[176:179], v[222:225], v[10:13]
	v_mfma_f32_16x16x32_bf16 v[6:9], v[158:161], v[222:225], v[6:9]
	v_mfma_f32_16x16x32_bf16 v[6:9], v[168:171], v[226:229], v[6:9]
	v_mfma_f32_16x16x32_bf16 v[14:17], v[154:157], v[226:229], v[14:17]
	v_mfma_f32_16x16x32_bf16 v[14:17], v[142:145], v[222:225], v[14:17]
	s_setprio 0
	s_barrier
	s_mov_b32 m0, s31
	ds_read_b128 v[142:145], v151
	global_load_lds_dwordx4 v130, s[24:25]
	s_mov_b32 m0, s33
	ds_read_b128 v[154:157], v151 offset:1024
	global_load_lds_dwordx4 v134, s[24:25]
	s_add_u32 s24, s24, 0x100000
	s_addc_u32 s25, s25, 0
	s_mov_b32 m0, s34
	ds_read_b128 v[158:161], v151 offset:2048
	global_load_lds_dwordx4 v130, s[24:25]
	s_mov_b32 m0, s35
	ds_read_b128 v[168:171], v151 offset:3072
	global_load_lds_dwordx4 v134, s[24:25]
	ds_read_b128 v[176:179], v152
	ds_read_b128 v[180:183], v152 offset:1024
	ds_read_b128 v[184:187], v152 offset:2048
	ds_read_b128 v[188:191], v152 offset:3072
	ds_read_b128 v[192:195], v150 offset:32768
	ds_read_b128 v[202:205], v150 offset:33792
	ds_read_b128 v[206:209], v150 offset:34816
	ds_read_b128 v[210:213], v150 offset:35840
	ds_read_b128 v[214:217], v150 offset:36864
	ds_read_b128 v[218:221], v150 offset:37888
	ds_read_b128 v[222:225], v150 offset:38912
	ds_read_b128 v[226:229], v150 offset:39936
	s_waitcnt vmcnt(8)
	s_waitcnt lgkmcnt(0)
	s_barrier
	s_setprio 1
	s_waitcnt lgkmcnt(0)
	v_mfma_f32_16x16x32_bf16 v[126:129], v[142:145], v[192:195], v[126:129]
	v_mfma_f32_16x16x32_bf16 v[126:129], v[154:157], v[202:205], v[126:129]
	v_mfma_f32_16x16x32_bf16 v[118:121], v[168:171], v[202:205], v[118:121]
	v_mfma_f32_16x16x32_bf16 v[118:121], v[158:161], v[192:195], v[118:121]
	v_mfma_f32_16x16x32_bf16 v[122:125], v[176:179], v[192:195], v[122:125]
	v_mfma_f32_16x16x32_bf16 v[122:125], v[180:183], v[202:205], v[122:125]
	v_mfma_f32_16x16x32_bf16 v[114:117], v[188:191], v[202:205], v[114:117]
	v_mfma_f32_16x16x32_bf16 v[114:117], v[184:187], v[192:195], v[114:117]
	v_mfma_f32_16x16x32_bf16 v[98:101], v[184:187], v[206:209], v[98:101]
	v_mfma_f32_16x16x32_bf16 v[98:101], v[188:191], v[210:213], v[98:101]
	v_mfma_f32_16x16x32_bf16 v[106:109], v[180:183], v[210:213], v[106:109]
	v_mfma_f32_16x16x32_bf16 v[106:109], v[176:179], v[206:209], v[106:109]
	v_mfma_f32_16x16x32_bf16 v[102:105], v[158:161], v[206:209], v[102:105]
	v_mfma_f32_16x16x32_bf16 v[102:105], v[168:171], v[210:213], v[102:105]
	v_mfma_f32_16x16x32_bf16 v[110:113], v[154:157], v[210:213], v[110:113]
	v_mfma_f32_16x16x32_bf16 v[110:113], v[142:145], v[206:209], v[110:113]
	v_mfma_f32_16x16x32_bf16 v[94:97], v[142:145], v[214:217], v[94:97]
	v_mfma_f32_16x16x32_bf16 v[94:97], v[154:157], v[218:221], v[94:97]
	v_mfma_f32_16x16x32_bf16 v[86:89], v[168:171], v[218:221], v[86:89]
	v_mfma_f32_16x16x32_bf16 v[86:89], v[158:161], v[214:217], v[86:89]
	v_mfma_f32_16x16x32_bf16 v[90:93], v[176:179], v[214:217], v[90:93]
	v_mfma_f32_16x16x32_bf16 v[90:93], v[180:183], v[218:221], v[90:93]
	v_mfma_f32_16x16x32_bf16 v[82:85], v[188:191], v[218:221], v[82:85]
	v_mfma_f32_16x16x32_bf16 v[82:85], v[184:187], v[214:217], v[82:85]
	v_mfma_f32_16x16x32_bf16 v[66:69], v[184:187], v[222:225], v[66:69]
	v_mfma_f32_16x16x32_bf16 v[66:69], v[188:191], v[226:229], v[66:69]
	v_mfma_f32_16x16x32_bf16 v[74:77], v[180:183], v[226:229], v[74:77]
	v_mfma_f32_16x16x32_bf16 v[74:77], v[176:179], v[222:225], v[74:77]
	v_mfma_f32_16x16x32_bf16 v[70:73], v[158:161], v[222:225], v[70:73]
	v_mfma_f32_16x16x32_bf16 v[70:73], v[168:171], v[226:229], v[70:73]
	v_mfma_f32_16x16x32_bf16 v[78:81], v[154:157], v[226:229], v[78:81]
	v_mfma_f32_16x16x32_bf16 v[78:81], v[142:145], v[222:225], v[78:81]
	s_setprio 0
	s_barrier
	s_mov_b32 m0, s48
	s_add_u32 s22, s22, 0x80
	s_addc_u32 s23, s23, 0
	global_load_lds_dwordx4 v132, s[22:23]
	s_mov_b32 m0, s49
	ds_read_b128 v[192:195], v150 offset:49152
	global_load_lds_dwordx4 v136, s[22:23]
	s_mov_b32 m0, s50
	s_add_u32 s22, s22, 0x100000
	s_addc_u32 s23, s23, 0
	global_load_lds_dwordx4 v132, s[22:23]
	s_mov_b32 m0, s51
	ds_read_b128 v[202:205], v150 offset:50176
	global_load_lds_dwordx4 v136, s[22:23]
	ds_read_b128 v[206:209], v150 offset:51200
	ds_read_b128 v[210:213], v150 offset:52224
	ds_read_b128 v[214:217], v150 offset:53248
	ds_read_b128 v[218:221], v150 offset:54272
	ds_read_b128 v[222:225], v150 offset:55296
	ds_read_b128 v[226:229], v150 offset:56320
	s_waitcnt vmcnt(6)
	s_waitcnt lgkmcnt(0)
	s_barrier
	s_setprio 1
	s_waitcnt lgkmcnt(0)
	v_mfma_f32_16x16x32_bf16 v[62:65], v[142:145], v[192:195], v[62:65]
	v_mfma_f32_16x16x32_bf16 v[62:65], v[154:157], v[202:205], v[62:65]
	v_mfma_f32_16x16x32_bf16 v[54:57], v[168:171], v[202:205], v[54:57]
	v_mfma_f32_16x16x32_bf16 v[54:57], v[158:161], v[192:195], v[54:57]
	v_mfma_f32_16x16x32_bf16 v[58:61], v[176:179], v[192:195], v[58:61]
	v_mfma_f32_16x16x32_bf16 v[58:61], v[180:183], v[202:205], v[58:61]
	v_mfma_f32_16x16x32_bf16 v[50:53], v[188:191], v[202:205], v[50:53]
	v_mfma_f32_16x16x32_bf16 v[50:53], v[184:187], v[192:195], v[50:53]
	v_mfma_f32_16x16x32_bf16 v[34:37], v[184:187], v[206:209], v[34:37]
	v_mfma_f32_16x16x32_bf16 v[34:37], v[188:191], v[210:213], v[34:37]
	v_mfma_f32_16x16x32_bf16 v[42:45], v[180:183], v[210:213], v[42:45]
	v_mfma_f32_16x16x32_bf16 v[42:45], v[176:179], v[206:209], v[42:45]
	v_mfma_f32_16x16x32_bf16 v[38:41], v[158:161], v[206:209], v[38:41]
	v_mfma_f32_16x16x32_bf16 v[38:41], v[168:171], v[210:213], v[38:41]
	v_mfma_f32_16x16x32_bf16 v[46:49], v[154:157], v[210:213], v[46:49]
	v_mfma_f32_16x16x32_bf16 v[46:49], v[142:145], v[206:209], v[46:49]
	v_mfma_f32_16x16x32_bf16 v[30:33], v[142:145], v[214:217], v[30:33]
	v_mfma_f32_16x16x32_bf16 v[30:33], v[154:157], v[218:221], v[30:33]
	v_mfma_f32_16x16x32_bf16 v[22:25], v[168:171], v[218:221], v[22:25]
	v_mfma_f32_16x16x32_bf16 v[22:25], v[158:161], v[214:217], v[22:25]
	v_mfma_f32_16x16x32_bf16 v[26:29], v[176:179], v[214:217], v[26:29]
	v_mfma_f32_16x16x32_bf16 v[26:29], v[180:183], v[218:221], v[26:29]
	v_mfma_f32_16x16x32_bf16 v[18:21], v[188:191], v[218:221], v[18:21]
	v_mfma_f32_16x16x32_bf16 v[18:21], v[184:187], v[214:217], v[18:21]
	v_mfma_f32_16x16x32_bf16 v[2:5], v[184:187], v[222:225], v[2:5]
	v_mfma_f32_16x16x32_bf16 v[2:5], v[188:191], v[226:229], v[2:5]
	v_mfma_f32_16x16x32_bf16 v[10:13], v[180:183], v[226:229], v[10:13]
	v_mfma_f32_16x16x32_bf16 v[10:13], v[176:179], v[222:225], v[10:13]
	v_mfma_f32_16x16x32_bf16 v[6:9], v[158:161], v[222:225], v[6:9]
	v_mfma_f32_16x16x32_bf16 v[6:9], v[168:171], v[226:229], v[6:9]
	v_mfma_f32_16x16x32_bf16 v[14:17], v[154:157], v[226:229], v[14:17]
	v_mfma_f32_16x16x32_bf16 v[14:17], v[142:145], v[222:225], v[14:17]
	s_setprio 0
	s_barrier
	s_add_i32 s61, s61, 2
	s_add_u32 s20, s20, 0x100
	s_addc_u32 s21, s21, 0
	s_add_u32 s57, s57, 0x100
	s_addc_u32 s60, s60, 0
	s_cmp_gt_u32 s61, 61
	s_cbranch_scc0 .LBB0_1172
	s_and_b64 vcc, exec, s[16:17]
	s_cbranch_vccz .LBB0_1175
	s_barrier

.LBB0_1418:
	s_add_u32 s56, s22, 0xffd50000
	s_addc_u32 s57, s23, -1
	s_mov_b32 m0, s40
	ds_read_b128 v[142:145], v156
	global_load_lds_dwordx4 v130, s[56:57]
	s_mov_b32 m0, s41
	ds_read_b128 v[168:171], v156 offset:1024
	global_load_lds_dwordx4 v134, s[56:57]
	s_mov_b32 m0, s42
	ds_read_b128 v[176:179], v156 offset:2048
	global_load_lds_dwordx4 v138, s[22:23]
	s_mov_b32 m0, s43
	ds_read_b128 v[180:183], v156 offset:3072
	global_load_lds_dwordx4 v140, s[22:23]
	ds_read_b128 v[184:187], v157
	ds_read_b128 v[188:191], v157 offset:1024
	ds_read_b128 v[192:195], v157 offset:2048
	ds_read_b128 v[204:207], v157 offset:3072
	s_add_u32 s24, s22, 0xffd50080
	s_addc_u32 s25, s23, -1
	s_cmpk_eq_i32 s55, 0xa8
	s_cselect_b32 s27, s19, s25
	s_cselect_b32 s26, s18, s24
	s_cselect_b32 s25, s17, s54
	s_cselect_b32 s24, s16, s53
	ds_read_b128 v[208:211], v158
	ds_read_b128 v[212:215], v158 offset:1024
	ds_read_b128 v[216:219], v158 offset:2048
	ds_read_b128 v[220:223], v158 offset:3072
	ds_read_b128 v[224:227], v158 offset:4096
	ds_read_b128 v[228:231], v158 offset:5120
	ds_read_b128 v[232:235], v158 offset:6144
	ds_read_b128 v[236:239], v158 offset:7168
	s_waitcnt vmcnt(8)
	s_waitcnt lgkmcnt(0)
	s_barrier
	s_setprio 1
	s_waitcnt lgkmcnt(0)
	v_mfma_f32_16x16x32_bf16 v[126:129], v[142:145], v[208:211], v[126:129]
	v_mfma_f32_16x16x32_bf16 v[126:129], v[168:171], v[212:215], v[126:129]
	v_mfma_f32_16x16x32_bf16 v[122:125], v[180:183], v[212:215], v[122:125]
	v_mfma_f32_16x16x32_bf16 v[122:125], v[176:179], v[208:211], v[122:125]
	v_mfma_f32_16x16x32_bf16 v[118:121], v[184:187], v[208:211], v[118:121]
	v_mfma_f32_16x16x32_bf16 v[118:121], v[188:191], v[212:215], v[118:121]
	v_mfma_f32_16x16x32_bf16 v[114:117], v[204:207], v[212:215], v[114:117]
	v_mfma_f32_16x16x32_bf16 v[114:117], v[192:195], v[208:211], v[114:117]
	v_mfma_f32_16x16x32_bf16 v[98:101], v[192:195], v[216:219], v[98:101]
	v_mfma_f32_16x16x32_bf16 v[98:101], v[204:207], v[220:223], v[98:101]
	v_mfma_f32_16x16x32_bf16 v[102:105], v[188:191], v[220:223], v[102:105]
	v_mfma_f32_16x16x32_bf16 v[102:105], v[184:187], v[216:219], v[102:105]
	v_mfma_f32_16x16x32_bf16 v[106:109], v[176:179], v[216:219], v[106:109]
	v_mfma_f32_16x16x32_bf16 v[106:109], v[180:183], v[220:223], v[106:109]
	v_mfma_f32_16x16x32_bf16 v[110:113], v[168:171], v[220:223], v[110:113]
	v_mfma_f32_16x16x32_bf16 v[110:113], v[142:145], v[216:219], v[110:113]
	v_mfma_f32_16x16x32_bf16 v[94:97], v[142:145], v[224:227], v[94:97]
	v_mfma_f32_16x16x32_bf16 v[94:97], v[168:171], v[228:231], v[94:97]
	v_mfma_f32_16x16x32_bf16 v[90:93], v[180:183], v[228:231], v[90:93]
	v_mfma_f32_16x16x32_bf16 v[90:93], v[176:179], v[224:227], v[90:93]
	v_mfma_f32_16x16x32_bf16 v[86:89], v[184:187], v[224:227], v[86:89]
	v_mfma_f32_16x16x32_bf16 v[86:89], v[188:191], v[228:231], v[86:89]
	v_mfma_f32_16x16x32_bf16 v[82:85], v[204:207], v[228:231], v[82:85]
	v_mfma_f32_16x16x32_bf16 v[82:85], v[192:195], v[224:227], v[82:85]
	v_mfma_f32_16x16x32_bf16 v[66:69], v[192:195], v[232:235], v[66:69]
	v_mfma_f32_16x16x32_bf16 v[66:69], v[204:207], v[236:239], v[66:69]
	v_mfma_f32_16x16x32_bf16 v[70:73], v[188:191], v[236:239], v[70:73]
	v_mfma_f32_16x16x32_bf16 v[70:73], v[184:187], v[232:235], v[70:73]
	v_mfma_f32_16x16x32_bf16 v[74:77], v[176:179], v[232:235], v[74:77]
	v_mfma_f32_16x16x32_bf16 v[74:77], v[180:183], v[236:239], v[74:77]
	v_mfma_f32_16x16x32_bf16 v[78:81], v[168:171], v[236:239], v[78:81]
	v_mfma_f32_16x16x32_bf16 v[78:81], v[142:145], v[232:235], v[78:81]
	s_setprio 0
	s_barrier
	s_mov_b32 m0, s44
	s_add_u32 s56, s24, 0x2b0000
	global_load_lds_dwordx4 v132, s[24:25]
	s_mov_b32 m0, s45
	s_addc_u32 s57, s25, 0
	global_load_lds_dwordx4 v136, s[24:25]
	s_mov_b32 m0, s46
	ds_read_b128 v[208:211], v158 offset:16384
	global_load_lds_dwordx4 v132, s[56:57]
	s_mov_b32 m0, s47
	ds_read_b128 v[212:215], v158 offset:17408
	global_load_lds_dwordx4 v136, s[56:57]
	ds_read_b128 v[216:219], v158 offset:18432
	ds_read_b128 v[220:223], v158 offset:19456
	ds_read_b128 v[224:227], v158 offset:20480
	ds_read_b128 v[228:231], v158 offset:21504
	ds_read_b128 v[232:235], v158 offset:22528
	ds_read_b128 v[236:239], v158 offset:23552
	s_waitcnt vmcnt(6)
	s_waitcnt lgkmcnt(0)
	s_barrier
	s_setprio 1
	s_waitcnt lgkmcnt(0)
	v_mfma_f32_16x16x32_bf16 v[62:65], v[142:145], v[208:211], v[62:65]
	v_mfma_f32_16x16x32_bf16 v[62:65], v[168:171], v[212:215], v[62:65]
	v_mfma_f32_16x16x32_bf16 v[58:61], v[180:183], v[212:215], v[58:61]
	v_mfma_f32_16x16x32_bf16 v[58:61], v[176:179], v[208:211], v[58:61]
	v_mfma_f32_16x16x32_bf16 v[54:57], v[184:187], v[208:211], v[54:57]
	v_mfma_f32_16x16x32_bf16 v[54:57], v[188:191], v[212:215], v[54:57]
	v_mfma_f32_16x16x32_bf16 v[50:53], v[204:207], v[212:215], v[50:53]
	v_mfma_f32_16x16x32_bf16 v[50:53], v[192:195], v[208:211], v[50:53]
	v_mfma_f32_16x16x32_bf16 v[34:37], v[192:195], v[216:219], v[34:37]
	v_mfma_f32_16x16x32_bf16 v[34:37], v[204:207], v[220:223], v[34:37]
	v_mfma_f32_16x16x32_bf16 v[38:41], v[188:191], v[220:223], v[38:41]
	v_mfma_f32_16x16x32_bf16 v[38:41], v[184:187], v[216:219], v[38:41]
	v_mfma_f32_16x16x32_bf16 v[42:45], v[176:179], v[216:219], v[42:45]
	v_mfma_f32_16x16x32_bf16 v[42:45], v[180:183], v[220:223], v[42:45]
	v_mfma_f32_16x16x32_bf16 v[46:49], v[168:171], v[220:223], v[46:49]
	v_mfma_f32_16x16x32_bf16 v[46:49], v[142:145], v[216:219], v[46:49]
	v_mfma_f32_16x16x32_bf16 v[30:33], v[142:145], v[224:227], v[30:33]
	v_mfma_f32_16x16x32_bf16 v[30:33], v[168:171], v[228:231], v[30:33]
	v_mfma_f32_16x16x32_bf16 v[26:29], v[180:183], v[228:231], v[26:29]
	v_mfma_f32_16x16x32_bf16 v[26:29], v[176:179], v[224:227], v[26:29]
	v_mfma_f32_16x16x32_bf16 v[22:25], v[184:187], v[224:227], v[22:25]
	v_mfma_f32_16x16x32_bf16 v[22:25], v[188:191], v[228:231], v[22:25]
	v_mfma_f32_16x16x32_bf16 v[18:21], v[204:207], v[228:231], v[18:21]
	v_mfma_f32_16x16x32_bf16 v[18:21], v[192:195], v[224:227], v[18:21]
	v_mfma_f32_16x16x32_bf16 v[2:5], v[192:195], v[232:235], v[2:5]
	v_mfma_f32_16x16x32_bf16 v[2:5], v[204:207], v[236:239], v[2:5]
	v_mfma_f32_16x16x32_bf16 v[6:9], v[188:191], v[236:239], v[6:9]
	v_mfma_f32_16x16x32_bf16 v[6:9], v[184:187], v[232:235], v[6:9]
	v_mfma_f32_16x16x32_bf16 v[10:13], v[176:179], v[232:235], v[10:13]
	v_mfma_f32_16x16x32_bf16 v[10:13], v[180:183], v[236:239], v[10:13]
	v_mfma_f32_16x16x32_bf16 v[14:17], v[168:171], v[236:239], v[14:17]
	v_mfma_f32_16x16x32_bf16 v[14:17], v[142:145], v[232:235], v[14:17]
	s_setprio 0
	s_barrier
	s_mov_b32 m0, s35
	ds_read_b128 v[142:145], v159
	global_load_lds_dwordx4 v130, s[26:27]
	s_mov_b32 m0, s36
	ds_read_b128 v[168:171], v159 offset:1024
	global_load_lds_dwordx4 v134, s[26:27]
	s_add_u32 s26, s26, 0x2b0000
	s_addc_u32 s27, s27, 0
	s_mov_b32 m0, s37
	ds_read_b128 v[176:179], v159 offset:2048
	global_load_lds_dwordx4 v130, s[26:27]
	s_mov_b32 m0, s38
	ds_read_b128 v[180:183], v159 offset:3072
	global_load_lds_dwordx4 v134, s[26:27]
	ds_read_b128 v[184:187], v160
	ds_read_b128 v[188:191], v160 offset:1024
	ds_read_b128 v[192:195], v160 offset:2048
	ds_read_b128 v[204:207], v160 offset:3072
	ds_read_b128 v[208:211], v158 offset:32768
	ds_read_b128 v[212:215], v158 offset:33792
	ds_read_b128 v[216:219], v158 offset:34816
	ds_read_b128 v[220:223], v158 offset:35840
	ds_read_b128 v[224:227], v158 offset:36864
	ds_read_b128 v[228:231], v158 offset:37888
	ds_read_b128 v[232:235], v158 offset:38912
	ds_read_b128 v[236:239], v158 offset:39936
	s_waitcnt vmcnt(8)
	s_waitcnt lgkmcnt(0)
	s_barrier
	s_setprio 1
	s_waitcnt lgkmcnt(0)
	v_mfma_f32_16x16x32_bf16 v[126:129], v[142:145], v[208:211], v[126:129]
	v_mfma_f32_16x16x32_bf16 v[126:129], v[168:171], v[212:215], v[126:129]
	v_mfma_f32_16x16x32_bf16 v[122:125], v[180:183], v[212:215], v[122:125]
	v_mfma_f32_16x16x32_bf16 v[122:125], v[176:179], v[208:211], v[122:125]
	v_mfma_f32_16x16x32_bf16 v[118:121], v[184:187], v[208:211], v[118:121]
	v_mfma_f32_16x16x32_bf16 v[118:121], v[188:191], v[212:215], v[118:121]
	v_mfma_f32_16x16x32_bf16 v[114:117], v[204:207], v[212:215], v[114:117]
	v_mfma_f32_16x16x32_bf16 v[114:117], v[192:195], v[208:211], v[114:117]
	v_mfma_f32_16x16x32_bf16 v[98:101], v[192:195], v[216:219], v[98:101]
	v_mfma_f32_16x16x32_bf16 v[98:101], v[204:207], v[220:223], v[98:101]
	v_mfma_f32_16x16x32_bf16 v[102:105], v[188:191], v[220:223], v[102:105]
	v_mfma_f32_16x16x32_bf16 v[102:105], v[184:187], v[216:219], v[102:105]
	v_mfma_f32_16x16x32_bf16 v[106:109], v[176:179], v[216:219], v[106:109]
	v_mfma_f32_16x16x32_bf16 v[106:109], v[180:183], v[220:223], v[106:109]
	v_mfma_f32_16x16x32_bf16 v[110:113], v[168:171], v[220:223], v[110:113]
	v_mfma_f32_16x16x32_bf16 v[110:113], v[142:145], v[216:219], v[110:113]
	v_mfma_f32_16x16x32_bf16 v[94:97], v[142:145], v[224:227], v[94:97]
	v_mfma_f32_16x16x32_bf16 v[94:97], v[168:171], v[228:231], v[94:97]
	v_mfma_f32_16x16x32_bf16 v[90:93], v[180:183], v[228:231], v[90:93]
	v_mfma_f32_16x16x32_bf16 v[90:93], v[176:179], v[224:227], v[90:93]
	v_mfma_f32_16x16x32_bf16 v[86:89], v[184:187], v[224:227], v[86:89]
	v_mfma_f32_16x16x32_bf16 v[86:89], v[188:191], v[228:231], v[86:89]
	v_mfma_f32_16x16x32_bf16 v[82:85], v[204:207], v[228:231], v[82:85]
	v_mfma_f32_16x16x32_bf16 v[82:85], v[192:195], v[224:227], v[82:85]
	v_mfma_f32_16x16x32_bf16 v[66:69], v[192:195], v[232:235], v[66:69]
	v_mfma_f32_16x16x32_bf16 v[66:69], v[204:207], v[236:239], v[66:69]
	v_mfma_f32_16x16x32_bf16 v[70:73], v[188:191], v[236:239], v[70:73]
	v_mfma_f32_16x16x32_bf16 v[70:73], v[184:187], v[232:235], v[70:73]
	v_mfma_f32_16x16x32_bf16 v[74:77], v[176:179], v[232:235], v[74:77]
	v_mfma_f32_16x16x32_bf16 v[74:77], v[180:183], v[236:239], v[74:77]
	v_mfma_f32_16x16x32_bf16 v[78:81], v[168:171], v[236:239], v[78:81]
	v_mfma_f32_16x16x32_bf16 v[78:81], v[142:145], v[232:235], v[78:81]
	s_setprio 0
	s_barrier
	s_mov_b32 m0, s48
	s_add_u32 s24, s24, 0x80
	s_addc_u32 s25, s25, 0
	global_load_lds_dwordx4 v132, s[24:25]
	s_mov_b32 m0, s49
	ds_read_b128 v[208:211], v158 offset:49152
	global_load_lds_dwordx4 v136, s[24:25]
	s_mov_b32 m0, s50
	s_add_u32 s24, s24, 0x2b0000
	s_addc_u32 s25, s25, 0
	global_load_lds_dwordx4 v132, s[24:25]
	s_add_i32 m0, s50, 0x2000
	ds_read_b128 v[212:215], v158 offset:50176
	global_load_lds_dwordx4 v136, s[24:25]
	ds_read_b128 v[216:219], v158 offset:51200
	ds_read_b128 v[220:223], v158 offset:52224
	ds_read_b128 v[224:227], v158 offset:53248
	ds_read_b128 v[228:231], v158 offset:54272
	ds_read_b128 v[232:235], v158 offset:55296
	ds_read_b128 v[236:239], v158 offset:56320
	s_waitcnt vmcnt(6)
	s_waitcnt lgkmcnt(0)
	s_barrier
	s_setprio 1
	s_waitcnt lgkmcnt(0)
	v_mfma_f32_16x16x32_bf16 v[62:65], v[142:145], v[208:211], v[62:65]
	v_mfma_f32_16x16x32_bf16 v[62:65], v[168:171], v[212:215], v[62:65]
	v_mfma_f32_16x16x32_bf16 v[58:61], v[180:183], v[212:215], v[58:61]
	v_mfma_f32_16x16x32_bf16 v[58:61], v[176:179], v[208:211], v[58:61]
	v_mfma_f32_16x16x32_bf16 v[54:57], v[184:187], v[208:211], v[54:57]
	v_mfma_f32_16x16x32_bf16 v[54:57], v[188:191], v[212:215], v[54:57]
	v_mfma_f32_16x16x32_bf16 v[50:53], v[204:207], v[212:215], v[50:53]
	v_mfma_f32_16x16x32_bf16 v[50:53], v[192:195], v[208:211], v[50:53]
	v_mfma_f32_16x16x32_bf16 v[34:37], v[192:195], v[216:219], v[34:37]
	v_mfma_f32_16x16x32_bf16 v[34:37], v[204:207], v[220:223], v[34:37]
	v_mfma_f32_16x16x32_bf16 v[38:41], v[188:191], v[220:223], v[38:41]
	v_mfma_f32_16x16x32_bf16 v[38:41], v[184:187], v[216:219], v[38:41]
	v_mfma_f32_16x16x32_bf16 v[42:45], v[176:179], v[216:219], v[42:45]
	v_mfma_f32_16x16x32_bf16 v[42:45], v[180:183], v[220:223], v[42:45]
	v_mfma_f32_16x16x32_bf16 v[46:49], v[168:171], v[220:223], v[46:49]
	v_mfma_f32_16x16x32_bf16 v[46:49], v[142:145], v[216:219], v[46:49]
	v_mfma_f32_16x16x32_bf16 v[30:33], v[142:145], v[224:227], v[30:33]
	v_mfma_f32_16x16x32_bf16 v[30:33], v[168:171], v[228:231], v[30:33]
	v_mfma_f32_16x16x32_bf16 v[26:29], v[180:183], v[228:231], v[26:29]
	v_mfma_f32_16x16x32_bf16 v[26:29], v[176:179], v[224:227], v[26:29]
	v_mfma_f32_16x16x32_bf16 v[22:25], v[184:187], v[224:227], v[22:25]
	v_mfma_f32_16x16x32_bf16 v[22:25], v[188:191], v[228:231], v[22:25]
	v_mfma_f32_16x16x32_bf16 v[18:21], v[204:207], v[228:231], v[18:21]
	v_mfma_f32_16x16x32_bf16 v[18:21], v[192:195], v[224:227], v[18:21]
	v_mfma_f32_16x16x32_bf16 v[2:5], v[192:195], v[232:235], v[2:5]
	v_mfma_f32_16x16x32_bf16 v[2:5], v[204:207], v[236:239], v[2:5]
	v_mfma_f32_16x16x32_bf16 v[6:9], v[188:191], v[236:239], v[6:9]
	v_mfma_f32_16x16x32_bf16 v[6:9], v[184:187], v[232:235], v[6:9]
	v_mfma_f32_16x16x32_bf16 v[10:13], v[176:179], v[232:235], v[10:13]
	v_mfma_f32_16x16x32_bf16 v[10:13], v[180:183], v[236:239], v[10:13]
	v_mfma_f32_16x16x32_bf16 v[14:17], v[168:171], v[236:239], v[14:17]
	v_mfma_f32_16x16x32_bf16 v[14:17], v[142:145], v[232:235], v[14:17]
	s_setprio 0
	s_barrier
	s_add_i32 s55, s55, 2
	s_add_u32 s22, s22, 0x100
	s_addc_u32 s23, s23, 0
	s_add_u32 s53, s53, 0x100
	s_addc_u32 s54, s54, 0
	s_cmpk_gt_u32 s55, 0xa9
	s_cbranch_scc0 .LBB0_1418
	s_and_b64 vcc, exec, s[14:15]
	s_cbranch_vccz .LBB0_1421
	s_barrier

.LBB0_1432:
	ds_read_b128 v[150:153], v139
	ds_read_b128 v[154:157], v139 offset:1024
	ds_read_b128 v[158:161], v139 offset:2048
	ds_read_b128 v[168:171], v139 offset:3072
	ds_read_b128 v[176:179], v144
	ds_read_b128 v[180:183], v144 offset:1024
	ds_read_b128 v[184:187], v144 offset:2048
	ds_read_b128 v[188:191], v144 offset:3072
	s_add_i32 s42, s15, 2
	s_add_u32 s14, s12, 0xc2050080
	s_addc_u32 s16, s13, -1
	s_cmp_lg_u32 s30, s15
	s_cselect_b32 s14, s14, 0
	s_cselect_b32 s15, s16, 0
	s_add_u32 s16, s4, s14
	s_addc_u32 s17, s5, s15
	s_add_u32 s14, s8, s14
	s_addc_u32 s15, s9, s15
	s_mov_b32 m0, s31
	v_lshl_add_u64 v[172:173], v[140:141], 0, s[12:13]
	ds_read_b128 v[192:195], v145
	ds_read_b128 v[204:207], v145 offset:1024
	ds_read_b128 v[208:211], v145 offset:2048
	ds_read_b128 v[212:215], v145 offset:3072
	ds_read_b128 v[216:219], v145 offset:4096
	ds_read_b128 v[220:223], v145 offset:5120
	ds_read_b128 v[224:227], v145 offset:6144
	ds_read_b128 v[228:231], v145 offset:7168
	global_load_lds_dwordx4 v[172:173], off
	v_lshl_add_u64 v[172:173], v[142:143], 0, s[12:13]
	s_mov_b32 m0, s33
	s_nop 0
	global_load_lds_dwordx4 v[172:173], off
	s_waitcnt vmcnt(8)
	s_waitcnt lgkmcnt(0)
	s_barrier
	s_setprio 1
	s_waitcnt lgkmcnt(0)
	v_mfma_f32_16x16x32_bf16 v[126:129], v[150:153], v[192:195], v[126:129]
	v_mfma_f32_16x16x32_bf16 v[126:129], v[154:157], v[204:207], v[126:129]
	v_mfma_f32_16x16x32_bf16 v[122:125], v[168:171], v[204:207], v[122:125]
	v_mfma_f32_16x16x32_bf16 v[122:125], v[158:161], v[192:195], v[122:125]
	v_mfma_f32_16x16x32_bf16 v[110:113], v[176:179], v[192:195], v[110:113]
	v_mfma_f32_16x16x32_bf16 v[110:113], v[180:183], v[204:207], v[110:113]
	v_mfma_f32_16x16x32_bf16 v[106:109], v[188:191], v[204:207], v[106:109]
	v_mfma_f32_16x16x32_bf16 v[106:109], v[184:187], v[192:195], v[106:109]
	v_mfma_f32_16x16x32_bf16 v[90:93], v[184:187], v[208:211], v[90:93]
	v_mfma_f32_16x16x32_bf16 v[90:93], v[188:191], v[212:215], v[90:93]
	v_mfma_f32_16x16x32_bf16 v[94:97], v[180:183], v[212:215], v[94:97]
	v_mfma_f32_16x16x32_bf16 v[94:97], v[176:179], v[208:211], v[94:97]
	v_mfma_f32_16x16x32_bf16 v[114:117], v[158:161], v[208:211], v[114:117]
	v_mfma_f32_16x16x32_bf16 v[114:117], v[168:171], v[212:215], v[114:117]
	v_mfma_f32_16x16x32_bf16 v[118:121], v[154:157], v[212:215], v[118:121]
	v_mfma_f32_16x16x32_bf16 v[118:121], v[150:153], v[208:211], v[118:121]
	v_mfma_f32_16x16x32_bf16 v[102:105], v[150:153], v[216:219], v[102:105]
	v_mfma_f32_16x16x32_bf16 v[102:105], v[154:157], v[220:223], v[102:105]
	v_mfma_f32_16x16x32_bf16 v[98:101], v[168:171], v[220:223], v[98:101]
	v_mfma_f32_16x16x32_bf16 v[98:101], v[158:161], v[216:219], v[98:101]
	v_mfma_f32_16x16x32_bf16 v[78:81], v[176:179], v[216:219], v[78:81]
	v_mfma_f32_16x16x32_bf16 v[78:81], v[180:183], v[220:223], v[78:81]
	v_mfma_f32_16x16x32_bf16 v[74:77], v[188:191], v[220:223], v[74:77]
	v_mfma_f32_16x16x32_bf16 v[74:77], v[184:187], v[216:219], v[74:77]
	v_mfma_f32_16x16x32_bf16 v[66:69], v[184:187], v[224:227], v[66:69]
	v_mfma_f32_16x16x32_bf16 v[66:69], v[188:191], v[228:231], v[66:69]
	v_mfma_f32_16x16x32_bf16 v[70:73], v[180:183], v[228:231], v[70:73]
	v_mfma_f32_16x16x32_bf16 v[70:73], v[176:179], v[224:227], v[70:73]
	v_mfma_f32_16x16x32_bf16 v[82:85], v[158:161], v[224:227], v[82:85]
	v_mfma_f32_16x16x32_bf16 v[82:85], v[168:171], v[228:231], v[82:85]
	v_mfma_f32_16x16x32_bf16 v[86:89], v[154:157], v[228:231], v[86:89]
	v_mfma_f32_16x16x32_bf16 v[86:89], v[150:153], v[224:227], v[86:89]
	s_setprio 0
	s_barrier
	s_mov_b32 m0, s34
	v_lshl_add_u64 v[172:173], s[14:15], 0, v[132:133]
	s_add_u32 s44, s14, 0x2b0000
	ds_read_b128 v[192:195], v145 offset:16384
	ds_read_b128 v[204:207], v145 offset:17408
	ds_read_b128 v[208:211], v145 offset:18432
	ds_read_b128 v[212:215], v145 offset:19456
	ds_read_b128 v[216:219], v145 offset:20480
	ds_read_b128 v[220:223], v145 offset:21504
	ds_read_b128 v[224:227], v145 offset:22528
	ds_read_b128 v[228:231], v145 offset:23552
	global_load_lds_dwordx4 v[172:173], off
	v_lshl_add_u64 v[196:197], s[14:15], 0, v[136:137]
	s_mov_b32 m0, s35
	s_addc_u32 s45, s15, 0
	global_load_lds_dwordx4 v[196:197], off
	v_lshl_add_u64 v[232:233], s[44:45], 0, v[132:133]
	s_mov_b32 m0, s36
	v_lshl_add_u64 v[234:235], s[16:17], 0, v[134:135]
	global_load_lds_dwordx4 v[232:233], off
	v_lshl_add_u64 v[232:233], s[44:45], 0, v[136:137]
	s_mov_b32 m0, s37
	s_nop 0
	global_load_lds_dwordx4 v[232:233], off
	v_lshl_add_u64 v[232:233], s[16:17], 0, v[130:131]
	s_mov_b32 m0, s21
	s_nop 0
	global_load_lds_dwordx4 v[232:233], off
	s_mov_b32 m0, s22
	s_nop 0
	global_load_lds_dwordx4 v[234:235], off
	s_waitcnt vmcnt(8)
	s_waitcnt lgkmcnt(0)
	s_barrier
	s_setprio 1
	s_waitcnt lgkmcnt(0)
	v_mfma_f32_16x16x32_bf16 v[62:65], v[150:153], v[192:195], v[62:65]
	v_mfma_f32_16x16x32_bf16 v[62:65], v[154:157], v[204:207], v[62:65]
	v_mfma_f32_16x16x32_bf16 v[58:61], v[168:171], v[204:207], v[58:61]
	v_mfma_f32_16x16x32_bf16 v[58:61], v[158:161], v[192:195], v[58:61]
	v_mfma_f32_16x16x32_bf16 v[46:49], v[176:179], v[192:195], v[46:49]
	v_mfma_f32_16x16x32_bf16 v[46:49], v[180:183], v[204:207], v[46:49]
	v_mfma_f32_16x16x32_bf16 v[42:45], v[188:191], v[204:207], v[42:45]
	v_mfma_f32_16x16x32_bf16 v[42:45], v[184:187], v[192:195], v[42:45]
	v_mfma_f32_16x16x32_bf16 v[26:29], v[184:187], v[208:211], v[26:29]
	v_mfma_f32_16x16x32_bf16 v[26:29], v[188:191], v[212:215], v[26:29]
	v_mfma_f32_16x16x32_bf16 v[30:33], v[180:183], v[212:215], v[30:33]
	v_mfma_f32_16x16x32_bf16 v[30:33], v[176:179], v[208:211], v[30:33]
	v_mfma_f32_16x16x32_bf16 v[50:53], v[158:161], v[208:211], v[50:53]
	v_mfma_f32_16x16x32_bf16 v[50:53], v[168:171], v[212:215], v[50:53]
	v_mfma_f32_16x16x32_bf16 v[54:57], v[154:157], v[212:215], v[54:57]
	v_mfma_f32_16x16x32_bf16 v[54:57], v[150:153], v[208:211], v[54:57]
	v_mfma_f32_16x16x32_bf16 v[38:41], v[150:153], v[216:219], v[38:41]
	v_mfma_f32_16x16x32_bf16 v[38:41], v[154:157], v[220:223], v[38:41]
	v_mfma_f32_16x16x32_bf16 v[34:37], v[168:171], v[220:223], v[34:37]
	v_mfma_f32_16x16x32_bf16 v[34:37], v[158:161], v[216:219], v[34:37]
	v_mfma_f32_16x16x32_bf16 v[14:17], v[176:179], v[216:219], v[14:17]
	v_mfma_f32_16x16x32_bf16 v[14:17], v[180:183], v[220:223], v[14:17]
	v_mfma_f32_16x16x32_bf16 v[10:13], v[188:191], v[220:223], v[10:13]
	v_mfma_f32_16x16x32_bf16 v[10:13], v[184:187], v[216:219], v[10:13]
	v_mfma_f32_16x16x32_bf16 v[2:5], v[184:187], v[224:227], v[2:5]
	v_mfma_f32_16x16x32_bf16 v[2:5], v[188:191], v[228:231], v[2:5]
	v_mfma_f32_16x16x32_bf16 v[6:9], v[180:183], v[228:231], v[6:9]
	v_mfma_f32_16x16x32_bf16 v[6:9], v[176:179], v[224:227], v[6:9]
	v_mfma_f32_16x16x32_bf16 v[18:21], v[158:161], v[224:227], v[18:21]
	v_mfma_f32_16x16x32_bf16 v[18:21], v[168:171], v[228:231], v[18:21]
	v_mfma_f32_16x16x32_bf16 v[22:25], v[154:157], v[228:231], v[22:25]
	v_mfma_f32_16x16x32_bf16 v[22:25], v[150:153], v[224:227], v[22:25]
	s_setprio 0
	s_barrier
	ds_read_b128 v[150:153], v146
	ds_read_b128 v[154:157], v146 offset:1024
	ds_read_b128 v[158:161], v146 offset:2048
	ds_read_b128 v[168:171], v146 offset:3072
	ds_read_b128 v[176:179], v147
	ds_read_b128 v[180:183], v147 offset:1024
	ds_read_b128 v[184:187], v147 offset:2048
	ds_read_b128 v[188:191], v147 offset:3072
	s_add_u32 s16, s16, 0x2b0000
	s_addc_u32 s17, s17, 0
	s_mov_b32 m0, s23
	v_lshl_add_u64 v[236:237], s[16:17], 0, v[130:131]
	ds_read_b128 v[192:195], v145 offset:32768
	ds_read_b128 v[204:207], v145 offset:33792
	ds_read_b128 v[208:211], v145 offset:34816
	ds_read_b128 v[212:215], v145 offset:35840
	ds_read_b128 v[216:219], v145 offset:36864
	ds_read_b128 v[220:223], v145 offset:37888
	ds_read_b128 v[224:227], v145 offset:38912
	ds_read_b128 v[228:231], v145 offset:39936
	global_load_lds_dwordx4 v[236:237], off
	v_lshl_add_u64 v[236:237], s[16:17], 0, v[134:135]
	s_mov_b32 m0, s24
	s_nop 0
	global_load_lds_dwordx4 v[236:237], off
	s_waitcnt vmcnt(8)
	s_waitcnt lgkmcnt(0)
	s_barrier
	s_setprio 1
	s_waitcnt lgkmcnt(0)
	v_mfma_f32_16x16x32_bf16 v[126:129], v[150:153], v[192:195], v[126:129]
	v_mfma_f32_16x16x32_bf16 v[126:129], v[154:157], v[204:207], v[126:129]
	v_mfma_f32_16x16x32_bf16 v[122:125], v[168:171], v[204:207], v[122:125]
	v_mfma_f32_16x16x32_bf16 v[122:125], v[158:161], v[192:195], v[122:125]
	v_mfma_f32_16x16x32_bf16 v[110:113], v[176:179], v[192:195], v[110:113]
	v_mfma_f32_16x16x32_bf16 v[110:113], v[180:183], v[204:207], v[110:113]
	v_mfma_f32_16x16x32_bf16 v[106:109], v[188:191], v[204:207], v[106:109]
	v_mfma_f32_16x16x32_bf16 v[106:109], v[184:187], v[192:195], v[106:109]
	v_mfma_f32_16x16x32_bf16 v[90:93], v[184:187], v[208:211], v[90:93]
	v_mfma_f32_16x16x32_bf16 v[90:93], v[188:191], v[212:215], v[90:93]
	v_mfma_f32_16x16x32_bf16 v[94:97], v[180:183], v[212:215], v[94:97]
	v_mfma_f32_16x16x32_bf16 v[94:97], v[176:179], v[208:211], v[94:97]
	v_mfma_f32_16x16x32_bf16 v[114:117], v[158:161], v[208:211], v[114:117]
	v_mfma_f32_16x16x32_bf16 v[114:117], v[168:171], v[212:215], v[114:117]
	v_mfma_f32_16x16x32_bf16 v[118:121], v[154:157], v[212:215], v[118:121]
	v_mfma_f32_16x16x32_bf16 v[118:121], v[150:153], v[208:211], v[118:121]
	v_mfma_f32_16x16x32_bf16 v[102:105], v[150:153], v[216:219], v[102:105]
	v_mfma_f32_16x16x32_bf16 v[102:105], v[154:157], v[220:223], v[102:105]
	v_mfma_f32_16x16x32_bf16 v[98:101], v[168:171], v[220:223], v[98:101]
	v_mfma_f32_16x16x32_bf16 v[98:101], v[158:161], v[216:219], v[98:101]
	v_mfma_f32_16x16x32_bf16 v[78:81], v[176:179], v[216:219], v[78:81]
	v_mfma_f32_16x16x32_bf16 v[78:81], v[180:183], v[220:223], v[78:81]
	v_mfma_f32_16x16x32_bf16 v[74:77], v[188:191], v[220:223], v[74:77]
	v_mfma_f32_16x16x32_bf16 v[74:77], v[184:187], v[216:219], v[74:77]
	v_mfma_f32_16x16x32_bf16 v[66:69], v[184:187], v[224:227], v[66:69]
	v_mfma_f32_16x16x32_bf16 v[66:69], v[188:191], v[228:231], v[66:69]
	v_mfma_f32_16x16x32_bf16 v[70:73], v[180:183], v[228:231], v[70:73]
	v_mfma_f32_16x16x32_bf16 v[70:73], v[176:179], v[224:227], v[70:73]
	v_mfma_f32_16x16x32_bf16 v[82:85], v[158:161], v[224:227], v[82:85]
	v_mfma_f32_16x16x32_bf16 v[82:85], v[168:171], v[228:231], v[82:85]
	v_mfma_f32_16x16x32_bf16 v[86:89], v[154:157], v[228:231], v[86:89]
	v_mfma_f32_16x16x32_bf16 v[86:89], v[150:153], v[224:227], v[86:89]
	s_setprio 0
	s_barrier
	s_mov_b32 m0, s38
	v_lshl_add_u64 v[172:173], v[172:173], 0, s[10:11]
	s_add_u32 s14, s14, 0x2b0080
	ds_read_b128 v[192:195], v145 offset:49152
	ds_read_b128 v[204:207], v145 offset:50176
	ds_read_b128 v[208:211], v145 offset:51200
	ds_read_b128 v[212:215], v145 offset:52224
	ds_read_b128 v[216:219], v145 offset:53248
	ds_read_b128 v[220:223], v145 offset:54272
	ds_read_b128 v[224:227], v145 offset:55296
	ds_read_b128 v[228:231], v145 offset:56320
	global_load_lds_dwordx4 v[172:173], off
	v_lshl_add_u64 v[172:173], v[196:197], 0, s[10:11]
	s_mov_b32 m0, s39
	s_addc_u32 s15, s15, 0
	global_load_lds_dwordx4 v[172:173], off
	v_lshl_add_u64 v[172:173], s[14:15], 0, v[132:133]
	s_mov_b32 m0, s40
	s_nop 0
	global_load_lds_dwordx4 v[172:173], off
	v_lshl_add_u64 v[172:173], s[14:15], 0, v[136:137]
	s_mov_b32 m0, s41
	s_nop 0
	global_load_lds_dwordx4 v[172:173], off
	v_lshl_add_u64 v[172:173], v[232:233], 0, s[10:11]
	s_mov_b32 m0, s26
	s_nop 0
	global_load_lds_dwordx4 v[172:173], off
	v_lshl_add_u64 v[172:173], v[234:235], 0, s[10:11]
	s_mov_b32 m0, s27
	s_nop 0
	global_load_lds_dwordx4 v[172:173], off
	s_waitcnt vmcnt(8)
	s_waitcnt lgkmcnt(0)
	s_barrier
	s_setprio 1
	s_waitcnt lgkmcnt(0)
	v_mfma_f32_16x16x32_bf16 v[62:65], v[150:153], v[192:195], v[62:65]
	v_mfma_f32_16x16x32_bf16 v[62:65], v[154:157], v[204:207], v[62:65]
	v_mfma_f32_16x16x32_bf16 v[58:61], v[168:171], v[204:207], v[58:61]
	v_mfma_f32_16x16x32_bf16 v[58:61], v[158:161], v[192:195], v[58:61]
	v_mfma_f32_16x16x32_bf16 v[46:49], v[176:179], v[192:195], v[46:49]
	v_mfma_f32_16x16x32_bf16 v[46:49], v[180:183], v[204:207], v[46:49]
	v_mfma_f32_16x16x32_bf16 v[42:45], v[188:191], v[204:207], v[42:45]
	v_mfma_f32_16x16x32_bf16 v[42:45], v[184:187], v[192:195], v[42:45]
	v_mfma_f32_16x16x32_bf16 v[26:29], v[184:187], v[208:211], v[26:29]
	v_mfma_f32_16x16x32_bf16 v[26:29], v[188:191], v[212:215], v[26:29]
	v_mfma_f32_16x16x32_bf16 v[30:33], v[180:183], v[212:215], v[30:33]
	v_mfma_f32_16x16x32_bf16 v[30:33], v[176:179], v[208:211], v[30:33]
	v_mfma_f32_16x16x32_bf16 v[50:53], v[158:161], v[208:211], v[50:53]
	v_mfma_f32_16x16x32_bf16 v[50:53], v[168:171], v[212:215], v[50:53]
	v_mfma_f32_16x16x32_bf16 v[54:57], v[154:157], v[212:215], v[54:57]
	v_mfma_f32_16x16x32_bf16 v[54:57], v[150:153], v[208:211], v[54:57]
	v_mfma_f32_16x16x32_bf16 v[38:41], v[150:153], v[216:219], v[38:41]
	v_mfma_f32_16x16x32_bf16 v[38:41], v[154:157], v[220:223], v[38:41]
	v_mfma_f32_16x16x32_bf16 v[34:37], v[168:171], v[220:223], v[34:37]
	v_mfma_f32_16x16x32_bf16 v[34:37], v[158:161], v[216:219], v[34:37]
	v_mfma_f32_16x16x32_bf16 v[14:17], v[176:179], v[216:219], v[14:17]
	v_mfma_f32_16x16x32_bf16 v[14:17], v[180:183], v[220:223], v[14:17]
	v_mfma_f32_16x16x32_bf16 v[10:13], v[188:191], v[220:223], v[10:13]
	v_mfma_f32_16x16x32_bf16 v[10:13], v[184:187], v[216:219], v[10:13]
	v_mfma_f32_16x16x32_bf16 v[2:5], v[184:187], v[224:227], v[2:5]
	v_mfma_f32_16x16x32_bf16 v[2:5], v[188:191], v[228:231], v[2:5]
	v_mfma_f32_16x16x32_bf16 v[6:9], v[180:183], v[228:231], v[6:9]
	v_mfma_f32_16x16x32_bf16 v[6:9], v[176:179], v[224:227], v[6:9]
	v_mfma_f32_16x16x32_bf16 v[18:21], v[158:161], v[224:227], v[18:21]
	v_mfma_f32_16x16x32_bf16 v[18:21], v[168:171], v[228:231], v[18:21]
	v_mfma_f32_16x16x32_bf16 v[22:25], v[154:157], v[228:231], v[22:25]
	v_mfma_f32_16x16x32_bf16 v[22:25], v[150:153], v[224:227], v[22:25]
	s_setprio 0
	s_barrier
	s_add_u32 s12, s12, 0x100
	s_addc_u32 s13, s13, 0
	s_cmp_ge_u32 s42, s19
	s_mov_b32 s15, s42
	s_cbranch_scc0 .LBB0_1432
	s_lshl_b32 s4, s18, 21
	v_readlane_b32 s0, v249, 29
	v_lshl_or_b32 v130, s20, 8, v148
	v_mov_b32_e32 v139, 0
	s_add_u32 s4, s0, s4
	v_readlane_b32 s0, v249, 31
	v_or_b32_e32 v130, s25, v130
	v_cvt_pk_bf16_f32 v70, v70, v71
	v_cvt_pk_bf16_f32 v71, v72, v73
	v_cvt_pk_bf16_f32 v72, v66, v67
	v_add_u32_e32 v66, 0x80, v138
	v_mov_b32_e32 v67, v139
	s_addc_u32 s5, s0, 0
	v_ashrrev_i32_e32 v131, 31, v130
	v_lshlrev_b64 v[132:133], 13, v[138:139]
	v_cvt_pk_bf16_f32 v110, v110, v111
	v_cvt_pk_bf16_f32 v111, v112, v113
	v_cvt_pk_bf16_f32 v112, v106, v107
	v_or_b32_e32 v106, 16, v138
	v_mov_b32_e32 v107, v139
	v_lshlrev_b64 v[66:67], 13, v[66:67]
	v_cvt_pk_bf16_f32 v46, v46, v47
	v_cvt_pk_bf16_f32 v47, v48, v49
	v_cvt_pk_bf16_f32 v48, v42, v43
	v_add_u32_e32 v42, 0x90, v138
	v_mov_b32_e32 v43, v139
	v_lshl_add_u64 v[132:133], s[4:5], 0, v[132:133]
	v_lshlrev_b64 v[130:131], 1, v[130:131]
	v_lshlrev_b64 v[106:107], 13, v[106:107]
	v_cvt_pk_bf16_f32 v94, v94, v95
	v_cvt_pk_bf16_f32 v95, v96, v97
	v_cvt_pk_bf16_f32 v96, v90, v91
	v_or_b32_e32 v90, 32, v138
	v_mov_b32_e32 v91, v139
	v_lshl_add_u64 v[66:67], s[4:5], 0, v[66:67]
	v_lshlrev_b64 v[42:43], 13, v[42:43]
	v_cvt_pk_bf16_f32 v30, v30, v31
	v_cvt_pk_bf16_f32 v31, v32, v33
	v_cvt_pk_bf16_f32 v32, v26, v27
	v_add_u32_e32 v26, 0xa0, v138
	v_mov_b32_e32 v27, v139
	v_lshl_add_u64 v[132:133], v[132:133], 0, v[130:131]
	v_cvt_pk_bf16_f32 v113, v108, v109
	v_lshl_add_u64 v[106:107], s[4:5], 0, v[106:107]
	v_lshlrev_b64 v[90:91], 13, v[90:91]
	v_cvt_pk_bf16_f32 v78, v78, v79
	v_cvt_pk_bf16_f32 v79, v80, v81
	v_cvt_pk_bf16_f32 v80, v74, v75
	v_or_b32_e32 v74, 48, v138
	v_mov_b32_e32 v75, v139
	v_lshl_add_u64 v[66:67], v[66:67], 0, v[130:131]
	v_cvt_pk_bf16_f32 v49, v44, v45
	v_lshl_add_u64 v[42:43], s[4:5], 0, v[42:43]
	v_lshlrev_b64 v[26:27], 13, v[26:27]
	v_add_u32_e32 v138, 0xb0, v138
	global_store_dwordx4 v[132:133], v[110:113], off offset:256
	v_cvt_pk_bf16_f32 v97, v92, v93
	v_lshl_add_u64 v[90:91], s[4:5], 0, v[90:91]
	v_lshl_add_u64 v[110:111], v[106:107], 0, v[130:131]
	v_lshlrev_b64 v[74:75], 13, v[74:75]
	global_store_dwordx4 v[66:67], v[46:49], off offset:256
	v_cvt_pk_bf16_f32 v33, v28, v29
	v_lshl_add_u64 v[26:27], s[4:5], 0, v[26:27]
	v_lshl_add_u64 v[46:47], v[42:43], 0, v[130:131]
	v_cvt_pk_bf16_f32 v14, v14, v15
	v_cvt_pk_bf16_f32 v15, v16, v17
	v_cvt_pk_bf16_f32 v16, v10, v11
	v_lshlrev_b64 v[10:11], 13, v[138:139]
	global_store_dwordx4 v[110:111], v[94:97], off offset:256
	v_cvt_pk_bf16_f32 v81, v76, v77
	v_lshl_add_u64 v[74:75], s[4:5], 0, v[74:75]
	v_lshl_add_u64 v[94:95], v[90:91], 0, v[130:131]
	global_store_dwordx4 v[46:47], v[30:33], off offset:256
	v_cvt_pk_bf16_f32 v17, v12, v13
	v_lshl_add_u64 v[10:11], s[4:5], 0, v[10:11]
	v_lshl_add_u64 v[30:31], v[26:27], 0, v[130:131]
	v_cvt_pk_bf16_f32 v126, v126, v127
	v_cvt_pk_bf16_f32 v127, v128, v129
	v_cvt_pk_bf16_f32 v128, v122, v123
	v_cvt_pk_bf16_f32 v129, v124, v125
	v_cvt_pk_bf16_f32 v106, v118, v119
	v_cvt_pk_bf16_f32 v107, v120, v121
	v_cvt_pk_bf16_f32 v108, v114, v115
	v_cvt_pk_bf16_f32 v109, v116, v117
	v_cvt_pk_bf16_f32 v90, v102, v103
	v_cvt_pk_bf16_f32 v91, v104, v105
	v_cvt_pk_bf16_f32 v92, v98, v99
	v_cvt_pk_bf16_f32 v93, v100, v101
	global_store_dwordx4 v[94:95], v[78:81], off offset:256
	v_cvt_pk_bf16_f32 v76, v82, v83
	v_cvt_pk_bf16_f32 v77, v84, v85
	v_lshl_add_u64 v[78:79], v[74:75], 0, v[130:131]
	v_cvt_pk_bf16_f32 v74, v86, v87
	v_cvt_pk_bf16_f32 v75, v88, v89
	v_cvt_pk_bf16_f32 v73, v68, v69
	v_cvt_pk_bf16_f32 v62, v62, v63
	v_cvt_pk_bf16_f32 v63, v64, v65
	v_cvt_pk_bf16_f32 v64, v58, v59
	v_cvt_pk_bf16_f32 v65, v60, v61
	v_cvt_pk_bf16_f32 v42, v54, v55
	v_cvt_pk_bf16_f32 v43, v56, v57
	v_cvt_pk_bf16_f32 v44, v50, v51
	v_cvt_pk_bf16_f32 v45, v52, v53
	v_cvt_pk_bf16_f32 v26, v38, v39
	v_cvt_pk_bf16_f32 v27, v40, v41
	v_cvt_pk_bf16_f32 v28, v34, v35
	v_cvt_pk_bf16_f32 v29, v36, v37
	global_store_dwordx4 v[30:31], v[14:17], off offset:256
	v_cvt_pk_bf16_f32 v12, v18, v19
	v_cvt_pk_bf16_f32 v13, v20, v21
	v_lshl_add_u64 v[14:15], v[10:11], 0, v[130:131]
	v_cvt_pk_bf16_f32 v10, v22, v23
	v_cvt_pk_bf16_f32 v11, v24, v25
	v_cvt_pk_bf16_f32 v6, v6, v7
	v_cvt_pk_bf16_f32 v7, v8, v9
	v_cvt_pk_bf16_f32 v8, v2, v3
	v_cvt_pk_bf16_f32 v9, v4, v5
	global_store_dwordx4 v[132:133], v[126:129], off
	global_store_dwordx4 v[110:111], v[106:109], off
	global_store_dwordx4 v[94:95], v[90:93], off
	global_store_dwordx4 v[78:79], v[74:77], off
	global_store_dwordx4 v[78:79], v[70:73], off offset:256
	global_store_dwordx4 v[66:67], v[62:65], off
	global_store_dwordx4 v[46:47], v[42:45], off
	global_store_dwordx4 v[30:31], v[26:29], off
	global_store_dwordx4 v[14:15], v[10:13], off
	global_store_dwordx4 v[14:15], v[6:9], off offset:256
	s_waitcnt vmcnt(0)
	s_cmpk_lt_u32 s3, 0x100
	s_cbranch_scc0 .LBB0_1435
	s_barrier

.LBB0_1565:
	ds_read_b128 v[130:133], v204
	ds_read_b128 v[134:137], v204 offset:1024
	ds_read_b128 v[138:141], v204 offset:2048
	ds_read_b128 v[142:145], v204 offset:3072
	ds_read_b128 v[146:149], v205
	ds_read_b128 v[150:153], v205 offset:1024
	ds_read_b128 v[154:157], v205 offset:2048
	ds_read_b128 v[158:161], v205 offset:3072
	s_add_u32 s8, s6, 0xfff00080
	s_addc_u32 s9, s7, -1
	s_cmp_eq_u32 s66, 60
	s_cselect_b32 s73, s41, s9
	s_cselect_b32 s72, s50, s8
	s_cselect_b32 s9, s13, s57
	s_cselect_b32 s8, s51, s56
	v_lshl_add_u64 v[196:197], s[6:7], 0, v[180:181]
	s_add_i32 m0, s42, 0xc000
	ds_read_b128 v[184:187], v206
	ds_read_b128 v[188:191], v206 offset:1024
	ds_read_b128 v[192:195], v206 offset:2048
	ds_read_b128 v[210:213], v206 offset:3072
	ds_read_b128 v[214:217], v206 offset:4096
	ds_read_b128 v[218:221], v206 offset:5120
	ds_read_b128 v[222:225], v206 offset:6144
	ds_read_b128 v[226:229], v206 offset:7168
	global_load_lds_dwordx4 v[196:197], off
	v_lshl_add_u64 v[196:197], s[6:7], 0, v[182:183]
	s_add_i32 m0, s42, 0xe000
	s_nop 0
	global_load_lds_dwordx4 v[196:197], off
	s_waitcnt vmcnt(8)
	s_waitcnt lgkmcnt(0)
	s_barrier
	s_setprio 1
	s_waitcnt lgkmcnt(0)
	v_mfma_f32_16x16x32_bf16 v[126:129], v[130:133], v[184:187], v[126:129]
	v_mfma_f32_16x16x32_bf16 v[126:129], v[134:137], v[188:191], v[126:129]
	v_mfma_f32_16x16x32_bf16 v[122:125], v[142:145], v[188:191], v[122:125]
	v_mfma_f32_16x16x32_bf16 v[122:125], v[138:141], v[184:187], v[122:125]
	v_mfma_f32_16x16x32_bf16 v[118:121], v[146:149], v[184:187], v[118:121]
	v_mfma_f32_16x16x32_bf16 v[118:121], v[150:153], v[188:191], v[118:121]
	v_mfma_f32_16x16x32_bf16 v[114:117], v[158:161], v[188:191], v[114:117]
	v_mfma_f32_16x16x32_bf16 v[114:117], v[154:157], v[184:187], v[114:117]
	v_mfma_f32_16x16x32_bf16 v[98:101], v[154:157], v[192:195], v[98:101]
	v_mfma_f32_16x16x32_bf16 v[98:101], v[158:161], v[210:213], v[98:101]
	v_mfma_f32_16x16x32_bf16 v[102:105], v[150:153], v[210:213], v[102:105]
	v_mfma_f32_16x16x32_bf16 v[102:105], v[146:149], v[192:195], v[102:105]
	v_mfma_f32_16x16x32_bf16 v[106:109], v[138:141], v[192:195], v[106:109]
	v_mfma_f32_16x16x32_bf16 v[106:109], v[142:145], v[210:213], v[106:109]
	v_mfma_f32_16x16x32_bf16 v[110:113], v[134:137], v[210:213], v[110:113]
	v_mfma_f32_16x16x32_bf16 v[110:113], v[130:133], v[192:195], v[110:113]
	v_mfma_f32_16x16x32_bf16 v[94:97], v[130:133], v[214:217], v[94:97]
	v_mfma_f32_16x16x32_bf16 v[94:97], v[134:137], v[218:221], v[94:97]
	v_mfma_f32_16x16x32_bf16 v[90:93], v[142:145], v[218:221], v[90:93]
	v_mfma_f32_16x16x32_bf16 v[90:93], v[138:141], v[214:217], v[90:93]
	v_mfma_f32_16x16x32_bf16 v[86:89], v[146:149], v[214:217], v[86:89]
	v_mfma_f32_16x16x32_bf16 v[86:89], v[150:153], v[218:221], v[86:89]
	v_mfma_f32_16x16x32_bf16 v[82:85], v[158:161], v[218:221], v[82:85]
	v_mfma_f32_16x16x32_bf16 v[82:85], v[154:157], v[214:217], v[82:85]
	v_mfma_f32_16x16x32_bf16 v[66:69], v[154:157], v[222:225], v[66:69]
	v_mfma_f32_16x16x32_bf16 v[66:69], v[158:161], v[226:229], v[66:69]
	v_mfma_f32_16x16x32_bf16 v[70:73], v[150:153], v[226:229], v[70:73]
	v_mfma_f32_16x16x32_bf16 v[70:73], v[146:149], v[222:225], v[70:73]
	v_mfma_f32_16x16x32_bf16 v[74:77], v[138:141], v[222:225], v[74:77]
	v_mfma_f32_16x16x32_bf16 v[74:77], v[142:145], v[226:229], v[74:77]
	v_mfma_f32_16x16x32_bf16 v[78:81], v[134:137], v[226:229], v[78:81]
	v_mfma_f32_16x16x32_bf16 v[78:81], v[130:133], v[222:225], v[78:81]
	s_setprio 0
	s_barrier
	s_add_i32 s67, s54, s35
	v_lshl_add_u64 v[196:197], s[8:9], 0, v[168:169]
	s_mov_b32 m0, s67
	ds_read_b128 v[184:187], v206 offset:16384
	ds_read_b128 v[188:191], v206 offset:17408
	ds_read_b128 v[192:195], v206 offset:18432
	ds_read_b128 v[210:213], v206 offset:19456
	ds_read_b128 v[214:217], v206 offset:20480
	ds_read_b128 v[218:221], v206 offset:21504
	ds_read_b128 v[222:225], v206 offset:22528
	ds_read_b128 v[226:229], v206 offset:23552
	global_load_lds_dwordx4 v[196:197], off
	s_add_i32 m0, s67, 0x2000
	s_add_u32 s68, s8, 0x100000
	v_lshl_add_u64 v[230:231], s[8:9], 0, v[170:171]
	s_addc_u32 s69, s9, 0
	s_add_i32 s67, s55, s35
	global_load_lds_dwordx4 v[230:231], off
	v_lshl_add_u64 v[232:233], s[68:69], 0, v[168:169]
	s_mov_b32 m0, s67
	v_lshl_add_u64 v[234:235], s[72:73], 0, v[170:171]
	global_load_lds_dwordx4 v[232:233], off
	v_lshl_add_u64 v[232:233], s[68:69], 0, v[170:171]
	s_add_i32 m0, s67, 0x2000
	s_nop 0
	global_load_lds_dwordx4 v[232:233], off
	v_lshl_add_u64 v[232:233], s[72:73], 0, v[168:169]
	s_mov_b32 m0, s42
	s_nop 0
	global_load_lds_dwordx4 v[232:233], off
	s_mov_b32 m0, s43
	s_nop 0
	global_load_lds_dwordx4 v[234:235], off
	s_waitcnt vmcnt(8)
	s_waitcnt lgkmcnt(0)
	s_barrier
	s_setprio 1
	s_waitcnt lgkmcnt(0)
	v_mfma_f32_16x16x32_bf16 v[62:65], v[130:133], v[184:187], v[62:65]
	v_mfma_f32_16x16x32_bf16 v[62:65], v[134:137], v[188:191], v[62:65]
	v_mfma_f32_16x16x32_bf16 v[58:61], v[142:145], v[188:191], v[58:61]
	v_mfma_f32_16x16x32_bf16 v[58:61], v[138:141], v[184:187], v[58:61]
	v_mfma_f32_16x16x32_bf16 v[54:57], v[146:149], v[184:187], v[54:57]
	v_mfma_f32_16x16x32_bf16 v[54:57], v[150:153], v[188:191], v[54:57]
	v_mfma_f32_16x16x32_bf16 v[50:53], v[158:161], v[188:191], v[50:53]
	v_mfma_f32_16x16x32_bf16 v[50:53], v[154:157], v[184:187], v[50:53]
	v_mfma_f32_16x16x32_bf16 v[34:37], v[154:157], v[192:195], v[34:37]
	v_mfma_f32_16x16x32_bf16 v[34:37], v[158:161], v[210:213], v[34:37]
	v_mfma_f32_16x16x32_bf16 v[38:41], v[150:153], v[210:213], v[38:41]
	v_mfma_f32_16x16x32_bf16 v[38:41], v[146:149], v[192:195], v[38:41]
	v_mfma_f32_16x16x32_bf16 v[42:45], v[138:141], v[192:195], v[42:45]
	v_mfma_f32_16x16x32_bf16 v[42:45], v[142:145], v[210:213], v[42:45]
	v_mfma_f32_16x16x32_bf16 v[46:49], v[134:137], v[210:213], v[46:49]
	v_mfma_f32_16x16x32_bf16 v[46:49], v[130:133], v[192:195], v[46:49]
	v_mfma_f32_16x16x32_bf16 v[30:33], v[130:133], v[214:217], v[30:33]
	v_mfma_f32_16x16x32_bf16 v[30:33], v[134:137], v[218:221], v[30:33]
	v_mfma_f32_16x16x32_bf16 v[26:29], v[142:145], v[218:221], v[26:29]
	v_mfma_f32_16x16x32_bf16 v[26:29], v[138:141], v[214:217], v[26:29]
	v_mfma_f32_16x16x32_bf16 v[22:25], v[146:149], v[214:217], v[22:25]
	v_mfma_f32_16x16x32_bf16 v[22:25], v[150:153], v[218:221], v[22:25]
	v_mfma_f32_16x16x32_bf16 v[18:21], v[158:161], v[218:221], v[18:21]
	v_mfma_f32_16x16x32_bf16 v[18:21], v[154:157], v[214:217], v[18:21]
	v_mfma_f32_16x16x32_bf16 v[2:5], v[154:157], v[222:225], v[2:5]
	v_mfma_f32_16x16x32_bf16 v[2:5], v[158:161], v[226:229], v[2:5]
	v_mfma_f32_16x16x32_bf16 v[6:9], v[150:153], v[226:229], v[6:9]
	v_mfma_f32_16x16x32_bf16 v[6:9], v[146:149], v[222:225], v[6:9]
	v_mfma_f32_16x16x32_bf16 v[10:13], v[138:141], v[222:225], v[10:13]
	v_mfma_f32_16x16x32_bf16 v[10:13], v[142:145], v[226:229], v[10:13]
	v_mfma_f32_16x16x32_bf16 v[14:17], v[134:137], v[226:229], v[14:17]
	v_mfma_f32_16x16x32_bf16 v[14:17], v[130:133], v[222:225], v[14:17]
	s_setprio 0
	s_barrier
	s_add_i32 s67, 0, 0x18000
	s_add_i32 s70, 0, 0x1c000
	v_add_u32_e32 v142, s67, v203
	v_add_u32_e32 v158, s70, v203
	ds_read_b128 v[130:133], v142
	ds_read_b128 v[134:137], v142 offset:1024
	ds_read_b128 v[138:141], v142 offset:2048
	ds_read_b128 v[142:145], v142 offset:3072
	ds_read_b128 v[146:149], v158
	ds_read_b128 v[150:153], v158 offset:1024
	ds_read_b128 v[154:157], v158 offset:2048
	ds_read_b128 v[158:161], v158 offset:3072
	s_add_u32 s68, s72, 0x100000
	s_addc_u32 s69, s73, 0
	s_mov_b32 m0, s44
	v_lshl_add_u64 v[236:237], s[68:69], 0, v[168:169]
	ds_read_b128 v[184:187], v206 offset:32768
	ds_read_b128 v[188:191], v206 offset:33792
	ds_read_b128 v[192:195], v206 offset:34816
	ds_read_b128 v[210:213], v206 offset:35840
	ds_read_b128 v[214:217], v206 offset:36864
	ds_read_b128 v[218:221], v206 offset:37888
	ds_read_b128 v[222:225], v206 offset:38912
	ds_read_b128 v[226:229], v206 offset:39936
	global_load_lds_dwordx4 v[236:237], off
	v_lshl_add_u64 v[236:237], s[68:69], 0, v[170:171]
	s_mov_b32 m0, s45
	s_nop 0
	global_load_lds_dwordx4 v[236:237], off
	s_waitcnt vmcnt(8)
	s_waitcnt lgkmcnt(0)
	s_barrier
	s_setprio 1
	s_waitcnt lgkmcnt(0)
	v_mfma_f32_16x16x32_bf16 v[126:129], v[130:133], v[184:187], v[126:129]
	v_mfma_f32_16x16x32_bf16 v[126:129], v[134:137], v[188:191], v[126:129]
	v_mfma_f32_16x16x32_bf16 v[122:125], v[142:145], v[188:191], v[122:125]
	v_mfma_f32_16x16x32_bf16 v[122:125], v[138:141], v[184:187], v[122:125]
	v_mfma_f32_16x16x32_bf16 v[118:121], v[146:149], v[184:187], v[118:121]
	v_mfma_f32_16x16x32_bf16 v[118:121], v[150:153], v[188:191], v[118:121]
	v_mfma_f32_16x16x32_bf16 v[114:117], v[158:161], v[188:191], v[114:117]
	v_mfma_f32_16x16x32_bf16 v[114:117], v[154:157], v[184:187], v[114:117]
	v_mfma_f32_16x16x32_bf16 v[98:101], v[154:157], v[192:195], v[98:101]
	v_mfma_f32_16x16x32_bf16 v[98:101], v[158:161], v[210:213], v[98:101]
	v_mfma_f32_16x16x32_bf16 v[102:105], v[150:153], v[210:213], v[102:105]
	v_mfma_f32_16x16x32_bf16 v[102:105], v[146:149], v[192:195], v[102:105]
	v_mfma_f32_16x16x32_bf16 v[106:109], v[138:141], v[192:195], v[106:109]
	v_mfma_f32_16x16x32_bf16 v[106:109], v[142:145], v[210:213], v[106:109]
	v_mfma_f32_16x16x32_bf16 v[110:113], v[134:137], v[210:213], v[110:113]
	v_mfma_f32_16x16x32_bf16 v[110:113], v[130:133], v[192:195], v[110:113]
	v_mfma_f32_16x16x32_bf16 v[94:97], v[130:133], v[214:217], v[94:97]
	v_mfma_f32_16x16x32_bf16 v[94:97], v[134:137], v[218:221], v[94:97]
	v_mfma_f32_16x16x32_bf16 v[90:93], v[142:145], v[218:221], v[90:93]
	v_mfma_f32_16x16x32_bf16 v[90:93], v[138:141], v[214:217], v[90:93]
	v_mfma_f32_16x16x32_bf16 v[86:89], v[146:149], v[214:217], v[86:89]
	v_mfma_f32_16x16x32_bf16 v[86:89], v[150:153], v[218:221], v[86:89]
	v_mfma_f32_16x16x32_bf16 v[82:85], v[158:161], v[218:221], v[82:85]
	v_mfma_f32_16x16x32_bf16 v[82:85], v[154:157], v[214:217], v[82:85]
	v_mfma_f32_16x16x32_bf16 v[66:69], v[154:157], v[222:225], v[66:69]
	v_mfma_f32_16x16x32_bf16 v[66:69], v[158:161], v[226:229], v[66:69]
	v_mfma_f32_16x16x32_bf16 v[70:73], v[150:153], v[226:229], v[70:73]
	v_mfma_f32_16x16x32_bf16 v[70:73], v[146:149], v[222:225], v[70:73]
	v_mfma_f32_16x16x32_bf16 v[74:77], v[138:141], v[222:225], v[74:77]
	v_mfma_f32_16x16x32_bf16 v[74:77], v[142:145], v[226:229], v[74:77]
	v_mfma_f32_16x16x32_bf16 v[78:81], v[134:137], v[226:229], v[78:81]
	v_mfma_f32_16x16x32_bf16 v[78:81], v[130:133], v[222:225], v[78:81]
	s_setprio 0
	s_barrier
	s_add_i32 s67, s67, s35
	v_lshl_add_u64 v[196:197], v[196:197], 0, s[22:23]
	s_mov_b32 m0, s67
	ds_read_b128 v[184:187], v206 offset:49152
	ds_read_b128 v[188:191], v206 offset:50176
	ds_read_b128 v[192:195], v206 offset:51200
	ds_read_b128 v[210:213], v206 offset:52224
	ds_read_b128 v[214:217], v206 offset:53248
	ds_read_b128 v[218:221], v206 offset:54272
	ds_read_b128 v[222:225], v206 offset:55296
	ds_read_b128 v[226:229], v206 offset:56320
	global_load_lds_dwordx4 v[196:197], off
	s_add_i32 m0, s67, 0x2000
	s_add_u32 s8, s8, 0x100080
	v_lshl_add_u64 v[196:197], v[230:231], 0, s[22:23]
	s_addc_u32 s9, s9, 0
	s_add_i32 s67, s70, s35
	global_load_lds_dwordx4 v[196:197], off
	v_lshl_add_u64 v[196:197], s[8:9], 0, v[168:169]
	s_mov_b32 m0, s67
	s_nop 0
	global_load_lds_dwordx4 v[196:197], off
	v_lshl_add_u64 v[196:197], s[8:9], 0, v[170:171]
	s_add_i32 m0, s67, 0x2000
	s_nop 0
	global_load_lds_dwordx4 v[196:197], off
	v_lshl_add_u64 v[196:197], v[232:233], 0, s[22:23]
	s_mov_b32 m0, s48
	s_nop 0
	global_load_lds_dwordx4 v[196:197], off
	v_lshl_add_u64 v[196:197], v[234:235], 0, s[22:23]
	s_mov_b32 m0, s49
	s_nop 0
	global_load_lds_dwordx4 v[196:197], off
	s_waitcnt vmcnt(8)
	s_waitcnt lgkmcnt(0)
	s_barrier
	s_setprio 1
	s_waitcnt lgkmcnt(0)
	v_mfma_f32_16x16x32_bf16 v[62:65], v[130:133], v[184:187], v[62:65]
	v_mfma_f32_16x16x32_bf16 v[62:65], v[134:137], v[188:191], v[62:65]
	v_mfma_f32_16x16x32_bf16 v[58:61], v[142:145], v[188:191], v[58:61]
	v_mfma_f32_16x16x32_bf16 v[58:61], v[138:141], v[184:187], v[58:61]
	v_mfma_f32_16x16x32_bf16 v[54:57], v[146:149], v[184:187], v[54:57]
	v_mfma_f32_16x16x32_bf16 v[54:57], v[150:153], v[188:191], v[54:57]
	v_mfma_f32_16x16x32_bf16 v[50:53], v[158:161], v[188:191], v[50:53]
	v_mfma_f32_16x16x32_bf16 v[50:53], v[154:157], v[184:187], v[50:53]
	v_mfma_f32_16x16x32_bf16 v[34:37], v[154:157], v[192:195], v[34:37]
	v_mfma_f32_16x16x32_bf16 v[34:37], v[158:161], v[210:213], v[34:37]
	v_mfma_f32_16x16x32_bf16 v[38:41], v[150:153], v[210:213], v[38:41]
	v_mfma_f32_16x16x32_bf16 v[38:41], v[146:149], v[192:195], v[38:41]
	v_mfma_f32_16x16x32_bf16 v[42:45], v[138:141], v[192:195], v[42:45]
	v_mfma_f32_16x16x32_bf16 v[42:45], v[142:145], v[210:213], v[42:45]
	v_mfma_f32_16x16x32_bf16 v[46:49], v[134:137], v[210:213], v[46:49]
	v_mfma_f32_16x16x32_bf16 v[46:49], v[130:133], v[192:195], v[46:49]
	v_mfma_f32_16x16x32_bf16 v[30:33], v[130:133], v[214:217], v[30:33]
	v_mfma_f32_16x16x32_bf16 v[30:33], v[134:137], v[218:221], v[30:33]
	v_mfma_f32_16x16x32_bf16 v[26:29], v[142:145], v[218:221], v[26:29]
	v_mfma_f32_16x16x32_bf16 v[26:29], v[138:141], v[214:217], v[26:29]
	v_mfma_f32_16x16x32_bf16 v[22:25], v[146:149], v[214:217], v[22:25]
	v_mfma_f32_16x16x32_bf16 v[22:25], v[150:153], v[218:221], v[22:25]
	v_mfma_f32_16x16x32_bf16 v[18:21], v[158:161], v[218:221], v[18:21]
	v_mfma_f32_16x16x32_bf16 v[18:21], v[154:157], v[214:217], v[18:21]
	v_mfma_f32_16x16x32_bf16 v[2:5], v[154:157], v[222:225], v[2:5]
	v_mfma_f32_16x16x32_bf16 v[2:5], v[158:161], v[226:229], v[2:5]
	v_mfma_f32_16x16x32_bf16 v[6:9], v[150:153], v[226:229], v[6:9]
	v_mfma_f32_16x16x32_bf16 v[6:9], v[146:149], v[222:225], v[6:9]
	v_mfma_f32_16x16x32_bf16 v[10:13], v[138:141], v[222:225], v[10:13]
	v_mfma_f32_16x16x32_bf16 v[10:13], v[142:145], v[226:229], v[10:13]
	v_mfma_f32_16x16x32_bf16 v[14:17], v[134:137], v[226:229], v[14:17]
	v_mfma_f32_16x16x32_bf16 v[14:17], v[130:133], v[222:225], v[14:17]
	s_setprio 0
	s_barrier
	s_add_i32 s66, s66, 2
	s_add_u32 s6, s6, 0x100
	s_addc_u32 s7, s7, 0
	s_add_u32 s56, s56, 0x100
	s_addc_u32 s57, s57, 0
	s_cmp_gt_u32 s66, 61
	s_cbranch_scc0 .LBB0_1565
	s_and_b64 vcc, exec, s[24:25]
	s_cbranch_vccz .LBB0_1568
	s_barrier

.LBB0_2230:
	ds_read_b128 v[142:145], v154
	ds_read_b128 v[158:161], v154 offset:1024
	ds_read_b128 v[168:171], v154 offset:2048
	ds_read_b128 v[176:179], v154 offset:3072
	ds_read_b128 v[180:183], v155
	ds_read_b128 v[184:187], v155 offset:1024
	ds_read_b128 v[188:191], v155 offset:2048
	ds_read_b128 v[192:195], v155 offset:3072
	s_add_u32 s24, s22, 0xfff00080
	s_addc_u32 s25, s23, -1
	s_cmp_eq_u32 s48, 60
	s_cselect_b32 s27, s19, s25
	s_cselect_b32 s26, s44, s24
	s_cselect_b32 s25, s7, s47
	s_cselect_b32 s24, s45, s46
	s_mov_b32 m0, s40
	v_lshl_add_u64 v[146:147], s[22:23], 0, v[138:139]
	ds_read_b128 v[204:207], v156
	ds_read_b128 v[208:211], v156 offset:1024
	ds_read_b128 v[212:215], v156 offset:2048
	ds_read_b128 v[216:219], v156 offset:3072
	ds_read_b128 v[220:223], v156 offset:4096
	ds_read_b128 v[224:227], v156 offset:5120
	ds_read_b128 v[228:231], v156 offset:6144
	ds_read_b128 v[232:235], v156 offset:7168
	global_load_lds_dwordx4 v[146:147], off
	v_lshl_add_u64 v[146:147], s[22:23], 0, v[140:141]
	s_mov_b32 m0, s41
	s_nop 0
	global_load_lds_dwordx4 v[146:147], off
	s_waitcnt vmcnt(8)
	s_waitcnt lgkmcnt(0)
	s_barrier
	s_setprio 1
	s_waitcnt lgkmcnt(0)
	v_mfma_f32_16x16x32_bf16 v[126:129], v[142:145], v[204:207], v[126:129]
	v_mfma_f32_16x16x32_bf16 v[126:129], v[158:161], v[208:211], v[126:129]
	v_mfma_f32_16x16x32_bf16 v[122:125], v[176:179], v[208:211], v[122:125]
	v_mfma_f32_16x16x32_bf16 v[122:125], v[168:171], v[204:207], v[122:125]
	v_mfma_f32_16x16x32_bf16 v[118:121], v[180:183], v[204:207], v[118:121]
	v_mfma_f32_16x16x32_bf16 v[118:121], v[184:187], v[208:211], v[118:121]
	v_mfma_f32_16x16x32_bf16 v[114:117], v[192:195], v[208:211], v[114:117]
	v_mfma_f32_16x16x32_bf16 v[114:117], v[188:191], v[204:207], v[114:117]
	v_mfma_f32_16x16x32_bf16 v[98:101], v[188:191], v[212:215], v[98:101]
	v_mfma_f32_16x16x32_bf16 v[98:101], v[192:195], v[216:219], v[98:101]
	v_mfma_f32_16x16x32_bf16 v[102:105], v[184:187], v[216:219], v[102:105]
	v_mfma_f32_16x16x32_bf16 v[102:105], v[180:183], v[212:215], v[102:105]
	v_mfma_f32_16x16x32_bf16 v[106:109], v[168:171], v[212:215], v[106:109]
	v_mfma_f32_16x16x32_bf16 v[106:109], v[176:179], v[216:219], v[106:109]
	v_mfma_f32_16x16x32_bf16 v[110:113], v[158:161], v[216:219], v[110:113]
	v_mfma_f32_16x16x32_bf16 v[110:113], v[142:145], v[212:215], v[110:113]
	v_mfma_f32_16x16x32_bf16 v[94:97], v[142:145], v[220:223], v[94:97]
	v_mfma_f32_16x16x32_bf16 v[94:97], v[158:161], v[224:227], v[94:97]
	v_mfma_f32_16x16x32_bf16 v[90:93], v[176:179], v[224:227], v[90:93]
	v_mfma_f32_16x16x32_bf16 v[90:93], v[168:171], v[220:223], v[90:93]
	v_mfma_f32_16x16x32_bf16 v[86:89], v[180:183], v[220:223], v[86:89]
	v_mfma_f32_16x16x32_bf16 v[86:89], v[184:187], v[224:227], v[86:89]
	v_mfma_f32_16x16x32_bf16 v[82:85], v[192:195], v[224:227], v[82:85]
	v_mfma_f32_16x16x32_bf16 v[82:85], v[188:191], v[220:223], v[82:85]
	v_mfma_f32_16x16x32_bf16 v[66:69], v[188:191], v[228:231], v[66:69]
	v_mfma_f32_16x16x32_bf16 v[66:69], v[192:195], v[232:235], v[66:69]
	v_mfma_f32_16x16x32_bf16 v[70:73], v[184:187], v[232:235], v[70:73]
	v_mfma_f32_16x16x32_bf16 v[70:73], v[180:183], v[228:231], v[70:73]
	v_mfma_f32_16x16x32_bf16 v[74:77], v[168:171], v[228:231], v[74:77]
	v_mfma_f32_16x16x32_bf16 v[74:77], v[176:179], v[232:235], v[74:77]
	v_mfma_f32_16x16x32_bf16 v[78:81], v[158:161], v[232:235], v[78:81]
	v_mfma_f32_16x16x32_bf16 v[78:81], v[142:145], v[228:231], v[78:81]
	s_setprio 0
	s_barrier
	s_add_i32 s49, s38, s28
	v_lshl_add_u64 v[146:147], s[24:25], 0, v[132:133]
	s_mov_b32 m0, s49
	ds_read_b128 v[204:207], v156 offset:16384
	ds_read_b128 v[208:211], v156 offset:17408
	ds_read_b128 v[212:215], v156 offset:18432
	ds_read_b128 v[216:219], v156 offset:19456
	ds_read_b128 v[220:223], v156 offset:20480
	ds_read_b128 v[224:227], v156 offset:21504
	ds_read_b128 v[228:231], v156 offset:22528
	ds_read_b128 v[232:235], v156 offset:23552
	global_load_lds_dwordx4 v[146:147], off
	s_add_i32 m0, s49, 0x2000
	s_add_u32 s50, s24, 0x100000
	v_lshl_add_u64 v[172:173], s[24:25], 0, v[136:137]
	s_addc_u32 s51, s25, 0
	s_add_i32 s49, s39, s28
	global_load_lds_dwordx4 v[172:173], off
	v_lshl_add_u64 v[196:197], s[50:51], 0, v[132:133]
	s_mov_b32 m0, s49
	v_lshl_add_u64 v[236:237], s[26:27], 0, v[134:135]
	global_load_lds_dwordx4 v[196:197], off
	v_lshl_add_u64 v[196:197], s[50:51], 0, v[136:137]
	s_add_i32 m0, s49, 0x2000
	s_nop 0
	global_load_lds_dwordx4 v[196:197], off
	v_lshl_add_u64 v[196:197], s[26:27], 0, v[130:131]
	s_mov_b32 m0, s30
	s_nop 0
	global_load_lds_dwordx4 v[196:197], off
	s_mov_b32 m0, s31
	s_nop 0
	global_load_lds_dwordx4 v[236:237], off
	s_waitcnt vmcnt(8)
	s_waitcnt lgkmcnt(0)
	s_barrier
	s_setprio 1
	s_waitcnt lgkmcnt(0)
	v_mfma_f32_16x16x32_bf16 v[62:65], v[142:145], v[204:207], v[62:65]
	v_mfma_f32_16x16x32_bf16 v[62:65], v[158:161], v[208:211], v[62:65]
	v_mfma_f32_16x16x32_bf16 v[58:61], v[176:179], v[208:211], v[58:61]
	v_mfma_f32_16x16x32_bf16 v[58:61], v[168:171], v[204:207], v[58:61]
	v_mfma_f32_16x16x32_bf16 v[54:57], v[180:183], v[204:207], v[54:57]
	v_mfma_f32_16x16x32_bf16 v[54:57], v[184:187], v[208:211], v[54:57]
	v_mfma_f32_16x16x32_bf16 v[50:53], v[192:195], v[208:211], v[50:53]
	v_mfma_f32_16x16x32_bf16 v[50:53], v[188:191], v[204:207], v[50:53]
	v_mfma_f32_16x16x32_bf16 v[34:37], v[188:191], v[212:215], v[34:37]
	v_mfma_f32_16x16x32_bf16 v[34:37], v[192:195], v[216:219], v[34:37]
	v_mfma_f32_16x16x32_bf16 v[38:41], v[184:187], v[216:219], v[38:41]
	v_mfma_f32_16x16x32_bf16 v[38:41], v[180:183], v[212:215], v[38:41]
	v_mfma_f32_16x16x32_bf16 v[42:45], v[168:171], v[212:215], v[42:45]
	v_mfma_f32_16x16x32_bf16 v[42:45], v[176:179], v[216:219], v[42:45]
	v_mfma_f32_16x16x32_bf16 v[46:49], v[158:161], v[216:219], v[46:49]
	v_mfma_f32_16x16x32_bf16 v[46:49], v[142:145], v[212:215], v[46:49]
	v_mfma_f32_16x16x32_bf16 v[30:33], v[142:145], v[220:223], v[30:33]
	v_mfma_f32_16x16x32_bf16 v[30:33], v[158:161], v[224:227], v[30:33]
	v_mfma_f32_16x16x32_bf16 v[26:29], v[176:179], v[224:227], v[26:29]
	v_mfma_f32_16x16x32_bf16 v[26:29], v[168:171], v[220:223], v[26:29]
	v_mfma_f32_16x16x32_bf16 v[22:25], v[180:183], v[220:223], v[22:25]
	v_mfma_f32_16x16x32_bf16 v[22:25], v[184:187], v[224:227], v[22:25]
	v_mfma_f32_16x16x32_bf16 v[18:21], v[192:195], v[224:227], v[18:21]
	v_mfma_f32_16x16x32_bf16 v[18:21], v[188:191], v[220:223], v[18:21]
	v_mfma_f32_16x16x32_bf16 v[2:5], v[188:191], v[228:231], v[2:5]
	v_mfma_f32_16x16x32_bf16 v[2:5], v[192:195], v[232:235], v[2:5]
	v_mfma_f32_16x16x32_bf16 v[6:9], v[184:187], v[232:235], v[6:9]
	v_mfma_f32_16x16x32_bf16 v[6:9], v[180:183], v[228:231], v[6:9]
	v_mfma_f32_16x16x32_bf16 v[10:13], v[168:171], v[228:231], v[10:13]
	v_mfma_f32_16x16x32_bf16 v[10:13], v[176:179], v[232:235], v[10:13]
	v_mfma_f32_16x16x32_bf16 v[14:17], v[158:161], v[232:235], v[14:17]
	v_mfma_f32_16x16x32_bf16 v[14:17], v[142:145], v[228:231], v[14:17]
	s_setprio 0
	s_barrier
	s_add_i32 s49, 0, 0x18000
	v_add_u32_e32 v157, s49, v152
	s_add_i32 s50, 0, 0x1c000
	ds_read_b128 v[142:145], v157
	ds_read_b128 v[158:161], v157 offset:1024
	ds_read_b128 v[168:171], v157 offset:2048
	ds_read_b128 v[176:179], v157 offset:3072
	v_add_u32_e32 v157, s50, v152
	ds_read_b128 v[180:183], v157
	ds_read_b128 v[184:187], v157 offset:1024
	ds_read_b128 v[188:191], v157 offset:2048
	ds_read_b128 v[192:195], v157 offset:3072
	s_add_u32 s26, s26, 0x100000
	s_addc_u32 s27, s27, 0
	s_mov_b32 m0, s33
	v_lshl_add_u64 v[238:239], s[26:27], 0, v[130:131]
	ds_read_b128 v[204:207], v156 offset:32768
	ds_read_b128 v[208:211], v156 offset:33792
	ds_read_b128 v[212:215], v156 offset:34816
	ds_read_b128 v[216:219], v156 offset:35840
	ds_read_b128 v[220:223], v156 offset:36864
	ds_read_b128 v[224:227], v156 offset:37888
	ds_read_b128 v[228:231], v156 offset:38912
	ds_read_b128 v[232:235], v156 offset:39936
	global_load_lds_dwordx4 v[238:239], off
	v_lshl_add_u64 v[238:239], s[26:27], 0, v[134:135]
	s_mov_b32 m0, s34
	s_nop 0
	global_load_lds_dwordx4 v[238:239], off
	s_waitcnt vmcnt(8)
	s_waitcnt lgkmcnt(0)
	s_barrier
	s_setprio 1
	s_waitcnt lgkmcnt(0)
	v_mfma_f32_16x16x32_bf16 v[126:129], v[142:145], v[204:207], v[126:129]
	v_mfma_f32_16x16x32_bf16 v[126:129], v[158:161], v[208:211], v[126:129]
	v_mfma_f32_16x16x32_bf16 v[122:125], v[176:179], v[208:211], v[122:125]
	v_mfma_f32_16x16x32_bf16 v[122:125], v[168:171], v[204:207], v[122:125]
	v_mfma_f32_16x16x32_bf16 v[118:121], v[180:183], v[204:207], v[118:121]
	v_mfma_f32_16x16x32_bf16 v[118:121], v[184:187], v[208:211], v[118:121]
	v_mfma_f32_16x16x32_bf16 v[114:117], v[192:195], v[208:211], v[114:117]
	v_mfma_f32_16x16x32_bf16 v[114:117], v[188:191], v[204:207], v[114:117]
	v_mfma_f32_16x16x32_bf16 v[98:101], v[188:191], v[212:215], v[98:101]
	v_mfma_f32_16x16x32_bf16 v[98:101], v[192:195], v[216:219], v[98:101]
	v_mfma_f32_16x16x32_bf16 v[102:105], v[184:187], v[216:219], v[102:105]
	v_mfma_f32_16x16x32_bf16 v[102:105], v[180:183], v[212:215], v[102:105]
	v_mfma_f32_16x16x32_bf16 v[106:109], v[168:171], v[212:215], v[106:109]
	v_mfma_f32_16x16x32_bf16 v[106:109], v[176:179], v[216:219], v[106:109]
	v_mfma_f32_16x16x32_bf16 v[110:113], v[158:161], v[216:219], v[110:113]
	v_mfma_f32_16x16x32_bf16 v[110:113], v[142:145], v[212:215], v[110:113]
	v_mfma_f32_16x16x32_bf16 v[94:97], v[142:145], v[220:223], v[94:97]
	v_mfma_f32_16x16x32_bf16 v[94:97], v[158:161], v[224:227], v[94:97]
	v_mfma_f32_16x16x32_bf16 v[90:93], v[176:179], v[224:227], v[90:93]
	v_mfma_f32_16x16x32_bf16 v[90:93], v[168:171], v[220:223], v[90:93]
	v_mfma_f32_16x16x32_bf16 v[86:89], v[180:183], v[220:223], v[86:89]
	v_mfma_f32_16x16x32_bf16 v[86:89], v[184:187], v[224:227], v[86:89]
	v_mfma_f32_16x16x32_bf16 v[82:85], v[192:195], v[224:227], v[82:85]
	v_mfma_f32_16x16x32_bf16 v[82:85], v[188:191], v[220:223], v[82:85]
	v_mfma_f32_16x16x32_bf16 v[66:69], v[188:191], v[228:231], v[66:69]
	v_mfma_f32_16x16x32_bf16 v[66:69], v[192:195], v[232:235], v[66:69]
	v_mfma_f32_16x16x32_bf16 v[70:73], v[184:187], v[232:235], v[70:73]
	v_mfma_f32_16x16x32_bf16 v[70:73], v[180:183], v[228:231], v[70:73]
	v_mfma_f32_16x16x32_bf16 v[74:77], v[168:171], v[228:231], v[74:77]
	v_mfma_f32_16x16x32_bf16 v[74:77], v[176:179], v[232:235], v[74:77]
	v_mfma_f32_16x16x32_bf16 v[78:81], v[158:161], v[232:235], v[78:81]
	v_mfma_f32_16x16x32_bf16 v[78:81], v[142:145], v[228:231], v[78:81]
	s_setprio 0
	s_barrier
	s_add_i32 s26, s49, s28
	v_lshl_add_u64 v[146:147], v[146:147], 0, s[14:15]
	s_mov_b32 m0, s26
	ds_read_b128 v[204:207], v156 offset:49152
	ds_read_b128 v[208:211], v156 offset:50176
	ds_read_b128 v[212:215], v156 offset:51200
	ds_read_b128 v[216:219], v156 offset:52224
	ds_read_b128 v[220:223], v156 offset:53248
	ds_read_b128 v[224:227], v156 offset:54272
	ds_read_b128 v[228:231], v156 offset:55296
	ds_read_b128 v[232:235], v156 offset:56320
	global_load_lds_dwordx4 v[146:147], off
	s_add_i32 m0, s26, 0x2000
	s_add_u32 s24, s24, 0x100080
	v_lshl_add_u64 v[146:147], v[172:173], 0, s[14:15]
	s_addc_u32 s25, s25, 0
	s_add_i32 s26, s50, s28
	global_load_lds_dwordx4 v[146:147], off
	v_lshl_add_u64 v[146:147], s[24:25], 0, v[132:133]
	s_mov_b32 m0, s26
	s_nop 0
	global_load_lds_dwordx4 v[146:147], off
	v_lshl_add_u64 v[146:147], s[24:25], 0, v[136:137]
	s_add_i32 m0, s26, 0x2000
	s_nop 0
	global_load_lds_dwordx4 v[146:147], off
	v_lshl_add_u64 v[146:147], v[196:197], 0, s[14:15]
	s_mov_b32 m0, s36
	s_nop 0
	global_load_lds_dwordx4 v[146:147], off
	v_lshl_add_u64 v[146:147], v[236:237], 0, s[14:15]
	s_mov_b32 m0, s37
	s_nop 0
	global_load_lds_dwordx4 v[146:147], off
	s_waitcnt vmcnt(8)
	s_waitcnt lgkmcnt(0)
	s_barrier
	s_setprio 1
	s_waitcnt lgkmcnt(0)
	v_mfma_f32_16x16x32_bf16 v[62:65], v[142:145], v[204:207], v[62:65]
	v_mfma_f32_16x16x32_bf16 v[62:65], v[158:161], v[208:211], v[62:65]
	v_mfma_f32_16x16x32_bf16 v[58:61], v[176:179], v[208:211], v[58:61]
	v_mfma_f32_16x16x32_bf16 v[58:61], v[168:171], v[204:207], v[58:61]
	v_mfma_f32_16x16x32_bf16 v[54:57], v[180:183], v[204:207], v[54:57]
	v_mfma_f32_16x16x32_bf16 v[54:57], v[184:187], v[208:211], v[54:57]
	v_mfma_f32_16x16x32_bf16 v[50:53], v[192:195], v[208:211], v[50:53]
	v_mfma_f32_16x16x32_bf16 v[50:53], v[188:191], v[204:207], v[50:53]
	v_mfma_f32_16x16x32_bf16 v[34:37], v[188:191], v[212:215], v[34:37]
	v_mfma_f32_16x16x32_bf16 v[34:37], v[192:195], v[216:219], v[34:37]
	v_mfma_f32_16x16x32_bf16 v[38:41], v[184:187], v[216:219], v[38:41]
	v_mfma_f32_16x16x32_bf16 v[38:41], v[180:183], v[212:215], v[38:41]
	v_mfma_f32_16x16x32_bf16 v[42:45], v[168:171], v[212:215], v[42:45]
	v_mfma_f32_16x16x32_bf16 v[42:45], v[176:179], v[216:219], v[42:45]
	v_mfma_f32_16x16x32_bf16 v[46:49], v[158:161], v[216:219], v[46:49]
	v_mfma_f32_16x16x32_bf16 v[46:49], v[142:145], v[212:215], v[46:49]
	v_mfma_f32_16x16x32_bf16 v[30:33], v[142:145], v[220:223], v[30:33]
	v_mfma_f32_16x16x32_bf16 v[30:33], v[158:161], v[224:227], v[30:33]
	v_mfma_f32_16x16x32_bf16 v[26:29], v[176:179], v[224:227], v[26:29]
	v_mfma_f32_16x16x32_bf16 v[26:29], v[168:171], v[220:223], v[26:29]
	v_mfma_f32_16x16x32_bf16 v[22:25], v[180:183], v[220:223], v[22:25]
	v_mfma_f32_16x16x32_bf16 v[22:25], v[184:187], v[224:227], v[22:25]
	v_mfma_f32_16x16x32_bf16 v[18:21], v[192:195], v[224:227], v[18:21]
	v_mfma_f32_16x16x32_bf16 v[18:21], v[188:191], v[220:223], v[18:21]
	v_mfma_f32_16x16x32_bf16 v[2:5], v[188:191], v[228:231], v[2:5]
	v_mfma_f32_16x16x32_bf16 v[2:5], v[192:195], v[232:235], v[2:5]
	v_mfma_f32_16x16x32_bf16 v[6:9], v[184:187], v[232:235], v[6:9]
	v_mfma_f32_16x16x32_bf16 v[6:9], v[180:183], v[228:231], v[6:9]
	v_mfma_f32_16x16x32_bf16 v[10:13], v[168:171], v[228:231], v[10:13]
	v_mfma_f32_16x16x32_bf16 v[10:13], v[176:179], v[232:235], v[10:13]
	v_mfma_f32_16x16x32_bf16 v[14:17], v[158:161], v[232:235], v[14:17]
	v_mfma_f32_16x16x32_bf16 v[14:17], v[142:145], v[228:231], v[14:17]
	s_setprio 0
	s_barrier
	s_add_i32 s48, s48, 2
	s_add_u32 s22, s22, 0x100
	s_addc_u32 s23, s23, 0
	s_add_u32 s46, s46, 0x100
	s_addc_u32 s47, s47, 0
	s_cmp_gt_u32 s48, 61
	s_cbranch_scc0 .LBB0_2230
	s_and_b64 vcc, exec, s[16:17]
	s_cbranch_vccz .LBB0_2233
	s_barrier

.LBB0_2240:
	s_add_i32 s20, s24, 0x100
	s_and_b64 s[18:19], s[18:19], exec
	s_cselect_b32 s19, 0, s20
	s_cselect_b32 s18, 0, 0
	s_add_u32 s20, s8, s19
	ds_read_b128 v[144:147], v139
	ds_read_b128 v[150:153], v139 offset:1024
	ds_read_b128 v[154:157], v139 offset:2048
	ds_read_b128 v[158:161], v139 offset:3072
	ds_read_b128 v[168:171], v140
	ds_read_b128 v[176:179], v140 offset:1024
	ds_read_b128 v[180:183], v140 offset:2048
	ds_read_b128 v[184:187], v140 offset:3072
	s_addc_u32 s21, s9, s18
	s_add_u32 s22, s10, s19
	s_addc_u32 s23, s11, s18
	s_add_u32 s28, s12, s24
	s_addc_u32 s29, s13, 0
	s_add_u32 s24, s22, 0x100000
	s_addc_u32 s25, s23, 0
	s_add_u32 s18, s20, 0x100000
	s_addc_u32 s19, s21, 0
	s_add_u32 s26, s22, 0x100080
	s_addc_u32 s27, s23, 0
	v_lshl_add_u64 v[172:173], s[28:29], 0, v[130:131]
	s_mov_b32 m0, s38
	v_lshl_add_u64 v[172:173], v[172:173], 0, s[14:15]
	ds_read_b128 v[188:191], v141
	ds_read_b128 v[192:195], v141 offset:1024
	ds_read_b128 v[204:207], v141 offset:2048
	ds_read_b128 v[208:211], v141 offset:3072
	ds_read_b128 v[212:215], v141 offset:4096
	ds_read_b128 v[216:219], v141 offset:5120
	ds_read_b128 v[220:223], v141 offset:6144
	ds_read_b128 v[224:227], v141 offset:7168
	global_load_lds_dwordx4 v[172:173], off
	v_lshl_add_u64 v[172:173], s[28:29], 0, v[134:135]
	v_lshl_add_u64 v[172:173], v[172:173], 0, s[14:15]
	s_mov_b32 m0, s39
	s_nop 0
	global_load_lds_dwordx4 v[172:173], off
	s_waitcnt vmcnt(8)
	s_waitcnt lgkmcnt(0)
	s_barrier
	s_setprio 1
	s_waitcnt lgkmcnt(0)
	v_mfma_f32_16x16x32_bf16 v[126:129], v[144:147], v[188:191], v[126:129]
	v_mfma_f32_16x16x32_bf16 v[126:129], v[150:153], v[192:195], v[126:129]
	v_mfma_f32_16x16x32_bf16 v[122:125], v[158:161], v[192:195], v[122:125]
	v_mfma_f32_16x16x32_bf16 v[122:125], v[154:157], v[188:191], v[122:125]
	v_mfma_f32_16x16x32_bf16 v[110:113], v[168:171], v[188:191], v[110:113]
	v_mfma_f32_16x16x32_bf16 v[110:113], v[176:179], v[192:195], v[110:113]
	v_mfma_f32_16x16x32_bf16 v[106:109], v[184:187], v[192:195], v[106:109]
	v_mfma_f32_16x16x32_bf16 v[106:109], v[180:183], v[188:191], v[106:109]
	v_mfma_f32_16x16x32_bf16 v[90:93], v[180:183], v[204:207], v[90:93]
	v_mfma_f32_16x16x32_bf16 v[90:93], v[184:187], v[208:211], v[90:93]
	v_mfma_f32_16x16x32_bf16 v[94:97], v[176:179], v[208:211], v[94:97]
	v_mfma_f32_16x16x32_bf16 v[94:97], v[168:171], v[204:207], v[94:97]
	v_mfma_f32_16x16x32_bf16 v[114:117], v[154:157], v[204:207], v[114:117]
	v_mfma_f32_16x16x32_bf16 v[114:117], v[158:161], v[208:211], v[114:117]
	v_mfma_f32_16x16x32_bf16 v[118:121], v[150:153], v[208:211], v[118:121]
	v_mfma_f32_16x16x32_bf16 v[118:121], v[144:147], v[204:207], v[118:121]
	v_mfma_f32_16x16x32_bf16 v[102:105], v[144:147], v[212:215], v[102:105]
	v_mfma_f32_16x16x32_bf16 v[102:105], v[150:153], v[216:219], v[102:105]
	v_mfma_f32_16x16x32_bf16 v[98:101], v[158:161], v[216:219], v[98:101]
	v_mfma_f32_16x16x32_bf16 v[98:101], v[154:157], v[212:215], v[98:101]
	v_mfma_f32_16x16x32_bf16 v[78:81], v[168:171], v[212:215], v[78:81]
	v_mfma_f32_16x16x32_bf16 v[78:81], v[176:179], v[216:219], v[78:81]
	v_mfma_f32_16x16x32_bf16 v[74:77], v[184:187], v[216:219], v[74:77]
	v_mfma_f32_16x16x32_bf16 v[74:77], v[180:183], v[212:215], v[74:77]
	v_mfma_f32_16x16x32_bf16 v[66:69], v[180:183], v[220:223], v[66:69]
	v_mfma_f32_16x16x32_bf16 v[66:69], v[184:187], v[224:227], v[66:69]
	v_mfma_f32_16x16x32_bf16 v[70:73], v[176:179], v[224:227], v[70:73]
	v_mfma_f32_16x16x32_bf16 v[70:73], v[168:171], v[220:223], v[70:73]
	v_mfma_f32_16x16x32_bf16 v[82:85], v[154:157], v[220:223], v[82:85]
	v_mfma_f32_16x16x32_bf16 v[82:85], v[158:161], v[224:227], v[82:85]
	v_mfma_f32_16x16x32_bf16 v[86:89], v[150:153], v[224:227], v[86:89]
	v_mfma_f32_16x16x32_bf16 v[86:89], v[144:147], v[220:223], v[86:89]
	s_setprio 0
	s_barrier
	s_mov_b32 m0, s40
	v_lshl_add_u64 v[172:173], s[22:23], 0, v[132:133]
	ds_read_b128 v[188:191], v141 offset:16384
	ds_read_b128 v[192:195], v141 offset:17408
	ds_read_b128 v[204:207], v141 offset:18432
	ds_read_b128 v[208:211], v141 offset:19456
	ds_read_b128 v[212:215], v141 offset:20480
	ds_read_b128 v[216:219], v141 offset:21504
	ds_read_b128 v[220:223], v141 offset:22528
	ds_read_b128 v[224:227], v141 offset:23552
	global_load_lds_dwordx4 v[172:173], off
	v_lshl_add_u64 v[196:197], s[22:23], 0, v[136:137]
	s_mov_b32 m0, s41
	v_lshl_add_u64 v[228:229], s[24:25], 0, v[132:133]
	global_load_lds_dwordx4 v[196:197], off
	s_mov_b32 m0, s42
	v_lshl_add_u64 v[230:231], s[20:21], 0, v[134:135]
	global_load_lds_dwordx4 v[228:229], off
	v_lshl_add_u64 v[228:229], s[24:25], 0, v[136:137]
	s_mov_b32 m0, s43
	s_nop 0
	global_load_lds_dwordx4 v[228:229], off
	v_lshl_add_u64 v[228:229], s[20:21], 0, v[130:131]
	s_mov_b32 m0, s7
	s_nop 0
	global_load_lds_dwordx4 v[228:229], off
	s_mov_b32 m0, s31
	s_nop 0
	global_load_lds_dwordx4 v[230:231], off
	s_waitcnt vmcnt(8)
	s_waitcnt lgkmcnt(0)
	s_barrier
	s_setprio 1
	s_waitcnt lgkmcnt(0)
	v_mfma_f32_16x16x32_bf16 v[62:65], v[144:147], v[188:191], v[62:65]
	v_mfma_f32_16x16x32_bf16 v[62:65], v[150:153], v[192:195], v[62:65]
	v_mfma_f32_16x16x32_bf16 v[58:61], v[158:161], v[192:195], v[58:61]
	v_mfma_f32_16x16x32_bf16 v[58:61], v[154:157], v[188:191], v[58:61]
	v_mfma_f32_16x16x32_bf16 v[46:49], v[168:171], v[188:191], v[46:49]
	v_mfma_f32_16x16x32_bf16 v[46:49], v[176:179], v[192:195], v[46:49]
	v_mfma_f32_16x16x32_bf16 v[42:45], v[184:187], v[192:195], v[42:45]
	v_mfma_f32_16x16x32_bf16 v[42:45], v[180:183], v[188:191], v[42:45]
	v_mfma_f32_16x16x32_bf16 v[26:29], v[180:183], v[204:207], v[26:29]
	v_mfma_f32_16x16x32_bf16 v[26:29], v[184:187], v[208:211], v[26:29]
	v_mfma_f32_16x16x32_bf16 v[30:33], v[176:179], v[208:211], v[30:33]
	v_mfma_f32_16x16x32_bf16 v[30:33], v[168:171], v[204:207], v[30:33]
	v_mfma_f32_16x16x32_bf16 v[50:53], v[154:157], v[204:207], v[50:53]
	v_mfma_f32_16x16x32_bf16 v[50:53], v[158:161], v[208:211], v[50:53]
	v_mfma_f32_16x16x32_bf16 v[54:57], v[150:153], v[208:211], v[54:57]
	v_mfma_f32_16x16x32_bf16 v[54:57], v[144:147], v[204:207], v[54:57]
	v_mfma_f32_16x16x32_bf16 v[38:41], v[144:147], v[212:215], v[38:41]
	v_mfma_f32_16x16x32_bf16 v[38:41], v[150:153], v[216:219], v[38:41]
	v_mfma_f32_16x16x32_bf16 v[34:37], v[158:161], v[216:219], v[34:37]
	v_mfma_f32_16x16x32_bf16 v[34:37], v[154:157], v[212:215], v[34:37]
	v_mfma_f32_16x16x32_bf16 v[14:17], v[168:171], v[212:215], v[14:17]
	v_mfma_f32_16x16x32_bf16 v[14:17], v[176:179], v[216:219], v[14:17]
	v_mfma_f32_16x16x32_bf16 v[10:13], v[184:187], v[216:219], v[10:13]
	v_mfma_f32_16x16x32_bf16 v[10:13], v[180:183], v[212:215], v[10:13]
	v_mfma_f32_16x16x32_bf16 v[2:5], v[180:183], v[220:223], v[2:5]
	v_mfma_f32_16x16x32_bf16 v[2:5], v[184:187], v[224:227], v[2:5]
	v_mfma_f32_16x16x32_bf16 v[6:9], v[176:179], v[224:227], v[6:9]
	v_mfma_f32_16x16x32_bf16 v[6:9], v[168:171], v[220:223], v[6:9]
	v_mfma_f32_16x16x32_bf16 v[18:21], v[154:157], v[220:223], v[18:21]
	v_mfma_f32_16x16x32_bf16 v[18:21], v[158:161], v[224:227], v[18:21]
	v_mfma_f32_16x16x32_bf16 v[22:25], v[150:153], v[224:227], v[22:25]
	v_mfma_f32_16x16x32_bf16 v[22:25], v[144:147], v[220:223], v[22:25]
	s_setprio 0
	s_barrier
	ds_read_b128 v[144:147], v142
	ds_read_b128 v[150:153], v142 offset:1024
	ds_read_b128 v[154:157], v142 offset:2048
	ds_read_b128 v[158:161], v142 offset:3072
	ds_read_b128 v[168:171], v143
	ds_read_b128 v[176:179], v143 offset:1024
	ds_read_b128 v[180:183], v143 offset:2048
	ds_read_b128 v[184:187], v143 offset:3072
	s_mov_b32 m0, s33
	v_lshl_add_u64 v[232:233], s[18:19], 0, v[130:131]
	ds_read_b128 v[188:191], v141 offset:32768
	ds_read_b128 v[192:195], v141 offset:33792
	ds_read_b128 v[204:207], v141 offset:34816
	ds_read_b128 v[208:211], v141 offset:35840
	ds_read_b128 v[212:215], v141 offset:36864
	ds_read_b128 v[216:219], v141 offset:37888
	ds_read_b128 v[220:223], v141 offset:38912
	ds_read_b128 v[224:227], v141 offset:39936
	global_load_lds_dwordx4 v[232:233], off
	v_lshl_add_u64 v[232:233], s[18:19], 0, v[134:135]
	s_mov_b32 m0, s34
	s_nop 0
	global_load_lds_dwordx4 v[232:233], off
	s_waitcnt vmcnt(8)
	s_waitcnt lgkmcnt(0)
	s_barrier
	s_setprio 1
	s_waitcnt lgkmcnt(0)
	v_mfma_f32_16x16x32_bf16 v[126:129], v[144:147], v[188:191], v[126:129]
	v_mfma_f32_16x16x32_bf16 v[126:129], v[150:153], v[192:195], v[126:129]
	v_mfma_f32_16x16x32_bf16 v[122:125], v[158:161], v[192:195], v[122:125]
	v_mfma_f32_16x16x32_bf16 v[122:125], v[154:157], v[188:191], v[122:125]
	v_mfma_f32_16x16x32_bf16 v[110:113], v[168:171], v[188:191], v[110:113]
	v_mfma_f32_16x16x32_bf16 v[110:113], v[176:179], v[192:195], v[110:113]
	v_mfma_f32_16x16x32_bf16 v[106:109], v[184:187], v[192:195], v[106:109]
	v_mfma_f32_16x16x32_bf16 v[106:109], v[180:183], v[188:191], v[106:109]
	v_mfma_f32_16x16x32_bf16 v[90:93], v[180:183], v[204:207], v[90:93]
	v_mfma_f32_16x16x32_bf16 v[90:93], v[184:187], v[208:211], v[90:93]
	v_mfma_f32_16x16x32_bf16 v[94:97], v[176:179], v[208:211], v[94:97]
	v_mfma_f32_16x16x32_bf16 v[94:97], v[168:171], v[204:207], v[94:97]
	v_mfma_f32_16x16x32_bf16 v[114:117], v[154:157], v[204:207], v[114:117]
	v_mfma_f32_16x16x32_bf16 v[114:117], v[158:161], v[208:211], v[114:117]
	v_mfma_f32_16x16x32_bf16 v[118:121], v[150:153], v[208:211], v[118:121]
	v_mfma_f32_16x16x32_bf16 v[118:121], v[144:147], v[204:207], v[118:121]
	v_mfma_f32_16x16x32_bf16 v[102:105], v[144:147], v[212:215], v[102:105]
	v_mfma_f32_16x16x32_bf16 v[102:105], v[150:153], v[216:219], v[102:105]
	v_mfma_f32_16x16x32_bf16 v[98:101], v[158:161], v[216:219], v[98:101]
	v_mfma_f32_16x16x32_bf16 v[98:101], v[154:157], v[212:215], v[98:101]
	v_mfma_f32_16x16x32_bf16 v[78:81], v[168:171], v[212:215], v[78:81]
	v_mfma_f32_16x16x32_bf16 v[78:81], v[176:179], v[216:219], v[78:81]
	v_mfma_f32_16x16x32_bf16 v[74:77], v[184:187], v[216:219], v[74:77]
	v_mfma_f32_16x16x32_bf16 v[74:77], v[180:183], v[212:215], v[74:77]
	v_mfma_f32_16x16x32_bf16 v[66:69], v[180:183], v[220:223], v[66:69]
	v_mfma_f32_16x16x32_bf16 v[66:69], v[184:187], v[224:227], v[66:69]
	v_mfma_f32_16x16x32_bf16 v[70:73], v[176:179], v[224:227], v[70:73]
	v_mfma_f32_16x16x32_bf16 v[70:73], v[168:171], v[220:223], v[70:73]
	v_mfma_f32_16x16x32_bf16 v[82:85], v[154:157], v[220:223], v[82:85]
	v_mfma_f32_16x16x32_bf16 v[82:85], v[158:161], v[224:227], v[82:85]
	v_mfma_f32_16x16x32_bf16 v[86:89], v[150:153], v[224:227], v[86:89]
	v_mfma_f32_16x16x32_bf16 v[86:89], v[144:147], v[220:223], v[86:89]
	s_setprio 0
	s_barrier
	s_mov_b32 m0, s44
	v_lshl_add_u64 v[172:173], v[172:173], 0, s[14:15]
	ds_read_b128 v[188:191], v141 offset:49152
	ds_read_b128 v[192:195], v141 offset:50176
	ds_read_b128 v[204:207], v141 offset:51200
	ds_read_b128 v[208:211], v141 offset:52224
	ds_read_b128 v[212:215], v141 offset:53248
	ds_read_b128 v[216:219], v141 offset:54272
	ds_read_b128 v[220:223], v141 offset:55296
	ds_read_b128 v[224:227], v141 offset:56320
	global_load_lds_dwordx4 v[172:173], off
	v_lshl_add_u64 v[172:173], v[196:197], 0, s[14:15]
	s_mov_b32 m0, s45
	s_nop 0
	global_load_lds_dwordx4 v[172:173], off
	v_lshl_add_u64 v[172:173], s[26:27], 0, v[132:133]
	s_mov_b32 m0, s46
	s_nop 0
	global_load_lds_dwordx4 v[172:173], off
	v_lshl_add_u64 v[172:173], s[26:27], 0, v[136:137]
	s_mov_b32 m0, s47
	s_nop 0
	global_load_lds_dwordx4 v[172:173], off
	v_lshl_add_u64 v[172:173], v[228:229], 0, s[14:15]
	s_mov_b32 m0, s36
	s_nop 0
	global_load_lds_dwordx4 v[172:173], off
	v_lshl_add_u64 v[172:173], v[230:231], 0, s[14:15]
	s_mov_b32 m0, s37
	s_nop 0
	global_load_lds_dwordx4 v[172:173], off
	s_waitcnt vmcnt(8)
	s_waitcnt lgkmcnt(0)
	s_barrier
	s_setprio 1
	s_waitcnt lgkmcnt(0)
	v_mfma_f32_16x16x32_bf16 v[62:65], v[144:147], v[188:191], v[62:65]
	v_mfma_f32_16x16x32_bf16 v[62:65], v[150:153], v[192:195], v[62:65]
	v_mfma_f32_16x16x32_bf16 v[58:61], v[158:161], v[192:195], v[58:61]
	v_mfma_f32_16x16x32_bf16 v[58:61], v[154:157], v[188:191], v[58:61]
	v_mfma_f32_16x16x32_bf16 v[46:49], v[168:171], v[188:191], v[46:49]
	v_mfma_f32_16x16x32_bf16 v[46:49], v[176:179], v[192:195], v[46:49]
	v_mfma_f32_16x16x32_bf16 v[42:45], v[184:187], v[192:195], v[42:45]
	v_mfma_f32_16x16x32_bf16 v[42:45], v[180:183], v[188:191], v[42:45]
	v_mfma_f32_16x16x32_bf16 v[26:29], v[180:183], v[204:207], v[26:29]
	v_mfma_f32_16x16x32_bf16 v[26:29], v[184:187], v[208:211], v[26:29]
	v_mfma_f32_16x16x32_bf16 v[30:33], v[176:179], v[208:211], v[30:33]
	v_mfma_f32_16x16x32_bf16 v[30:33], v[168:171], v[204:207], v[30:33]
	v_mfma_f32_16x16x32_bf16 v[50:53], v[154:157], v[204:207], v[50:53]
	v_mfma_f32_16x16x32_bf16 v[50:53], v[158:161], v[208:211], v[50:53]
	v_mfma_f32_16x16x32_bf16 v[54:57], v[150:153], v[208:211], v[54:57]
	v_mfma_f32_16x16x32_bf16 v[54:57], v[144:147], v[204:207], v[54:57]
	v_mfma_f32_16x16x32_bf16 v[38:41], v[144:147], v[212:215], v[38:41]
	v_mfma_f32_16x16x32_bf16 v[38:41], v[150:153], v[216:219], v[38:41]
	v_mfma_f32_16x16x32_bf16 v[34:37], v[158:161], v[216:219], v[34:37]
	v_mfma_f32_16x16x32_bf16 v[34:37], v[154:157], v[212:215], v[34:37]
	v_mfma_f32_16x16x32_bf16 v[14:17], v[168:171], v[212:215], v[14:17]
	v_mfma_f32_16x16x32_bf16 v[14:17], v[176:179], v[216:219], v[14:17]
	v_mfma_f32_16x16x32_bf16 v[10:13], v[184:187], v[216:219], v[10:13]
	v_mfma_f32_16x16x32_bf16 v[10:13], v[180:183], v[212:215], v[10:13]
	v_mfma_f32_16x16x32_bf16 v[2:5], v[180:183], v[220:223], v[2:5]
	v_mfma_f32_16x16x32_bf16 v[2:5], v[184:187], v[224:227], v[2:5]
	v_mfma_f32_16x16x32_bf16 v[6:9], v[176:179], v[224:227], v[6:9]
	v_mfma_f32_16x16x32_bf16 v[6:9], v[168:171], v[220:223], v[6:9]
	v_mfma_f32_16x16x32_bf16 v[18:21], v[154:157], v[220:223], v[18:21]
	v_mfma_f32_16x16x32_bf16 v[18:21], v[158:161], v[224:227], v[18:21]
	v_mfma_f32_16x16x32_bf16 v[22:25], v[150:153], v[224:227], v[22:25]
	v_mfma_f32_16x16x32_bf16 v[22:25], v[144:147], v[220:223], v[22:25]
	s_setprio 0
	s_barrier
	s_andn2_b64 vcc, exec, s[16:17]
	s_mov_b64 s[18:19], -1
	s_mov_b64 s[16:17], 0
	s_movk_i32 s24, 0x100
	s_cbranch_vccz .LBB0_2240
	s_lshl_b32 s7, s30, 21
	v_readlane_b32 s0, v249, 29
	v_lshl_or_b32 v130, s6, 8, v148
	v_mov_b32_e32 v139, 0
	s_add_u32 s8, s0, s7
	v_readlane_b32 s0, v249, 31
	v_or_b32_e32 v130, s35, v130
	v_cvt_pk_bf16_f32 v70, v70, v71
	v_cvt_pk_bf16_f32 v71, v72, v73
	v_cvt_pk_bf16_f32 v72, v66, v67
	v_add_u32_e32 v66, 0x80, v138
	v_mov_b32_e32 v67, v139
	s_addc_u32 s9, s0, 0
	v_ashrrev_i32_e32 v131, 31, v130
	v_lshlrev_b64 v[132:133], 13, v[138:139]
	v_cvt_pk_bf16_f32 v110, v110, v111
	v_cvt_pk_bf16_f32 v111, v112, v113
	v_cvt_pk_bf16_f32 v112, v106, v107
	v_or_b32_e32 v106, 16, v138
	v_mov_b32_e32 v107, v139
	v_lshlrev_b64 v[66:67], 13, v[66:67]
	v_cvt_pk_bf16_f32 v46, v46, v47
	v_cvt_pk_bf16_f32 v47, v48, v49
	v_cvt_pk_bf16_f32 v48, v42, v43
	v_add_u32_e32 v42, 0x90, v138
	v_mov_b32_e32 v43, v139
	v_lshl_add_u64 v[132:133], s[8:9], 0, v[132:133]
	v_lshlrev_b64 v[130:131], 1, v[130:131]
	v_lshlrev_b64 v[106:107], 13, v[106:107]
	v_cvt_pk_bf16_f32 v94, v94, v95
	v_cvt_pk_bf16_f32 v95, v96, v97
	v_cvt_pk_bf16_f32 v96, v90, v91
	v_or_b32_e32 v90, 32, v138
	v_mov_b32_e32 v91, v139
	v_lshl_add_u64 v[66:67], s[8:9], 0, v[66:67]
	v_lshlrev_b64 v[42:43], 13, v[42:43]
	v_cvt_pk_bf16_f32 v30, v30, v31
	v_cvt_pk_bf16_f32 v31, v32, v33
	v_cvt_pk_bf16_f32 v32, v26, v27
	v_add_u32_e32 v26, 0xa0, v138
	v_mov_b32_e32 v27, v139
	v_lshl_add_u64 v[132:133], v[132:133], 0, v[130:131]
	v_cvt_pk_bf16_f32 v113, v108, v109
	v_lshl_add_u64 v[106:107], s[8:9], 0, v[106:107]
	v_lshlrev_b64 v[90:91], 13, v[90:91]
	v_cvt_pk_bf16_f32 v78, v78, v79
	v_cvt_pk_bf16_f32 v79, v80, v81
	v_cvt_pk_bf16_f32 v80, v74, v75
	v_or_b32_e32 v74, 48, v138
	v_mov_b32_e32 v75, v139
	v_lshl_add_u64 v[66:67], v[66:67], 0, v[130:131]
	v_cvt_pk_bf16_f32 v49, v44, v45
	v_lshl_add_u64 v[42:43], s[8:9], 0, v[42:43]
	v_lshlrev_b64 v[26:27], 13, v[26:27]
	v_add_u32_e32 v138, 0xb0, v138
	global_store_dwordx4 v[132:133], v[110:113], off offset:256
	v_cvt_pk_bf16_f32 v97, v92, v93
	v_lshl_add_u64 v[90:91], s[8:9], 0, v[90:91]
	v_lshl_add_u64 v[110:111], v[106:107], 0, v[130:131]
	v_lshlrev_b64 v[74:75], 13, v[74:75]
	global_store_dwordx4 v[66:67], v[46:49], off offset:256
	v_cvt_pk_bf16_f32 v33, v28, v29
	v_lshl_add_u64 v[26:27], s[8:9], 0, v[26:27]
	v_lshl_add_u64 v[46:47], v[42:43], 0, v[130:131]
	v_cvt_pk_bf16_f32 v14, v14, v15
	v_cvt_pk_bf16_f32 v15, v16, v17
	v_cvt_pk_bf16_f32 v16, v10, v11
	v_lshlrev_b64 v[10:11], 13, v[138:139]
	global_store_dwordx4 v[110:111], v[94:97], off offset:256
	v_cvt_pk_bf16_f32 v81, v76, v77
	v_lshl_add_u64 v[74:75], s[8:9], 0, v[74:75]
	v_lshl_add_u64 v[94:95], v[90:91], 0, v[130:131]
	global_store_dwordx4 v[46:47], v[30:33], off offset:256
	v_cvt_pk_bf16_f32 v17, v12, v13
	v_lshl_add_u64 v[10:11], s[8:9], 0, v[10:11]
	v_lshl_add_u64 v[30:31], v[26:27], 0, v[130:131]
	v_cvt_pk_bf16_f32 v126, v126, v127
	v_cvt_pk_bf16_f32 v127, v128, v129
	v_cvt_pk_bf16_f32 v128, v122, v123
	v_cvt_pk_bf16_f32 v129, v124, v125
	v_cvt_pk_bf16_f32 v106, v118, v119
	v_cvt_pk_bf16_f32 v107, v120, v121
	v_cvt_pk_bf16_f32 v108, v114, v115
	v_cvt_pk_bf16_f32 v109, v116, v117
	v_cvt_pk_bf16_f32 v90, v102, v103
	v_cvt_pk_bf16_f32 v91, v104, v105
	v_cvt_pk_bf16_f32 v92, v98, v99
	v_cvt_pk_bf16_f32 v93, v100, v101
	global_store_dwordx4 v[94:95], v[78:81], off offset:256
	v_cvt_pk_bf16_f32 v76, v82, v83
	v_cvt_pk_bf16_f32 v77, v84, v85
	v_lshl_add_u64 v[78:79], v[74:75], 0, v[130:131]
	v_cvt_pk_bf16_f32 v74, v86, v87
	v_cvt_pk_bf16_f32 v75, v88, v89
	v_cvt_pk_bf16_f32 v73, v68, v69
	v_cvt_pk_bf16_f32 v62, v62, v63
	v_cvt_pk_bf16_f32 v63, v64, v65
	v_cvt_pk_bf16_f32 v64, v58, v59
	v_cvt_pk_bf16_f32 v65, v60, v61
	v_cvt_pk_bf16_f32 v42, v54, v55
	v_cvt_pk_bf16_f32 v43, v56, v57
	v_cvt_pk_bf16_f32 v44, v50, v51
	v_cvt_pk_bf16_f32 v45, v52, v53
	v_cvt_pk_bf16_f32 v26, v38, v39
	v_cvt_pk_bf16_f32 v27, v40, v41
	v_cvt_pk_bf16_f32 v28, v34, v35
	v_cvt_pk_bf16_f32 v29, v36, v37
	global_store_dwordx4 v[30:31], v[14:17], off offset:256
	v_cvt_pk_bf16_f32 v12, v18, v19
	v_cvt_pk_bf16_f32 v13, v20, v21
	v_lshl_add_u64 v[14:15], v[10:11], 0, v[130:131]
	v_cvt_pk_bf16_f32 v10, v22, v23
	v_cvt_pk_bf16_f32 v11, v24, v25
	v_cvt_pk_bf16_f32 v6, v6, v7
	v_cvt_pk_bf16_f32 v7, v8, v9
	v_cvt_pk_bf16_f32 v8, v2, v3
	v_cvt_pk_bf16_f32 v9, v4, v5
	global_store_dwordx4 v[132:133], v[126:129], off
	global_store_dwordx4 v[110:111], v[106:109], off
	global_store_dwordx4 v[94:95], v[90:93], off
	global_store_dwordx4 v[78:79], v[74:77], off
	global_store_dwordx4 v[78:79], v[70:73], off offset:256
	global_store_dwordx4 v[66:67], v[62:65], off
	global_store_dwordx4 v[46:47], v[42:45], off
	global_store_dwordx4 v[30:31], v[26:29], off
	global_store_dwordx4 v[14:15], v[10:13], off
	global_store_dwordx4 v[14:15], v[6:9], off offset:256
	s_waitcnt vmcnt(0)
	s_cmpk_lt_u32 s3, 0x100
	s_cbranch_scc0 .LBB0_2243
	s_barrier

.LBB0_2373:
	s_add_u32 s60, s20, 0xfff00000
	s_addc_u32 s61, s21, -1
	s_mov_b32 m0, s35
	ds_read_b128 v[142:145], v148
	global_load_lds_dwordx4 v130, s[60:61]
	s_mov_b32 m0, s36
	ds_read_b128 v[154:157], v148 offset:1024
	global_load_lds_dwordx4 v134, s[60:61]
	s_mov_b32 m0, s40
	ds_read_b128 v[158:161], v148 offset:2048
	global_load_lds_dwordx4 v138, s[20:21]
	s_mov_b32 m0, s41
	ds_read_b128 v[168:171], v148 offset:3072
	global_load_lds_dwordx4 v140, s[20:21]
	ds_read_b128 v[176:179], v149
	ds_read_b128 v[180:183], v149 offset:1024
	ds_read_b128 v[184:187], v149 offset:2048
	ds_read_b128 v[188:191], v149 offset:3072
	s_add_u32 s22, s20, 0xfff00080
	s_addc_u32 s23, s21, -1
	s_cmp_eq_u32 s57, 60
	s_cselect_b32 s25, s52, s23
	s_cselect_b32 s24, s53, s22
	s_cselect_b32 s23, s7, s56
	s_cselect_b32 s22, s54, s55
	ds_read_b128 v[192:195], v150
	ds_read_b128 v[204:207], v150 offset:1024
	ds_read_b128 v[208:211], v150 offset:2048
	ds_read_b128 v[212:215], v150 offset:3072
	ds_read_b128 v[216:219], v150 offset:4096
	ds_read_b128 v[220:223], v150 offset:5120
	ds_read_b128 v[224:227], v150 offset:6144
	ds_read_b128 v[228:231], v150 offset:7168
	s_waitcnt vmcnt(8)
	s_waitcnt lgkmcnt(0)
	s_barrier
	s_setprio 1
	s_waitcnt lgkmcnt(0)
	v_mfma_f32_16x16x32_bf16 v[126:129], v[142:145], v[192:195], v[126:129]
	v_mfma_f32_16x16x32_bf16 v[126:129], v[154:157], v[204:207], v[126:129]
	v_mfma_f32_16x16x32_bf16 v[122:125], v[168:171], v[204:207], v[122:125]
	v_mfma_f32_16x16x32_bf16 v[122:125], v[158:161], v[192:195], v[122:125]
	v_mfma_f32_16x16x32_bf16 v[118:121], v[176:179], v[192:195], v[118:121]
	v_mfma_f32_16x16x32_bf16 v[118:121], v[180:183], v[204:207], v[118:121]
	v_mfma_f32_16x16x32_bf16 v[114:117], v[188:191], v[204:207], v[114:117]
	v_mfma_f32_16x16x32_bf16 v[114:117], v[184:187], v[192:195], v[114:117]
	v_mfma_f32_16x16x32_bf16 v[98:101], v[184:187], v[208:211], v[98:101]
	v_mfma_f32_16x16x32_bf16 v[98:101], v[188:191], v[212:215], v[98:101]
	v_mfma_f32_16x16x32_bf16 v[102:105], v[180:183], v[212:215], v[102:105]
	v_mfma_f32_16x16x32_bf16 v[102:105], v[176:179], v[208:211], v[102:105]
	v_mfma_f32_16x16x32_bf16 v[106:109], v[158:161], v[208:211], v[106:109]
	v_mfma_f32_16x16x32_bf16 v[106:109], v[168:171], v[212:215], v[106:109]
	v_mfma_f32_16x16x32_bf16 v[110:113], v[154:157], v[212:215], v[110:113]
	v_mfma_f32_16x16x32_bf16 v[110:113], v[142:145], v[208:211], v[110:113]
	v_mfma_f32_16x16x32_bf16 v[94:97], v[142:145], v[216:219], v[94:97]
	v_mfma_f32_16x16x32_bf16 v[94:97], v[154:157], v[220:223], v[94:97]
	v_mfma_f32_16x16x32_bf16 v[90:93], v[168:171], v[220:223], v[90:93]
	v_mfma_f32_16x16x32_bf16 v[90:93], v[158:161], v[216:219], v[90:93]
	v_mfma_f32_16x16x32_bf16 v[86:89], v[176:179], v[216:219], v[86:89]
	v_mfma_f32_16x16x32_bf16 v[86:89], v[180:183], v[220:223], v[86:89]
	v_mfma_f32_16x16x32_bf16 v[82:85], v[188:191], v[220:223], v[82:85]
	v_mfma_f32_16x16x32_bf16 v[82:85], v[184:187], v[216:219], v[82:85]
	v_mfma_f32_16x16x32_bf16 v[66:69], v[184:187], v[224:227], v[66:69]
	v_mfma_f32_16x16x32_bf16 v[66:69], v[188:191], v[228:231], v[66:69]
	v_mfma_f32_16x16x32_bf16 v[70:73], v[180:183], v[228:231], v[70:73]
	v_mfma_f32_16x16x32_bf16 v[70:73], v[176:179], v[224:227], v[70:73]
	v_mfma_f32_16x16x32_bf16 v[74:77], v[158:161], v[224:227], v[74:77]
	v_mfma_f32_16x16x32_bf16 v[74:77], v[168:171], v[228:231], v[74:77]
	v_mfma_f32_16x16x32_bf16 v[78:81], v[154:157], v[228:231], v[78:81]
	v_mfma_f32_16x16x32_bf16 v[78:81], v[142:145], v[224:227], v[78:81]
	s_setprio 0
	s_barrier
	s_mov_b32 m0, s42
	s_add_u32 s60, s22, 0x100000
	global_load_lds_dwordx4 v132, s[22:23]
	s_mov_b32 m0, s43
	s_addc_u32 s61, s23, 0
	global_load_lds_dwordx4 v136, s[22:23]
	s_mov_b32 m0, s44
	ds_read_b128 v[192:195], v150 offset:16384
	global_load_lds_dwordx4 v132, s[60:61]
	s_mov_b32 m0, s45
	ds_read_b128 v[204:207], v150 offset:17408
	global_load_lds_dwordx4 v136, s[60:61]
	ds_read_b128 v[208:211], v150 offset:18432
	ds_read_b128 v[212:215], v150 offset:19456
	ds_read_b128 v[216:219], v150 offset:20480
	ds_read_b128 v[220:223], v150 offset:21504
	ds_read_b128 v[224:227], v150 offset:22528
	ds_read_b128 v[228:231], v150 offset:23552
	s_waitcnt vmcnt(6)
	s_waitcnt lgkmcnt(0)
	s_barrier
	s_setprio 1
	s_waitcnt lgkmcnt(0)
	v_mfma_f32_16x16x32_bf16 v[62:65], v[142:145], v[192:195], v[62:65]
	v_mfma_f32_16x16x32_bf16 v[62:65], v[154:157], v[204:207], v[62:65]
	v_mfma_f32_16x16x32_bf16 v[58:61], v[168:171], v[204:207], v[58:61]
	v_mfma_f32_16x16x32_bf16 v[58:61], v[158:161], v[192:195], v[58:61]
	v_mfma_f32_16x16x32_bf16 v[54:57], v[176:179], v[192:195], v[54:57]
	v_mfma_f32_16x16x32_bf16 v[54:57], v[180:183], v[204:207], v[54:57]
	v_mfma_f32_16x16x32_bf16 v[50:53], v[188:191], v[204:207], v[50:53]
	v_mfma_f32_16x16x32_bf16 v[50:53], v[184:187], v[192:195], v[50:53]
	v_mfma_f32_16x16x32_bf16 v[34:37], v[184:187], v[208:211], v[34:37]
	v_mfma_f32_16x16x32_bf16 v[34:37], v[188:191], v[212:215], v[34:37]
	v_mfma_f32_16x16x32_bf16 v[38:41], v[180:183], v[212:215], v[38:41]
	v_mfma_f32_16x16x32_bf16 v[38:41], v[176:179], v[208:211], v[38:41]
	v_mfma_f32_16x16x32_bf16 v[42:45], v[158:161], v[208:211], v[42:45]
	v_mfma_f32_16x16x32_bf16 v[42:45], v[168:171], v[212:215], v[42:45]
	v_mfma_f32_16x16x32_bf16 v[46:49], v[154:157], v[212:215], v[46:49]
	v_mfma_f32_16x16x32_bf16 v[46:49], v[142:145], v[208:211], v[46:49]
	v_mfma_f32_16x16x32_bf16 v[30:33], v[142:145], v[216:219], v[30:33]
	v_mfma_f32_16x16x32_bf16 v[30:33], v[154:157], v[220:223], v[30:33]
	v_mfma_f32_16x16x32_bf16 v[26:29], v[168:171], v[220:223], v[26:29]
	v_mfma_f32_16x16x32_bf16 v[26:29], v[158:161], v[216:219], v[26:29]
	v_mfma_f32_16x16x32_bf16 v[22:25], v[176:179], v[216:219], v[22:25]
	v_mfma_f32_16x16x32_bf16 v[22:25], v[180:183], v[220:223], v[22:25]
	v_mfma_f32_16x16x32_bf16 v[18:21], v[188:191], v[220:223], v[18:21]
	v_mfma_f32_16x16x32_bf16 v[18:21], v[184:187], v[216:219], v[18:21]
	v_mfma_f32_16x16x32_bf16 v[2:5], v[184:187], v[224:227], v[2:5]
	v_mfma_f32_16x16x32_bf16 v[2:5], v[188:191], v[228:231], v[2:5]
	v_mfma_f32_16x16x32_bf16 v[6:9], v[180:183], v[228:231], v[6:9]
	v_mfma_f32_16x16x32_bf16 v[6:9], v[176:179], v[224:227], v[6:9]
	v_mfma_f32_16x16x32_bf16 v[10:13], v[158:161], v[224:227], v[10:13]
	v_mfma_f32_16x16x32_bf16 v[10:13], v[168:171], v[228:231], v[10:13]
	v_mfma_f32_16x16x32_bf16 v[14:17], v[154:157], v[228:231], v[14:17]
	v_mfma_f32_16x16x32_bf16 v[14:17], v[142:145], v[224:227], v[14:17]
	s_setprio 0
	s_barrier
	s_mov_b32 m0, s29
	ds_read_b128 v[142:145], v151
	global_load_lds_dwordx4 v130, s[24:25]
	s_mov_b32 m0, s30
	ds_read_b128 v[154:157], v151 offset:1024
	global_load_lds_dwordx4 v134, s[24:25]
	s_add_u32 s24, s24, 0x100000
	s_addc_u32 s25, s25, 0
	s_mov_b32 m0, s31
	ds_read_b128 v[158:161], v151 offset:2048
	global_load_lds_dwordx4 v130, s[24:25]
	s_mov_b32 m0, s33
	ds_read_b128 v[168:171], v151 offset:3072
	global_load_lds_dwordx4 v134, s[24:25]
	ds_read_b128 v[176:179], v152
	ds_read_b128 v[180:183], v152 offset:1024
	ds_read_b128 v[184:187], v152 offset:2048
	ds_read_b128 v[188:191], v152 offset:3072
	ds_read_b128 v[192:195], v150 offset:32768
	ds_read_b128 v[204:207], v150 offset:33792
	ds_read_b128 v[208:211], v150 offset:34816
	ds_read_b128 v[212:215], v150 offset:35840
	ds_read_b128 v[216:219], v150 offset:36864
	ds_read_b128 v[220:223], v150 offset:37888
	ds_read_b128 v[224:227], v150 offset:38912
	ds_read_b128 v[228:231], v150 offset:39936
	s_waitcnt vmcnt(8)
	s_waitcnt lgkmcnt(0)
	s_barrier
	s_setprio 1
	s_waitcnt lgkmcnt(0)
	v_mfma_f32_16x16x32_bf16 v[126:129], v[142:145], v[192:195], v[126:129]
	v_mfma_f32_16x16x32_bf16 v[126:129], v[154:157], v[204:207], v[126:129]
	v_mfma_f32_16x16x32_bf16 v[122:125], v[168:171], v[204:207], v[122:125]
	v_mfma_f32_16x16x32_bf16 v[122:125], v[158:161], v[192:195], v[122:125]
	v_mfma_f32_16x16x32_bf16 v[118:121], v[176:179], v[192:195], v[118:121]
	v_mfma_f32_16x16x32_bf16 v[118:121], v[180:183], v[204:207], v[118:121]
	v_mfma_f32_16x16x32_bf16 v[114:117], v[188:191], v[204:207], v[114:117]
	v_mfma_f32_16x16x32_bf16 v[114:117], v[184:187], v[192:195], v[114:117]
	v_mfma_f32_16x16x32_bf16 v[98:101], v[184:187], v[208:211], v[98:101]
	v_mfma_f32_16x16x32_bf16 v[98:101], v[188:191], v[212:215], v[98:101]
	v_mfma_f32_16x16x32_bf16 v[102:105], v[180:183], v[212:215], v[102:105]
	v_mfma_f32_16x16x32_bf16 v[102:105], v[176:179], v[208:211], v[102:105]
	v_mfma_f32_16x16x32_bf16 v[106:109], v[158:161], v[208:211], v[106:109]
	v_mfma_f32_16x16x32_bf16 v[106:109], v[168:171], v[212:215], v[106:109]
	v_mfma_f32_16x16x32_bf16 v[110:113], v[154:157], v[212:215], v[110:113]
	v_mfma_f32_16x16x32_bf16 v[110:113], v[142:145], v[208:211], v[110:113]
	v_mfma_f32_16x16x32_bf16 v[94:97], v[142:145], v[216:219], v[94:97]
	v_mfma_f32_16x16x32_bf16 v[94:97], v[154:157], v[220:223], v[94:97]
	v_mfma_f32_16x16x32_bf16 v[90:93], v[168:171], v[220:223], v[90:93]
	v_mfma_f32_16x16x32_bf16 v[90:93], v[158:161], v[216:219], v[90:93]
	v_mfma_f32_16x16x32_bf16 v[86:89], v[176:179], v[216:219], v[86:89]
	v_mfma_f32_16x16x32_bf16 v[86:89], v[180:183], v[220:223], v[86:89]
	v_mfma_f32_16x16x32_bf16 v[82:85], v[188:191], v[220:223], v[82:85]
	v_mfma_f32_16x16x32_bf16 v[82:85], v[184:187], v[216:219], v[82:85]
	v_mfma_f32_16x16x32_bf16 v[66:69], v[184:187], v[224:227], v[66:69]
	v_mfma_f32_16x16x32_bf16 v[66:69], v[188:191], v[228:231], v[66:69]
	v_mfma_f32_16x16x32_bf16 v[70:73], v[180:183], v[228:231], v[70:73]
	v_mfma_f32_16x16x32_bf16 v[70:73], v[176:179], v[224:227], v[70:73]
	v_mfma_f32_16x16x32_bf16 v[74:77], v[158:161], v[224:227], v[74:77]
	v_mfma_f32_16x16x32_bf16 v[74:77], v[168:171], v[228:231], v[74:77]
	v_mfma_f32_16x16x32_bf16 v[78:81], v[154:157], v[228:231], v[78:81]
	v_mfma_f32_16x16x32_bf16 v[78:81], v[142:145], v[224:227], v[78:81]
	s_setprio 0
	s_barrier
	s_mov_b32 m0, s46
	s_add_u32 s22, s22, 0x80
	s_addc_u32 s23, s23, 0
	global_load_lds_dwordx4 v132, s[22:23]
	s_mov_b32 m0, s47
	ds_read_b128 v[192:195], v150 offset:49152
	global_load_lds_dwordx4 v136, s[22:23]
	s_mov_b32 m0, s48
	s_add_u32 s22, s22, 0x100000
	s_addc_u32 s23, s23, 0
	global_load_lds_dwordx4 v132, s[22:23]
	s_mov_b32 m0, s49
	ds_read_b128 v[204:207], v150 offset:50176
	global_load_lds_dwordx4 v136, s[22:23]
	ds_read_b128 v[208:211], v150 offset:51200
	ds_read_b128 v[212:215], v150 offset:52224
	ds_read_b128 v[216:219], v150 offset:53248
	ds_read_b128 v[220:223], v150 offset:54272
	ds_read_b128 v[224:227], v150 offset:55296
	ds_read_b128 v[228:231], v150 offset:56320
	s_waitcnt vmcnt(6)
	s_waitcnt lgkmcnt(0)
	s_barrier
	s_setprio 1
	s_waitcnt lgkmcnt(0)
	v_mfma_f32_16x16x32_bf16 v[62:65], v[142:145], v[192:195], v[62:65]
	v_mfma_f32_16x16x32_bf16 v[62:65], v[154:157], v[204:207], v[62:65]
	v_mfma_f32_16x16x32_bf16 v[58:61], v[168:171], v[204:207], v[58:61]
	v_mfma_f32_16x16x32_bf16 v[58:61], v[158:161], v[192:195], v[58:61]
	v_mfma_f32_16x16x32_bf16 v[54:57], v[176:179], v[192:195], v[54:57]
	v_mfma_f32_16x16x32_bf16 v[54:57], v[180:183], v[204:207], v[54:57]
	v_mfma_f32_16x16x32_bf16 v[50:53], v[188:191], v[204:207], v[50:53]
	v_mfma_f32_16x16x32_bf16 v[50:53], v[184:187], v[192:195], v[50:53]
	v_mfma_f32_16x16x32_bf16 v[34:37], v[184:187], v[208:211], v[34:37]
	v_mfma_f32_16x16x32_bf16 v[34:37], v[188:191], v[212:215], v[34:37]
	v_mfma_f32_16x16x32_bf16 v[38:41], v[180:183], v[212:215], v[38:41]
	v_mfma_f32_16x16x32_bf16 v[38:41], v[176:179], v[208:211], v[38:41]
	v_mfma_f32_16x16x32_bf16 v[42:45], v[158:161], v[208:211], v[42:45]
	v_mfma_f32_16x16x32_bf16 v[42:45], v[168:171], v[212:215], v[42:45]
	v_mfma_f32_16x16x32_bf16 v[46:49], v[154:157], v[212:215], v[46:49]
	v_mfma_f32_16x16x32_bf16 v[46:49], v[142:145], v[208:211], v[46:49]
	v_mfma_f32_16x16x32_bf16 v[30:33], v[142:145], v[216:219], v[30:33]
	v_mfma_f32_16x16x32_bf16 v[30:33], v[154:157], v[220:223], v[30:33]
	v_mfma_f32_16x16x32_bf16 v[26:29], v[168:171], v[220:223], v[26:29]
	v_mfma_f32_16x16x32_bf16 v[26:29], v[158:161], v[216:219], v[26:29]
	v_mfma_f32_16x16x32_bf16 v[22:25], v[176:179], v[216:219], v[22:25]
	v_mfma_f32_16x16x32_bf16 v[22:25], v[180:183], v[220:223], v[22:25]
	v_mfma_f32_16x16x32_bf16 v[18:21], v[188:191], v[220:223], v[18:21]
	v_mfma_f32_16x16x32_bf16 v[18:21], v[184:187], v[216:219], v[18:21]
	v_mfma_f32_16x16x32_bf16 v[2:5], v[184:187], v[224:227], v[2:5]
	v_mfma_f32_16x16x32_bf16 v[2:5], v[188:191], v[228:231], v[2:5]
	v_mfma_f32_16x16x32_bf16 v[6:9], v[180:183], v[228:231], v[6:9]
	v_mfma_f32_16x16x32_bf16 v[6:9], v[176:179], v[224:227], v[6:9]
	v_mfma_f32_16x16x32_bf16 v[10:13], v[158:161], v[224:227], v[10:13]
	v_mfma_f32_16x16x32_bf16 v[10:13], v[168:171], v[228:231], v[10:13]
	v_mfma_f32_16x16x32_bf16 v[14:17], v[154:157], v[228:231], v[14:17]
	v_mfma_f32_16x16x32_bf16 v[14:17], v[142:145], v[224:227], v[14:17]
	s_setprio 0
	s_barrier
	s_add_i32 s57, s57, 2
	s_add_u32 s20, s20, 0x100
	s_addc_u32 s21, s21, 0
	s_add_u32 s55, s55, 0x100
	s_addc_u32 s56, s56, 0
	s_cmp_gt_u32 s57, 61
	s_cbranch_scc0 .LBB0_2373
	s_and_b64 vcc, exec, s[16:17]
	s_cbranch_vccz .LBB0_2376
	s_barrier

.LBB0_2618:
	s_add_u32 s64, s28, 0xffd50000
	s_addc_u32 s65, s29, -1
	s_mov_b32 m0, s44
	ds_read_b128 v[142:145], v156
	global_load_lds_dwordx4 v130, s[64:65]
	s_mov_b32 m0, s45
	ds_read_b128 v[168:171], v156 offset:1024
	global_load_lds_dwordx4 v134, s[64:65]
	s_mov_b32 m0, s46
	ds_read_b128 v[172:175], v156 offset:2048
	global_load_lds_dwordx4 v138, s[28:29]
	s_mov_b32 m0, s47
	ds_read_b128 v[176:179], v156 offset:3072
	global_load_lds_dwordx4 v140, s[28:29]
	ds_read_b128 v[180:183], v157
	ds_read_b128 v[184:187], v157 offset:1024
	ds_read_b128 v[188:191], v157 offset:2048
	ds_read_b128 v[192:195], v157 offset:3072
	s_add_u32 s30, s28, 0xffd50080
	s_addc_u32 s31, s29, -1
	s_cmpk_eq_i32 s62, 0xa8
	s_cselect_b32 s35, s25, s31
	s_cselect_b32 s34, s24, s30
	s_cselect_b32 s31, s23, s61
	s_cselect_b32 s30, s22, s60
	ds_read_b128 v[196:199], v158
	ds_read_b128 v[200:203], v158 offset:1024
	ds_read_b128 v[204:207], v158 offset:2048
	ds_read_b128 v[208:211], v158 offset:3072
	ds_read_b128 v[212:215], v158 offset:4096
	ds_read_b128 v[216:219], v158 offset:5120
	ds_read_b128 v[220:223], v158 offset:6144
	ds_read_b128 v[224:227], v158 offset:7168
	s_waitcnt vmcnt(8)
	s_waitcnt lgkmcnt(0)
	s_barrier
	s_setprio 1
	s_waitcnt lgkmcnt(0)
	v_mfma_f32_16x16x32_bf16 v[126:129], v[142:145], v[196:199], v[126:129]
	v_mfma_f32_16x16x32_bf16 v[126:129], v[168:171], v[200:203], v[126:129]
	v_mfma_f32_16x16x32_bf16 v[122:125], v[176:179], v[200:203], v[122:125]
	v_mfma_f32_16x16x32_bf16 v[122:125], v[172:175], v[196:199], v[122:125]
	v_mfma_f32_16x16x32_bf16 v[118:121], v[180:183], v[196:199], v[118:121]
	v_mfma_f32_16x16x32_bf16 v[118:121], v[184:187], v[200:203], v[118:121]
	v_mfma_f32_16x16x32_bf16 v[114:117], v[192:195], v[200:203], v[114:117]
	v_mfma_f32_16x16x32_bf16 v[114:117], v[188:191], v[196:199], v[114:117]
	v_mfma_f32_16x16x32_bf16 v[98:101], v[188:191], v[204:207], v[98:101]
	v_mfma_f32_16x16x32_bf16 v[98:101], v[192:195], v[208:211], v[98:101]
	v_mfma_f32_16x16x32_bf16 v[102:105], v[184:187], v[208:211], v[102:105]
	v_mfma_f32_16x16x32_bf16 v[102:105], v[180:183], v[204:207], v[102:105]
	v_mfma_f32_16x16x32_bf16 v[106:109], v[172:175], v[204:207], v[106:109]
	v_mfma_f32_16x16x32_bf16 v[106:109], v[176:179], v[208:211], v[106:109]
	v_mfma_f32_16x16x32_bf16 v[110:113], v[168:171], v[208:211], v[110:113]
	v_mfma_f32_16x16x32_bf16 v[110:113], v[142:145], v[204:207], v[110:113]
	v_mfma_f32_16x16x32_bf16 v[94:97], v[142:145], v[212:215], v[94:97]
	v_mfma_f32_16x16x32_bf16 v[94:97], v[168:171], v[216:219], v[94:97]
	v_mfma_f32_16x16x32_bf16 v[90:93], v[176:179], v[216:219], v[90:93]
	v_mfma_f32_16x16x32_bf16 v[90:93], v[172:175], v[212:215], v[90:93]
	v_mfma_f32_16x16x32_bf16 v[86:89], v[180:183], v[212:215], v[86:89]
	v_mfma_f32_16x16x32_bf16 v[86:89], v[184:187], v[216:219], v[86:89]
	v_mfma_f32_16x16x32_bf16 v[82:85], v[192:195], v[216:219], v[82:85]
	v_mfma_f32_16x16x32_bf16 v[82:85], v[188:191], v[212:215], v[82:85]
	v_mfma_f32_16x16x32_bf16 v[66:69], v[188:191], v[220:223], v[66:69]
	v_mfma_f32_16x16x32_bf16 v[66:69], v[192:195], v[224:227], v[66:69]
	v_mfma_f32_16x16x32_bf16 v[70:73], v[184:187], v[224:227], v[70:73]
	v_mfma_f32_16x16x32_bf16 v[70:73], v[180:183], v[220:223], v[70:73]
	v_mfma_f32_16x16x32_bf16 v[74:77], v[172:175], v[220:223], v[74:77]
	v_mfma_f32_16x16x32_bf16 v[74:77], v[176:179], v[224:227], v[74:77]
	v_mfma_f32_16x16x32_bf16 v[78:81], v[168:171], v[224:227], v[78:81]
	v_mfma_f32_16x16x32_bf16 v[78:81], v[142:145], v[220:223], v[78:81]
	s_setprio 0
	s_barrier
	s_mov_b32 m0, s48
	s_add_u32 s64, s30, 0x2b0000
	global_load_lds_dwordx4 v132, s[30:31]
	s_mov_b32 m0, s49
	s_addc_u32 s65, s31, 0
	global_load_lds_dwordx4 v136, s[30:31]
	s_mov_b32 m0, s50
	ds_read_b128 v[196:199], v158 offset:16384
	global_load_lds_dwordx4 v132, s[64:65]
	s_mov_b32 m0, s51
	ds_read_b128 v[200:203], v158 offset:17408
	global_load_lds_dwordx4 v136, s[64:65]
	ds_read_b128 v[204:207], v158 offset:18432
	ds_read_b128 v[208:211], v158 offset:19456
	ds_read_b128 v[212:215], v158 offset:20480
	ds_read_b128 v[216:219], v158 offset:21504
	ds_read_b128 v[220:223], v158 offset:22528
	ds_read_b128 v[224:227], v158 offset:23552
	s_waitcnt vmcnt(6)
	s_waitcnt lgkmcnt(0)
	s_barrier
	s_setprio 1
	s_waitcnt lgkmcnt(0)
	v_mfma_f32_16x16x32_bf16 v[62:65], v[142:145], v[196:199], v[62:65]
	v_mfma_f32_16x16x32_bf16 v[62:65], v[168:171], v[200:203], v[62:65]
	v_mfma_f32_16x16x32_bf16 v[58:61], v[176:179], v[200:203], v[58:61]
	v_mfma_f32_16x16x32_bf16 v[58:61], v[172:175], v[196:199], v[58:61]
	v_mfma_f32_16x16x32_bf16 v[54:57], v[180:183], v[196:199], v[54:57]
	v_mfma_f32_16x16x32_bf16 v[54:57], v[184:187], v[200:203], v[54:57]
	v_mfma_f32_16x16x32_bf16 v[50:53], v[192:195], v[200:203], v[50:53]
	v_mfma_f32_16x16x32_bf16 v[50:53], v[188:191], v[196:199], v[50:53]
	v_mfma_f32_16x16x32_bf16 v[34:37], v[188:191], v[204:207], v[34:37]
	v_mfma_f32_16x16x32_bf16 v[34:37], v[192:195], v[208:211], v[34:37]
	v_mfma_f32_16x16x32_bf16 v[38:41], v[184:187], v[208:211], v[38:41]
	v_mfma_f32_16x16x32_bf16 v[38:41], v[180:183], v[204:207], v[38:41]
	v_mfma_f32_16x16x32_bf16 v[42:45], v[172:175], v[204:207], v[42:45]
	v_mfma_f32_16x16x32_bf16 v[42:45], v[176:179], v[208:211], v[42:45]
	v_mfma_f32_16x16x32_bf16 v[46:49], v[168:171], v[208:211], v[46:49]
	v_mfma_f32_16x16x32_bf16 v[46:49], v[142:145], v[204:207], v[46:49]
	v_mfma_f32_16x16x32_bf16 v[30:33], v[142:145], v[212:215], v[30:33]
	v_mfma_f32_16x16x32_bf16 v[30:33], v[168:171], v[216:219], v[30:33]
	v_mfma_f32_16x16x32_bf16 v[26:29], v[176:179], v[216:219], v[26:29]
	v_mfma_f32_16x16x32_bf16 v[26:29], v[172:175], v[212:215], v[26:29]
	v_mfma_f32_16x16x32_bf16 v[22:25], v[180:183], v[212:215], v[22:25]
	v_mfma_f32_16x16x32_bf16 v[22:25], v[184:187], v[216:219], v[22:25]
	v_mfma_f32_16x16x32_bf16 v[18:21], v[192:195], v[216:219], v[18:21]
	v_mfma_f32_16x16x32_bf16 v[18:21], v[188:191], v[212:215], v[18:21]
	v_mfma_f32_16x16x32_bf16 v[2:5], v[188:191], v[220:223], v[2:5]
	v_mfma_f32_16x16x32_bf16 v[2:5], v[192:195], v[224:227], v[2:5]
	v_mfma_f32_16x16x32_bf16 v[6:9], v[184:187], v[224:227], v[6:9]
	v_mfma_f32_16x16x32_bf16 v[6:9], v[180:183], v[220:223], v[6:9]
	v_mfma_f32_16x16x32_bf16 v[10:13], v[172:175], v[220:223], v[10:13]
	v_mfma_f32_16x16x32_bf16 v[10:13], v[176:179], v[224:227], v[10:13]
	v_mfma_f32_16x16x32_bf16 v[14:17], v[168:171], v[224:227], v[14:17]
	v_mfma_f32_16x16x32_bf16 v[14:17], v[142:145], v[220:223], v[14:17]
	s_setprio 0
	s_barrier
	s_mov_b32 m0, s39
	ds_read_b128 v[142:145], v159
	global_load_lds_dwordx4 v130, s[34:35]
	s_mov_b32 m0, s40
	ds_read_b128 v[168:171], v159 offset:1024
	global_load_lds_dwordx4 v134, s[34:35]
	s_add_u32 s34, s34, 0x2b0000
	s_addc_u32 s35, s35, 0
	s_mov_b32 m0, s41
	ds_read_b128 v[172:175], v159 offset:2048
	global_load_lds_dwordx4 v130, s[34:35]
	s_mov_b32 m0, s42
	ds_read_b128 v[176:179], v159 offset:3072
	global_load_lds_dwordx4 v134, s[34:35]
	ds_read_b128 v[180:183], v160
	ds_read_b128 v[184:187], v160 offset:1024
	ds_read_b128 v[188:191], v160 offset:2048
	ds_read_b128 v[192:195], v160 offset:3072
	ds_read_b128 v[196:199], v158 offset:32768
	ds_read_b128 v[200:203], v158 offset:33792
	ds_read_b128 v[204:207], v158 offset:34816
	ds_read_b128 v[208:211], v158 offset:35840
	ds_read_b128 v[212:215], v158 offset:36864
	ds_read_b128 v[216:219], v158 offset:37888
	ds_read_b128 v[220:223], v158 offset:38912
	ds_read_b128 v[224:227], v158 offset:39936
	s_waitcnt vmcnt(8)
	s_waitcnt lgkmcnt(0)
	s_barrier
	s_setprio 1
	s_waitcnt lgkmcnt(0)
	v_mfma_f32_16x16x32_bf16 v[126:129], v[142:145], v[196:199], v[126:129]
	v_mfma_f32_16x16x32_bf16 v[126:129], v[168:171], v[200:203], v[126:129]
	v_mfma_f32_16x16x32_bf16 v[122:125], v[176:179], v[200:203], v[122:125]
	v_mfma_f32_16x16x32_bf16 v[122:125], v[172:175], v[196:199], v[122:125]
	v_mfma_f32_16x16x32_bf16 v[118:121], v[180:183], v[196:199], v[118:121]
	v_mfma_f32_16x16x32_bf16 v[118:121], v[184:187], v[200:203], v[118:121]
	v_mfma_f32_16x16x32_bf16 v[114:117], v[192:195], v[200:203], v[114:117]
	v_mfma_f32_16x16x32_bf16 v[114:117], v[188:191], v[196:199], v[114:117]
	v_mfma_f32_16x16x32_bf16 v[98:101], v[188:191], v[204:207], v[98:101]
	v_mfma_f32_16x16x32_bf16 v[98:101], v[192:195], v[208:211], v[98:101]
	v_mfma_f32_16x16x32_bf16 v[102:105], v[184:187], v[208:211], v[102:105]
	v_mfma_f32_16x16x32_bf16 v[102:105], v[180:183], v[204:207], v[102:105]
	v_mfma_f32_16x16x32_bf16 v[106:109], v[172:175], v[204:207], v[106:109]
	v_mfma_f32_16x16x32_bf16 v[106:109], v[176:179], v[208:211], v[106:109]
	v_mfma_f32_16x16x32_bf16 v[110:113], v[168:171], v[208:211], v[110:113]
	v_mfma_f32_16x16x32_bf16 v[110:113], v[142:145], v[204:207], v[110:113]
	v_mfma_f32_16x16x32_bf16 v[94:97], v[142:145], v[212:215], v[94:97]
	v_mfma_f32_16x16x32_bf16 v[94:97], v[168:171], v[216:219], v[94:97]
	v_mfma_f32_16x16x32_bf16 v[90:93], v[176:179], v[216:219], v[90:93]
	v_mfma_f32_16x16x32_bf16 v[90:93], v[172:175], v[212:215], v[90:93]
	v_mfma_f32_16x16x32_bf16 v[86:89], v[180:183], v[212:215], v[86:89]
	v_mfma_f32_16x16x32_bf16 v[86:89], v[184:187], v[216:219], v[86:89]
	v_mfma_f32_16x16x32_bf16 v[82:85], v[192:195], v[216:219], v[82:85]
	v_mfma_f32_16x16x32_bf16 v[82:85], v[188:191], v[212:215], v[82:85]
	v_mfma_f32_16x16x32_bf16 v[66:69], v[188:191], v[220:223], v[66:69]
	v_mfma_f32_16x16x32_bf16 v[66:69], v[192:195], v[224:227], v[66:69]
	v_mfma_f32_16x16x32_bf16 v[70:73], v[184:187], v[224:227], v[70:73]
	v_mfma_f32_16x16x32_bf16 v[70:73], v[180:183], v[220:223], v[70:73]
	v_mfma_f32_16x16x32_bf16 v[74:77], v[172:175], v[220:223], v[74:77]
	v_mfma_f32_16x16x32_bf16 v[74:77], v[176:179], v[224:227], v[74:77]
	v_mfma_f32_16x16x32_bf16 v[78:81], v[168:171], v[224:227], v[78:81]
	v_mfma_f32_16x16x32_bf16 v[78:81], v[142:145], v[220:223], v[78:81]
	s_setprio 0
	s_barrier
	s_mov_b32 m0, s52
	s_add_u32 s30, s30, 0x80
	s_addc_u32 s31, s31, 0
	global_load_lds_dwordx4 v132, s[30:31]
	s_mov_b32 m0, s53
	ds_read_b128 v[196:199], v158 offset:49152
	global_load_lds_dwordx4 v136, s[30:31]
	s_mov_b32 m0, s54
	s_add_u32 s30, s30, 0x2b0000
	s_addc_u32 s31, s31, 0
	global_load_lds_dwordx4 v132, s[30:31]
	s_mov_b32 m0, s55
	ds_read_b128 v[200:203], v158 offset:50176
	global_load_lds_dwordx4 v136, s[30:31]
	ds_read_b128 v[204:207], v158 offset:51200
	ds_read_b128 v[208:211], v158 offset:52224
	ds_read_b128 v[212:215], v158 offset:53248
	ds_read_b128 v[216:219], v158 offset:54272
	ds_read_b128 v[220:223], v158 offset:55296
	ds_read_b128 v[224:227], v158 offset:56320
	s_waitcnt vmcnt(6)
	s_waitcnt lgkmcnt(0)
	s_barrier
	s_setprio 1
	s_waitcnt lgkmcnt(0)
	v_mfma_f32_16x16x32_bf16 v[62:65], v[142:145], v[196:199], v[62:65]
	v_mfma_f32_16x16x32_bf16 v[62:65], v[168:171], v[200:203], v[62:65]
	v_mfma_f32_16x16x32_bf16 v[58:61], v[176:179], v[200:203], v[58:61]
	v_mfma_f32_16x16x32_bf16 v[58:61], v[172:175], v[196:199], v[58:61]
	v_mfma_f32_16x16x32_bf16 v[54:57], v[180:183], v[196:199], v[54:57]
	v_mfma_f32_16x16x32_bf16 v[54:57], v[184:187], v[200:203], v[54:57]
	v_mfma_f32_16x16x32_bf16 v[50:53], v[192:195], v[200:203], v[50:53]
	v_mfma_f32_16x16x32_bf16 v[50:53], v[188:191], v[196:199], v[50:53]
	v_mfma_f32_16x16x32_bf16 v[34:37], v[188:191], v[204:207], v[34:37]
	v_mfma_f32_16x16x32_bf16 v[34:37], v[192:195], v[208:211], v[34:37]
	v_mfma_f32_16x16x32_bf16 v[38:41], v[184:187], v[208:211], v[38:41]
	v_mfma_f32_16x16x32_bf16 v[38:41], v[180:183], v[204:207], v[38:41]
	v_mfma_f32_16x16x32_bf16 v[42:45], v[172:175], v[204:207], v[42:45]
	v_mfma_f32_16x16x32_bf16 v[42:45], v[176:179], v[208:211], v[42:45]
	v_mfma_f32_16x16x32_bf16 v[46:49], v[168:171], v[208:211], v[46:49]
	v_mfma_f32_16x16x32_bf16 v[46:49], v[142:145], v[204:207], v[46:49]
	v_mfma_f32_16x16x32_bf16 v[30:33], v[142:145], v[212:215], v[30:33]
	v_mfma_f32_16x16x32_bf16 v[30:33], v[168:171], v[216:219], v[30:33]
	v_mfma_f32_16x16x32_bf16 v[26:29], v[176:179], v[216:219], v[26:29]
	v_mfma_f32_16x16x32_bf16 v[26:29], v[172:175], v[212:215], v[26:29]
	v_mfma_f32_16x16x32_bf16 v[22:25], v[180:183], v[212:215], v[22:25]
	v_mfma_f32_16x16x32_bf16 v[22:25], v[184:187], v[216:219], v[22:25]
	v_mfma_f32_16x16x32_bf16 v[18:21], v[192:195], v[216:219], v[18:21]
	v_mfma_f32_16x16x32_bf16 v[18:21], v[188:191], v[212:215], v[18:21]
	v_mfma_f32_16x16x32_bf16 v[2:5], v[188:191], v[220:223], v[2:5]
	v_mfma_f32_16x16x32_bf16 v[2:5], v[192:195], v[224:227], v[2:5]
	v_mfma_f32_16x16x32_bf16 v[6:9], v[184:187], v[224:227], v[6:9]
	v_mfma_f32_16x16x32_bf16 v[6:9], v[180:183], v[220:223], v[6:9]
	v_mfma_f32_16x16x32_bf16 v[10:13], v[172:175], v[220:223], v[10:13]
	v_mfma_f32_16x16x32_bf16 v[10:13], v[176:179], v[224:227], v[10:13]
	v_mfma_f32_16x16x32_bf16 v[14:17], v[168:171], v[224:227], v[14:17]
	v_mfma_f32_16x16x32_bf16 v[14:17], v[142:145], v[220:223], v[14:17]
	s_setprio 0
	s_barrier
	s_add_i32 s62, s62, 2
	s_add_u32 s28, s28, 0x100
	s_addc_u32 s29, s29, 0
	s_add_u32 s60, s60, 0x100
	s_addc_u32 s61, s61, 0
	s_cmpk_gt_u32 s62, 0xa9
	s_cbranch_scc0 .LBB0_2618
	s_and_b64 vcc, exec, s[12:13]
	s_cbranch_vccz .LBB0_2621
	s_barrier

.LBB0_2632:
	ds_read_b128 v[150:153], v1
	ds_read_b128 v[154:157], v1 offset:1024
	ds_read_b128 v[158:161], v1 offset:2048
	ds_read_b128 v[166:169], v1 offset:3072
	ds_read_b128 v[170:173], v139
	ds_read_b128 v[174:177], v139 offset:1024
	ds_read_b128 v[178:181], v139 offset:2048
	ds_read_b128 v[182:185], v139 offset:3072
	s_add_i32 s38, s13, 2
	s_add_u32 s12, s10, 0xc2050080
	s_addc_u32 s14, s11, -1
	s_cmp_lg_u32 s26, s13
	s_cselect_b32 s12, s12, 0
	s_cselect_b32 s13, s14, 0
	s_add_u32 s14, s4, s12
	s_addc_u32 s15, s5, s13
	s_add_u32 s12, s6, s12
	s_addc_u32 s13, s7, s13
	s_mov_b32 m0, s27
	v_lshl_add_u64 v[162:163], v[140:141], 0, s[10:11]
	ds_read_b128 v[186:189], v144
	ds_read_b128 v[190:193], v144 offset:1024
	ds_read_b128 v[194:197], v144 offset:2048
	ds_read_b128 v[198:201], v144 offset:3072
	ds_read_b128 v[202:205], v144 offset:4096
	ds_read_b128 v[206:209], v144 offset:5120
	ds_read_b128 v[210:213], v144 offset:6144
	ds_read_b128 v[214:217], v144 offset:7168
	global_load_lds_dwordx4 v[162:163], off
	v_lshl_add_u64 v[162:163], v[142:143], 0, s[10:11]
	s_mov_b32 m0, s28
	s_nop 0
	global_load_lds_dwordx4 v[162:163], off
	s_waitcnt vmcnt(8)
	s_waitcnt lgkmcnt(0)
	s_barrier
	s_setprio 1
	s_waitcnt lgkmcnt(0)
	v_mfma_f32_16x16x32_bf16 v[126:129], v[150:153], v[186:189], v[126:129]
	v_mfma_f32_16x16x32_bf16 v[126:129], v[154:157], v[190:193], v[126:129]
	v_mfma_f32_16x16x32_bf16 v[122:125], v[166:169], v[190:193], v[122:125]
	v_mfma_f32_16x16x32_bf16 v[122:125], v[158:161], v[186:189], v[122:125]
	v_mfma_f32_16x16x32_bf16 v[110:113], v[170:173], v[186:189], v[110:113]
	v_mfma_f32_16x16x32_bf16 v[110:113], v[174:177], v[190:193], v[110:113]
	v_mfma_f32_16x16x32_bf16 v[106:109], v[182:185], v[190:193], v[106:109]
	v_mfma_f32_16x16x32_bf16 v[106:109], v[178:181], v[186:189], v[106:109]
	v_mfma_f32_16x16x32_bf16 v[90:93], v[178:181], v[194:197], v[90:93]
	v_mfma_f32_16x16x32_bf16 v[90:93], v[182:185], v[198:201], v[90:93]
	v_mfma_f32_16x16x32_bf16 v[94:97], v[174:177], v[198:201], v[94:97]
	v_mfma_f32_16x16x32_bf16 v[94:97], v[170:173], v[194:197], v[94:97]
	v_mfma_f32_16x16x32_bf16 v[114:117], v[158:161], v[194:197], v[114:117]
	v_mfma_f32_16x16x32_bf16 v[114:117], v[166:169], v[198:201], v[114:117]
	v_mfma_f32_16x16x32_bf16 v[118:121], v[154:157], v[198:201], v[118:121]
	v_mfma_f32_16x16x32_bf16 v[118:121], v[150:153], v[194:197], v[118:121]
	v_mfma_f32_16x16x32_bf16 v[102:105], v[150:153], v[202:205], v[102:105]
	v_mfma_f32_16x16x32_bf16 v[102:105], v[154:157], v[206:209], v[102:105]
	v_mfma_f32_16x16x32_bf16 v[98:101], v[166:169], v[206:209], v[98:101]
	v_mfma_f32_16x16x32_bf16 v[98:101], v[158:161], v[202:205], v[98:101]
	v_mfma_f32_16x16x32_bf16 v[78:81], v[170:173], v[202:205], v[78:81]
	v_mfma_f32_16x16x32_bf16 v[78:81], v[174:177], v[206:209], v[78:81]
	v_mfma_f32_16x16x32_bf16 v[74:77], v[182:185], v[206:209], v[74:77]
	v_mfma_f32_16x16x32_bf16 v[74:77], v[178:181], v[202:205], v[74:77]
	v_mfma_f32_16x16x32_bf16 v[66:69], v[178:181], v[210:213], v[66:69]
	v_mfma_f32_16x16x32_bf16 v[66:69], v[182:185], v[214:217], v[66:69]
	v_mfma_f32_16x16x32_bf16 v[70:73], v[174:177], v[214:217], v[70:73]
	v_mfma_f32_16x16x32_bf16 v[70:73], v[170:173], v[210:213], v[70:73]
	v_mfma_f32_16x16x32_bf16 v[82:85], v[158:161], v[210:213], v[82:85]
	v_mfma_f32_16x16x32_bf16 v[82:85], v[166:169], v[214:217], v[82:85]
	v_mfma_f32_16x16x32_bf16 v[86:89], v[154:157], v[214:217], v[86:89]
	v_mfma_f32_16x16x32_bf16 v[86:89], v[150:153], v[210:213], v[86:89]
	s_setprio 0
	s_barrier
	s_mov_b32 m0, s29
	v_lshl_add_u64 v[162:163], s[12:13], 0, v[132:133]
	s_add_u32 s40, s12, 0x2b0000
	ds_read_b128 v[186:189], v144 offset:16384
	ds_read_b128 v[190:193], v144 offset:17408
	ds_read_b128 v[194:197], v144 offset:18432
	ds_read_b128 v[198:201], v144 offset:19456
	ds_read_b128 v[202:205], v144 offset:20480
	ds_read_b128 v[206:209], v144 offset:21504
	ds_read_b128 v[210:213], v144 offset:22528
	ds_read_b128 v[214:217], v144 offset:23552
	global_load_lds_dwordx4 v[162:163], off
	v_lshl_add_u64 v[218:219], s[12:13], 0, v[136:137]
	s_mov_b32 m0, s30
	s_addc_u32 s41, s13, 0
	global_load_lds_dwordx4 v[218:219], off
	v_lshl_add_u64 v[220:221], s[40:41], 0, v[132:133]
	s_mov_b32 m0, s31
	v_lshl_add_u64 v[222:223], s[14:15], 0, v[134:135]
	global_load_lds_dwordx4 v[220:221], off
	v_lshl_add_u64 v[220:221], s[40:41], 0, v[136:137]
	s_mov_b32 m0, s33
	s_nop 0
	global_load_lds_dwordx4 v[220:221], off
	v_lshl_add_u64 v[220:221], s[14:15], 0, v[130:131]
	s_mov_b32 m0, s19
	s_nop 0
	global_load_lds_dwordx4 v[220:221], off
	s_mov_b32 m0, s20
	s_nop 0
	global_load_lds_dwordx4 v[222:223], off
	s_waitcnt vmcnt(8)
	s_waitcnt lgkmcnt(0)
	s_barrier
	s_setprio 1
	s_waitcnt lgkmcnt(0)
	v_mfma_f32_16x16x32_bf16 v[62:65], v[150:153], v[186:189], v[62:65]
	v_mfma_f32_16x16x32_bf16 v[62:65], v[154:157], v[190:193], v[62:65]
	v_mfma_f32_16x16x32_bf16 v[58:61], v[166:169], v[190:193], v[58:61]
	v_mfma_f32_16x16x32_bf16 v[58:61], v[158:161], v[186:189], v[58:61]
	v_mfma_f32_16x16x32_bf16 v[46:49], v[170:173], v[186:189], v[46:49]
	v_mfma_f32_16x16x32_bf16 v[46:49], v[174:177], v[190:193], v[46:49]
	v_mfma_f32_16x16x32_bf16 v[42:45], v[182:185], v[190:193], v[42:45]
	v_mfma_f32_16x16x32_bf16 v[42:45], v[178:181], v[186:189], v[42:45]
	v_mfma_f32_16x16x32_bf16 v[26:29], v[178:181], v[194:197], v[26:29]
	v_mfma_f32_16x16x32_bf16 v[26:29], v[182:185], v[198:201], v[26:29]
	v_mfma_f32_16x16x32_bf16 v[30:33], v[174:177], v[198:201], v[30:33]
	v_mfma_f32_16x16x32_bf16 v[30:33], v[170:173], v[194:197], v[30:33]
	v_mfma_f32_16x16x32_bf16 v[50:53], v[158:161], v[194:197], v[50:53]
	v_mfma_f32_16x16x32_bf16 v[50:53], v[166:169], v[198:201], v[50:53]
	v_mfma_f32_16x16x32_bf16 v[54:57], v[154:157], v[198:201], v[54:57]
	v_mfma_f32_16x16x32_bf16 v[54:57], v[150:153], v[194:197], v[54:57]
	v_mfma_f32_16x16x32_bf16 v[38:41], v[150:153], v[202:205], v[38:41]
	v_mfma_f32_16x16x32_bf16 v[38:41], v[154:157], v[206:209], v[38:41]
	v_mfma_f32_16x16x32_bf16 v[34:37], v[166:169], v[206:209], v[34:37]
	v_mfma_f32_16x16x32_bf16 v[34:37], v[158:161], v[202:205], v[34:37]
	v_mfma_f32_16x16x32_bf16 v[14:17], v[170:173], v[202:205], v[14:17]
	v_mfma_f32_16x16x32_bf16 v[14:17], v[174:177], v[206:209], v[14:17]
	v_mfma_f32_16x16x32_bf16 v[10:13], v[182:185], v[206:209], v[10:13]
	v_mfma_f32_16x16x32_bf16 v[10:13], v[178:181], v[202:205], v[10:13]
	v_mfma_f32_16x16x32_bf16 v[2:5], v[178:181], v[210:213], v[2:5]
	v_mfma_f32_16x16x32_bf16 v[2:5], v[182:185], v[214:217], v[2:5]
	v_mfma_f32_16x16x32_bf16 v[6:9], v[174:177], v[214:217], v[6:9]
	v_mfma_f32_16x16x32_bf16 v[6:9], v[170:173], v[210:213], v[6:9]
	v_mfma_f32_16x16x32_bf16 v[18:21], v[158:161], v[210:213], v[18:21]
	v_mfma_f32_16x16x32_bf16 v[18:21], v[166:169], v[214:217], v[18:21]
	v_mfma_f32_16x16x32_bf16 v[22:25], v[154:157], v[214:217], v[22:25]
	v_mfma_f32_16x16x32_bf16 v[22:25], v[150:153], v[210:213], v[22:25]
	s_setprio 0
	s_barrier
	ds_read_b128 v[150:153], v145
	ds_read_b128 v[154:157], v145 offset:1024
	ds_read_b128 v[158:161], v145 offset:2048
	ds_read_b128 v[166:169], v145 offset:3072
	ds_read_b128 v[170:173], v146
	ds_read_b128 v[174:177], v146 offset:1024
	ds_read_b128 v[178:181], v146 offset:2048
	ds_read_b128 v[182:185], v146 offset:3072
	s_add_u32 s14, s14, 0x2b0000
	s_addc_u32 s15, s15, 0
	s_mov_b32 m0, s21
	v_lshl_add_u64 v[224:225], s[14:15], 0, v[130:131]
	ds_read_b128 v[186:189], v144 offset:32768
	ds_read_b128 v[190:193], v144 offset:33792
	ds_read_b128 v[194:197], v144 offset:34816
	ds_read_b128 v[198:201], v144 offset:35840
	ds_read_b128 v[202:205], v144 offset:36864
	ds_read_b128 v[206:209], v144 offset:37888
	ds_read_b128 v[210:213], v144 offset:38912
	ds_read_b128 v[214:217], v144 offset:39936
	global_load_lds_dwordx4 v[224:225], off
	v_lshl_add_u64 v[224:225], s[14:15], 0, v[134:135]
	s_mov_b32 m0, s22
	s_nop 0
	global_load_lds_dwordx4 v[224:225], off
	s_waitcnt vmcnt(8)
	s_waitcnt lgkmcnt(0)
	s_barrier
	s_setprio 1
	s_waitcnt lgkmcnt(0)
	v_mfma_f32_16x16x32_bf16 v[126:129], v[150:153], v[186:189], v[126:129]
	v_mfma_f32_16x16x32_bf16 v[126:129], v[154:157], v[190:193], v[126:129]
	v_mfma_f32_16x16x32_bf16 v[122:125], v[166:169], v[190:193], v[122:125]
	v_mfma_f32_16x16x32_bf16 v[122:125], v[158:161], v[186:189], v[122:125]
	v_mfma_f32_16x16x32_bf16 v[110:113], v[170:173], v[186:189], v[110:113]
	v_mfma_f32_16x16x32_bf16 v[110:113], v[174:177], v[190:193], v[110:113]
	v_mfma_f32_16x16x32_bf16 v[106:109], v[182:185], v[190:193], v[106:109]
	v_mfma_f32_16x16x32_bf16 v[106:109], v[178:181], v[186:189], v[106:109]
	v_mfma_f32_16x16x32_bf16 v[90:93], v[178:181], v[194:197], v[90:93]
	v_mfma_f32_16x16x32_bf16 v[90:93], v[182:185], v[198:201], v[90:93]
	v_mfma_f32_16x16x32_bf16 v[94:97], v[174:177], v[198:201], v[94:97]
	v_mfma_f32_16x16x32_bf16 v[94:97], v[170:173], v[194:197], v[94:97]
	v_mfma_f32_16x16x32_bf16 v[114:117], v[158:161], v[194:197], v[114:117]
	v_mfma_f32_16x16x32_bf16 v[114:117], v[166:169], v[198:201], v[114:117]
	v_mfma_f32_16x16x32_bf16 v[118:121], v[154:157], v[198:201], v[118:121]
	v_mfma_f32_16x16x32_bf16 v[118:121], v[150:153], v[194:197], v[118:121]
	v_mfma_f32_16x16x32_bf16 v[102:105], v[150:153], v[202:205], v[102:105]
	v_mfma_f32_16x16x32_bf16 v[102:105], v[154:157], v[206:209], v[102:105]
	v_mfma_f32_16x16x32_bf16 v[98:101], v[166:169], v[206:209], v[98:101]
	v_mfma_f32_16x16x32_bf16 v[98:101], v[158:161], v[202:205], v[98:101]
	v_mfma_f32_16x16x32_bf16 v[78:81], v[170:173], v[202:205], v[78:81]
	v_mfma_f32_16x16x32_bf16 v[78:81], v[174:177], v[206:209], v[78:81]
	v_mfma_f32_16x16x32_bf16 v[74:77], v[182:185], v[206:209], v[74:77]
	v_mfma_f32_16x16x32_bf16 v[74:77], v[178:181], v[202:205], v[74:77]
	v_mfma_f32_16x16x32_bf16 v[66:69], v[178:181], v[210:213], v[66:69]
	v_mfma_f32_16x16x32_bf16 v[66:69], v[182:185], v[214:217], v[66:69]
	v_mfma_f32_16x16x32_bf16 v[70:73], v[174:177], v[214:217], v[70:73]
	v_mfma_f32_16x16x32_bf16 v[70:73], v[170:173], v[210:213], v[70:73]
	v_mfma_f32_16x16x32_bf16 v[82:85], v[158:161], v[210:213], v[82:85]
	v_mfma_f32_16x16x32_bf16 v[82:85], v[166:169], v[214:217], v[82:85]
	v_mfma_f32_16x16x32_bf16 v[86:89], v[154:157], v[214:217], v[86:89]
	v_mfma_f32_16x16x32_bf16 v[86:89], v[150:153], v[210:213], v[86:89]
	s_setprio 0
	s_barrier
	s_mov_b32 m0, s34
	v_lshl_add_u64 v[162:163], v[162:163], 0, s[8:9]
	s_add_u32 s12, s12, 0x2b0080
	ds_read_b128 v[186:189], v144 offset:49152
	ds_read_b128 v[190:193], v144 offset:50176
	ds_read_b128 v[194:197], v144 offset:51200
	ds_read_b128 v[198:201], v144 offset:52224
	ds_read_b128 v[202:205], v144 offset:53248
	ds_read_b128 v[206:209], v144 offset:54272
	ds_read_b128 v[210:213], v144 offset:55296
	ds_read_b128 v[214:217], v144 offset:56320
	global_load_lds_dwordx4 v[162:163], off
	v_lshl_add_u64 v[162:163], v[218:219], 0, s[8:9]
	s_mov_b32 m0, s35
	s_addc_u32 s13, s13, 0
	global_load_lds_dwordx4 v[162:163], off
	v_lshl_add_u64 v[162:163], s[12:13], 0, v[132:133]
	s_mov_b32 m0, s36
	s_nop 0
	global_load_lds_dwordx4 v[162:163], off
	v_lshl_add_u64 v[162:163], s[12:13], 0, v[136:137]
	s_mov_b32 m0, s37
	s_nop 0
	global_load_lds_dwordx4 v[162:163], off
	v_lshl_add_u64 v[162:163], v[220:221], 0, s[8:9]
	s_mov_b32 m0, s24
	s_nop 0
	global_load_lds_dwordx4 v[162:163], off
	v_lshl_add_u64 v[162:163], v[222:223], 0, s[8:9]
	s_mov_b32 m0, s25
	s_nop 0
	global_load_lds_dwordx4 v[162:163], off
	s_waitcnt vmcnt(8)
	s_waitcnt lgkmcnt(0)
	s_barrier
	s_setprio 1
	s_waitcnt lgkmcnt(0)
	v_mfma_f32_16x16x32_bf16 v[62:65], v[150:153], v[186:189], v[62:65]
	v_mfma_f32_16x16x32_bf16 v[62:65], v[154:157], v[190:193], v[62:65]
	v_mfma_f32_16x16x32_bf16 v[58:61], v[166:169], v[190:193], v[58:61]
	v_mfma_f32_16x16x32_bf16 v[58:61], v[158:161], v[186:189], v[58:61]
	v_mfma_f32_16x16x32_bf16 v[46:49], v[170:173], v[186:189], v[46:49]
	v_mfma_f32_16x16x32_bf16 v[46:49], v[174:177], v[190:193], v[46:49]
	v_mfma_f32_16x16x32_bf16 v[42:45], v[182:185], v[190:193], v[42:45]
	v_mfma_f32_16x16x32_bf16 v[42:45], v[178:181], v[186:189], v[42:45]
	v_mfma_f32_16x16x32_bf16 v[26:29], v[178:181], v[194:197], v[26:29]
	v_mfma_f32_16x16x32_bf16 v[26:29], v[182:185], v[198:201], v[26:29]
	v_mfma_f32_16x16x32_bf16 v[30:33], v[174:177], v[198:201], v[30:33]
	v_mfma_f32_16x16x32_bf16 v[30:33], v[170:173], v[194:197], v[30:33]
	v_mfma_f32_16x16x32_bf16 v[50:53], v[158:161], v[194:197], v[50:53]
	v_mfma_f32_16x16x32_bf16 v[50:53], v[166:169], v[198:201], v[50:53]
	v_mfma_f32_16x16x32_bf16 v[54:57], v[154:157], v[198:201], v[54:57]
	v_mfma_f32_16x16x32_bf16 v[54:57], v[150:153], v[194:197], v[54:57]
	v_mfma_f32_16x16x32_bf16 v[38:41], v[150:153], v[202:205], v[38:41]
	v_mfma_f32_16x16x32_bf16 v[38:41], v[154:157], v[206:209], v[38:41]
	v_mfma_f32_16x16x32_bf16 v[34:37], v[166:169], v[206:209], v[34:37]
	v_mfma_f32_16x16x32_bf16 v[34:37], v[158:161], v[202:205], v[34:37]
	v_mfma_f32_16x16x32_bf16 v[14:17], v[170:173], v[202:205], v[14:17]
	v_mfma_f32_16x16x32_bf16 v[14:17], v[174:177], v[206:209], v[14:17]
	v_mfma_f32_16x16x32_bf16 v[10:13], v[182:185], v[206:209], v[10:13]
	v_mfma_f32_16x16x32_bf16 v[10:13], v[178:181], v[202:205], v[10:13]
	v_mfma_f32_16x16x32_bf16 v[2:5], v[178:181], v[210:213], v[2:5]
	v_mfma_f32_16x16x32_bf16 v[2:5], v[182:185], v[214:217], v[2:5]
	v_mfma_f32_16x16x32_bf16 v[6:9], v[174:177], v[214:217], v[6:9]
	v_mfma_f32_16x16x32_bf16 v[6:9], v[170:173], v[210:213], v[6:9]
	v_mfma_f32_16x16x32_bf16 v[18:21], v[158:161], v[210:213], v[18:21]
	v_mfma_f32_16x16x32_bf16 v[18:21], v[166:169], v[214:217], v[18:21]
	v_mfma_f32_16x16x32_bf16 v[22:25], v[154:157], v[214:217], v[22:25]
	v_mfma_f32_16x16x32_bf16 v[22:25], v[150:153], v[210:213], v[22:25]
	s_setprio 0
	s_barrier
	s_add_u32 s10, s10, 0x100
	s_addc_u32 s11, s11, 0
	s_cmp_ge_u32 s38, s17
	s_mov_b32 s13, s38
	s_cbranch_scc0 .LBB0_2632
	s_lshl_b32 s4, s16, 21
	v_readlane_b32 s2, v249, 29
	v_lshl_or_b32 v1, s18, 8, v148
	v_mov_b32_e32 v139, 0
	s_add_u32 s4, s2, s4
	v_readlane_b32 s2, v249, 31
	v_or_b32_e32 v130, s23, v1
	v_cvt_pk_bf16_f32 v70, v70, v71
	v_cvt_pk_bf16_f32 v71, v72, v73
	v_cvt_pk_bf16_f32 v72, v66, v67
	v_add_u32_e32 v66, 0x80, v138
	v_mov_b32_e32 v67, v139
	s_addc_u32 s5, s2, 0
	v_ashrrev_i32_e32 v131, 31, v130
	v_lshlrev_b64 v[132:133], 13, v[138:139]
	v_cvt_pk_bf16_f32 v110, v110, v111
	v_cvt_pk_bf16_f32 v111, v112, v113
	v_cvt_pk_bf16_f32 v112, v106, v107
	v_or_b32_e32 v106, 16, v138
	v_mov_b32_e32 v107, v139
	v_lshlrev_b64 v[66:67], 13, v[66:67]
	v_cvt_pk_bf16_f32 v46, v46, v47
	v_cvt_pk_bf16_f32 v47, v48, v49
	v_cvt_pk_bf16_f32 v48, v42, v43
	v_add_u32_e32 v42, 0x90, v138
	v_mov_b32_e32 v43, v139
	v_lshl_add_u64 v[132:133], s[4:5], 0, v[132:133]
	v_lshlrev_b64 v[130:131], 1, v[130:131]
	v_lshlrev_b64 v[106:107], 13, v[106:107]
	v_cvt_pk_bf16_f32 v94, v94, v95
	v_cvt_pk_bf16_f32 v95, v96, v97
	v_cvt_pk_bf16_f32 v96, v90, v91
	v_or_b32_e32 v90, 32, v138
	v_mov_b32_e32 v91, v139
	v_lshl_add_u64 v[66:67], s[4:5], 0, v[66:67]
	v_lshlrev_b64 v[42:43], 13, v[42:43]
	v_cvt_pk_bf16_f32 v30, v30, v31
	v_cvt_pk_bf16_f32 v31, v32, v33
	v_cvt_pk_bf16_f32 v32, v26, v27
	v_add_u32_e32 v26, 0xa0, v138
	v_mov_b32_e32 v27, v139
	v_lshl_add_u64 v[132:133], v[132:133], 0, v[130:131]
	v_cvt_pk_bf16_f32 v113, v108, v109
	v_lshl_add_u64 v[106:107], s[4:5], 0, v[106:107]
	v_lshlrev_b64 v[90:91], 13, v[90:91]
	v_cvt_pk_bf16_f32 v78, v78, v79
	v_cvt_pk_bf16_f32 v79, v80, v81
	v_cvt_pk_bf16_f32 v80, v74, v75
	v_or_b32_e32 v74, 48, v138
	v_mov_b32_e32 v75, v139
	v_lshl_add_u64 v[66:67], v[66:67], 0, v[130:131]
	v_cvt_pk_bf16_f32 v49, v44, v45
	v_lshl_add_u64 v[42:43], s[4:5], 0, v[42:43]
	v_lshlrev_b64 v[26:27], 13, v[26:27]
	v_add_u32_e32 v138, 0xb0, v138
	global_store_dwordx4 v[132:133], v[110:113], off offset:256
	v_cvt_pk_bf16_f32 v97, v92, v93
	v_lshl_add_u64 v[90:91], s[4:5], 0, v[90:91]
	v_lshl_add_u64 v[110:111], v[106:107], 0, v[130:131]
	v_lshlrev_b64 v[74:75], 13, v[74:75]
	global_store_dwordx4 v[66:67], v[46:49], off offset:256
	v_cvt_pk_bf16_f32 v33, v28, v29
	v_lshl_add_u64 v[26:27], s[4:5], 0, v[26:27]
	v_lshl_add_u64 v[46:47], v[42:43], 0, v[130:131]
	v_cvt_pk_bf16_f32 v14, v14, v15
	v_cvt_pk_bf16_f32 v15, v16, v17
	v_cvt_pk_bf16_f32 v16, v10, v11
	v_lshlrev_b64 v[10:11], 13, v[138:139]
	global_store_dwordx4 v[110:111], v[94:97], off offset:256
	v_cvt_pk_bf16_f32 v81, v76, v77
	v_lshl_add_u64 v[74:75], s[4:5], 0, v[74:75]
	v_lshl_add_u64 v[94:95], v[90:91], 0, v[130:131]
	global_store_dwordx4 v[46:47], v[30:33], off offset:256
	v_cvt_pk_bf16_f32 v17, v12, v13
	v_lshl_add_u64 v[10:11], s[4:5], 0, v[10:11]
	v_lshl_add_u64 v[30:31], v[26:27], 0, v[130:131]
	v_cvt_pk_bf16_f32 v126, v126, v127
	v_cvt_pk_bf16_f32 v127, v128, v129
	v_cvt_pk_bf16_f32 v128, v122, v123
	v_cvt_pk_bf16_f32 v129, v124, v125
	v_cvt_pk_bf16_f32 v106, v118, v119
	v_cvt_pk_bf16_f32 v107, v120, v121
	v_cvt_pk_bf16_f32 v108, v114, v115
	v_cvt_pk_bf16_f32 v109, v116, v117
	v_cvt_pk_bf16_f32 v90, v102, v103
	v_cvt_pk_bf16_f32 v91, v104, v105
	v_cvt_pk_bf16_f32 v92, v98, v99
	v_cvt_pk_bf16_f32 v93, v100, v101
	global_store_dwordx4 v[94:95], v[78:81], off offset:256
	v_cvt_pk_bf16_f32 v76, v82, v83
	v_cvt_pk_bf16_f32 v77, v84, v85
	v_lshl_add_u64 v[78:79], v[74:75], 0, v[130:131]
	v_cvt_pk_bf16_f32 v74, v86, v87
	v_cvt_pk_bf16_f32 v75, v88, v89
	v_cvt_pk_bf16_f32 v73, v68, v69
	v_cvt_pk_bf16_f32 v62, v62, v63
	v_cvt_pk_bf16_f32 v63, v64, v65
	v_cvt_pk_bf16_f32 v64, v58, v59
	v_cvt_pk_bf16_f32 v65, v60, v61
	v_cvt_pk_bf16_f32 v42, v54, v55
	v_cvt_pk_bf16_f32 v43, v56, v57
	v_cvt_pk_bf16_f32 v44, v50, v51
	v_cvt_pk_bf16_f32 v45, v52, v53
	v_cvt_pk_bf16_f32 v26, v38, v39
	v_cvt_pk_bf16_f32 v27, v40, v41
	v_cvt_pk_bf16_f32 v28, v34, v35
	v_cvt_pk_bf16_f32 v29, v36, v37
	global_store_dwordx4 v[30:31], v[14:17], off offset:256
	v_cvt_pk_bf16_f32 v12, v18, v19
	v_cvt_pk_bf16_f32 v13, v20, v21
	v_lshl_add_u64 v[14:15], v[10:11], 0, v[130:131]
	v_cvt_pk_bf16_f32 v10, v22, v23
	v_cvt_pk_bf16_f32 v11, v24, v25
	v_cvt_pk_bf16_f32 v6, v6, v7
	v_cvt_pk_bf16_f32 v7, v8, v9
	v_cvt_pk_bf16_f32 v8, v2, v3
	v_cvt_pk_bf16_f32 v9, v4, v5
	global_store_dwordx4 v[132:133], v[126:129], off
	global_store_dwordx4 v[110:111], v[106:109], off
	global_store_dwordx4 v[94:95], v[90:93], off
	global_store_dwordx4 v[78:79], v[74:77], off
	global_store_dwordx4 v[78:79], v[70:73], off offset:256
	global_store_dwordx4 v[66:67], v[62:65], off
	global_store_dwordx4 v[46:47], v[42:45], off
	global_store_dwordx4 v[30:31], v[26:29], off
	global_store_dwordx4 v[14:15], v[10:13], off
	global_store_dwordx4 v[14:15], v[6:9], off offset:256
	s_waitcnt vmcnt(0)
	s_cmpk_lt_u32 s3, 0x100
	s_cbranch_scc0 .LBB0_2635
	s_barrier
